# gMLP stats loop prefetch depth 2 (two 4-load groups in flight) + EpiGate bias prefetch
# baseline (speedup 1.0000x reference)
.LBB0_618:
	s_andn2_b64 vcc, exec, s[0:1]
	s_cbranch_vccnz .LBB0_639
	s_cmpk_gt_i32 s10, 0x7f
	s_cbranch_scc0 .LBB0_625
	s_add_i32 s38, s10, 0xffffff80
	s_lshl_b32 s0, s38, 5
	v_mov_b32_e32 v50, v194
	v_readlane_b32 s40, v251, 54
	s_and_b32 s4, s0, 0x7fffff80
	v_readlane_b32 s46, v251, 60
	v_bfe_u32 v31, v50, 1, 7
	v_readlane_b32 s47, v251, 61
	v_and_b32_e32 v18, 1, v50
	v_or_b32_e32 v0, s4, v31
	v_mov_b64_e32 v[2:3], s[46:47]
	v_mad_u64_u32 v[10:11], s[0:1], v0, s3, v[2:3]
	v_lshlrev_b32_e32 v0, 9, v18
	v_mov_b32_e32 v14, 0
	v_lshrrev_b32_e32 v30, 1, v50
	v_lshl_add_u64 v[12:13], v[10:11], 0, v[0:1]
	v_readfirstlane_b32 s64, v194
	s_lshr_b32 s64, s64, 8
	s_lshl_b32 s0, s64, 8
	s_mov_b32 s1, 0
	s_add_i32 s65, s0, 0x100
	v_mov_b32_e32 v15, v14
	v_readlane_b32 s41, v251, 55
	v_readlane_b32 s42, v251, 56
	v_readlane_b32 s43, v251, 57
	v_readlane_b32 s44, v251, 58
	v_readlane_b32 s45, v251, 59
	v_readlane_b32 s48, v251, 62
	v_readlane_b32 s49, v251, 63
	v_readlane_b32 s50, v252, 0
	v_readlane_b32 s51, v252, 1
	v_readlane_b32 s52, v252, 2
	v_readlane_b32 s53, v252, 3
	v_readlane_b32 s54, v252, 4
	v_readlane_b32 s55, v252, 5
	v_lshl_add_u64 v[172:173], v[12:13], 0, s[0:1]
	global_load_dwordx4 v[176:179], v[172:173], off offset:1072
	global_load_dwordx4 v[180:183], v[172:173], off offset:1056
	global_load_dwordx4 v[184:187], v[172:173], off offset:1040
	global_load_dwordx4 v[188:191], v[172:173], off offset:1024
	global_load_dwordx4 v[140:143], v[172:173], off offset:1136
	global_load_dwordx4 v[144:147], v[172:173], off offset:1120
	global_load_dwordx4 v[148:151], v[172:173], off offset:1104
	global_load_dwordx4 v[152:155], v[172:173], off offset:1088
.LBB0_621:
	s_add_u32 s0, s0, 0x80
	s_addc_u32 s1, s1, 0
	s_waitcnt vmcnt(4)
	v_mov_b32_e32 v2, v176
	v_mov_b32_e32 v3, v177
	v_mov_b32_e32 v4, v178
	v_mov_b32_e32 v5, v179
	v_mov_b32_e32 v6, v180
	v_mov_b32_e32 v7, v181
	v_mov_b32_e32 v8, v182
	v_mov_b32_e32 v9, v183
	v_mov_b32_e32 v20, v184
	v_mov_b32_e32 v21, v185
	v_mov_b32_e32 v22, v186
	v_mov_b32_e32 v23, v187
	v_mov_b32_e32 v24, v188
	v_mov_b32_e32 v25, v189
	v_mov_b32_e32 v26, v190
	v_mov_b32_e32 v27, v191
	v_lshl_add_u64 v[172:173], v[12:13], 0, s[0:1]
	global_load_dwordx4 v[176:179], v[172:173], off offset:1072
	global_load_dwordx4 v[180:183], v[172:173], off offset:1056
	global_load_dwordx4 v[184:187], v[172:173], off offset:1040
	global_load_dwordx4 v[188:191], v[172:173], off offset:1024
	s_cmp_lg_u32 s0, s65
	v_lshlrev_b32_e32 v0, 16, v24
	v_mul_f32_e32 v19, v0, v0
	v_fmamk_f32 v19, v19, 0xbdd2d3e7, v129
	v_mul_f32_e32 v19, v19, v0
	v_exp_f32_e32 v19, v19
	v_and_b32_e32 v40, 0xffff0000, v27
	v_add_f32_e32 v19, 1.0, v19
	v_rcp_f32_e32 v19, v19
	s_nop 0
	v_mul_f32_e32 v29, v19, v0
	v_and_b32_e32 v0, 0xffff0000, v24
	v_mul_f32_e32 v19, v0, v0
	v_fmamk_f32 v19, v19, 0xbdd2d3e7, v129
	v_mul_f32_e32 v19, v19, v0
	v_exp_f32_e32 v19, v19
	v_mul_f32_e32 v28, v29, v29
	v_add_f32_e32 v19, 1.0, v19
	v_rcp_f32_e32 v19, v19
	s_nop 0
	v_mul_f32_e32 v33, v19, v0
	v_lshlrev_b32_e32 v0, 16, v25
	v_mul_f32_e32 v19, v0, v0
	v_fmamk_f32 v19, v19, 0xbdd2d3e7, v129
	v_mul_f32_e32 v19, v19, v0
	v_exp_f32_e32 v19, v19
	v_mul_f32_e32 v32, v33, v33
	v_add_f32_e32 v19, 1.0, v19
	v_rcp_f32_e32 v19, v19
	s_nop 0
	v_mul_f32_e32 v35, v19, v0
	v_and_b32_e32 v0, 0xffff0000, v25
	v_mul_f32_e32 v19, v0, v0
	v_fmamk_f32 v19, v19, 0xbdd2d3e7, v129
	v_mul_f32_e32 v19, v19, v0
	v_exp_f32_e32 v19, v19
	v_mul_f32_e32 v34, v35, v35
	v_add_f32_e32 v19, 1.0, v19
	v_rcp_f32_e32 v19, v19
	s_nop 0
	v_mul_f32_e32 v25, v19, v0
	v_lshlrev_b32_e32 v0, 16, v26
	v_mul_f32_e32 v19, v0, v0
	v_fmamk_f32 v19, v19, 0xbdd2d3e7, v129
	v_mul_f32_e32 v19, v19, v0
	v_exp_f32_e32 v19, v19
	v_mul_f32_e32 v24, v25, v25
	v_pk_add_f32 v[24:25], v[34:35], v[24:25]
	v_add_f32_e32 v19, 1.0, v19
	v_rcp_f32_e32 v19, v19
	s_nop 0
	v_mul_f32_e32 v37, v19, v0
	v_and_b32_e32 v0, 0xffff0000, v26
	v_mul_f32_e32 v19, v0, v0
	v_fmamk_f32 v19, v19, 0xbdd2d3e7, v129
	v_mul_f32_e32 v19, v19, v0
	v_exp_f32_e32 v19, v19
	v_mul_f32_e32 v26, v40, v40
	v_fmamk_f32 v26, v26, 0xbdd2d3e7, v129
	v_mul_f32_e32 v26, v26, v40
	v_add_f32_e32 v19, 1.0, v19
	v_rcp_f32_e32 v19, v19
	v_exp_f32_e32 v26, v26
	v_mul_f32_e32 v39, v19, v0
	v_lshlrev_b32_e32 v0, 16, v27
	v_mul_f32_e32 v19, v0, v0
	v_fmamk_f32 v19, v19, 0xbdd2d3e7, v129
	v_mul_f32_e32 v19, v19, v0
	v_exp_f32_e32 v19, v19
	v_add_f32_e32 v26, 1.0, v26
	v_rcp_f32_e32 v41, v26
	v_pk_add_f32 v[26:27], v[28:29], v[32:33]
	v_add_f32_e32 v19, 1.0, v19
	v_rcp_f32_e32 v19, v19
	v_mul_f32_e32 v36, v37, v37
	v_mul_f32_e32 v38, v39, v39
	v_pk_add_f32 v[14:15], v[14:15], v[26:27]
	v_mul_f32_e32 v27, v41, v40
	v_pk_add_f32 v[14:15], v[14:15], v[24:25]
	v_pk_add_f32 v[24:25], v[36:37], v[38:39]
	v_mul_f32_e32 v26, v27, v27
	v_pk_add_f32 v[14:15], v[14:15], v[24:25]
	v_mul_f32_e32 v25, v19, v0
	v_lshlrev_b32_e32 v0, 16, v20
	v_mul_f32_e32 v19, v0, v0
	v_fmamk_f32 v19, v19, 0xbdd2d3e7, v129
	v_mul_f32_e32 v19, v19, v0
	v_exp_f32_e32 v19, v19
	v_mul_f32_e32 v24, v25, v25
	v_pk_add_f32 v[24:25], v[24:25], v[26:27]
	v_and_b32_e32 v36, 0xffff0000, v23
	v_add_f32_e32 v19, 1.0, v19
	v_rcp_f32_e32 v19, v19
	v_pk_add_f32 v[14:15], v[14:15], v[24:25]
	v_mul_f32_e32 v25, v19, v0
	v_and_b32_e32 v0, 0xffff0000, v20
	v_mul_f32_e32 v19, v0, v0
	v_fmamk_f32 v19, v19, 0xbdd2d3e7, v129
	v_mul_f32_e32 v19, v19, v0
	v_exp_f32_e32 v19, v19
	v_mul_f32_e32 v24, v25, v25
	v_add_f32_e32 v19, 1.0, v19
	v_rcp_f32_e32 v19, v19
	s_nop 0
	v_mul_f32_e32 v27, v19, v0
	v_lshlrev_b32_e32 v0, 16, v21
	v_mul_f32_e32 v19, v0, v0
	v_fmamk_f32 v19, v19, 0xbdd2d3e7, v129
	v_mul_f32_e32 v19, v19, v0
	v_exp_f32_e32 v19, v19
	v_mul_f32_e32 v26, v27, v27
	v_add_f32_e32 v19, 1.0, v19
	v_rcp_f32_e32 v19, v19
	s_nop 0
	v_mul_f32_e32 v29, v19, v0
	v_and_b32_e32 v0, 0xffff0000, v21
	v_mul_f32_e32 v19, v0, v0
	v_fmamk_f32 v19, v19, 0xbdd2d3e7, v129
	v_mul_f32_e32 v19, v19, v0
	v_exp_f32_e32 v19, v19
	v_mul_f32_e32 v28, v29, v29
	v_add_f32_e32 v19, 1.0, v19
	v_rcp_f32_e32 v19, v19
	s_nop 0
	v_mul_f32_e32 v21, v19, v0
	v_lshlrev_b32_e32 v0, 16, v22
	v_mul_f32_e32 v19, v0, v0
	v_fmamk_f32 v19, v19, 0xbdd2d3e7, v129
	v_mul_f32_e32 v19, v19, v0
	v_exp_f32_e32 v19, v19
	v_mul_f32_e32 v20, v21, v21
	v_pk_add_f32 v[20:21], v[28:29], v[20:21]
	v_add_f32_e32 v19, 1.0, v19
	v_rcp_f32_e32 v19, v19
	s_nop 0
	v_mul_f32_e32 v33, v19, v0
	v_and_b32_e32 v0, 0xffff0000, v22
	v_mul_f32_e32 v19, v0, v0
	v_fmamk_f32 v19, v19, 0xbdd2d3e7, v129
	v_mul_f32_e32 v19, v19, v0
	v_exp_f32_e32 v19, v19
	v_mul_f32_e32 v22, v36, v36
	v_fmamk_f32 v22, v22, 0xbdd2d3e7, v129
	v_mul_f32_e32 v22, v22, v36
	v_add_f32_e32 v19, 1.0, v19
	v_rcp_f32_e32 v19, v19
	v_exp_f32_e32 v22, v22
	v_mul_f32_e32 v35, v19, v0
	v_lshlrev_b32_e32 v0, 16, v23
	v_mul_f32_e32 v19, v0, v0
	v_fmamk_f32 v19, v19, 0xbdd2d3e7, v129
	v_mul_f32_e32 v19, v19, v0
	v_exp_f32_e32 v19, v19
	v_add_f32_e32 v22, 1.0, v22
	v_rcp_f32_e32 v37, v22
	v_pk_add_f32 v[22:23], v[24:25], v[26:27]
	v_add_f32_e32 v19, 1.0, v19
	v_rcp_f32_e32 v19, v19
	v_mul_f32_e32 v32, v33, v33
	v_mul_f32_e32 v34, v35, v35
	v_pk_add_f32 v[14:15], v[14:15], v[22:23]
	v_mul_f32_e32 v23, v37, v36
	v_pk_add_f32 v[14:15], v[14:15], v[20:21]
	v_pk_add_f32 v[20:21], v[32:33], v[34:35]
	v_mul_f32_e32 v22, v23, v23
	v_pk_add_f32 v[14:15], v[14:15], v[20:21]
	v_mul_f32_e32 v21, v19, v0
	v_lshlrev_b32_e32 v0, 16, v6
	v_mul_f32_e32 v19, v0, v0
	v_fmamk_f32 v19, v19, 0xbdd2d3e7, v129
	v_mul_f32_e32 v19, v19, v0
	v_exp_f32_e32 v19, v19
	v_mul_f32_e32 v20, v21, v21
	v_pk_add_f32 v[20:21], v[20:21], v[22:23]
	v_and_b32_e32 v32, 0xffff0000, v9
	v_add_f32_e32 v19, 1.0, v19
	v_rcp_f32_e32 v19, v19
	v_pk_add_f32 v[14:15], v[14:15], v[20:21]
	v_mul_f32_e32 v21, v19, v0
	v_and_b32_e32 v0, 0xffff0000, v6
	v_mul_f32_e32 v6, v0, v0
	v_fmamk_f32 v6, v6, 0xbdd2d3e7, v129
	v_mul_f32_e32 v6, v6, v0
	v_exp_f32_e32 v6, v6
	v_mul_f32_e32 v20, v21, v21
	v_add_f32_e32 v6, 1.0, v6
	v_rcp_f32_e32 v6, v6
	s_nop 0
	v_mul_f32_e32 v23, v6, v0
	v_lshlrev_b32_e32 v0, 16, v7
	v_mul_f32_e32 v6, v0, v0
	v_fmamk_f32 v6, v6, 0xbdd2d3e7, v129
	v_mul_f32_e32 v6, v6, v0
	v_exp_f32_e32 v6, v6
	v_mul_f32_e32 v22, v23, v23
	v_add_f32_e32 v6, 1.0, v6
	v_rcp_f32_e32 v6, v6
	s_nop 0
	v_mul_f32_e32 v25, v6, v0
	v_and_b32_e32 v0, 0xffff0000, v7
	v_mul_f32_e32 v6, v0, v0
	v_fmamk_f32 v6, v6, 0xbdd2d3e7, v129
	v_mul_f32_e32 v6, v6, v0
	v_exp_f32_e32 v6, v6
	v_mul_f32_e32 v24, v25, v25
	v_add_f32_e32 v6, 1.0, v6
	v_rcp_f32_e32 v6, v6
	s_nop 0
	v_mul_f32_e32 v7, v6, v0
	v_lshlrev_b32_e32 v0, 16, v8
	v_mul_f32_e32 v19, v0, v0
	v_fmamk_f32 v19, v19, 0xbdd2d3e7, v129
	v_mul_f32_e32 v19, v19, v0
	v_exp_f32_e32 v19, v19
	v_mul_f32_e32 v6, v7, v7
	v_pk_add_f32 v[6:7], v[24:25], v[6:7]
	v_add_f32_e32 v19, 1.0, v19
	v_rcp_f32_e32 v19, v19
	s_nop 0
	v_mul_f32_e32 v27, v19, v0
	v_and_b32_e32 v0, 0xffff0000, v8
	v_mul_f32_e32 v8, v0, v0
	v_fmamk_f32 v8, v8, 0xbdd2d3e7, v129
	v_mul_f32_e32 v8, v8, v0
	v_exp_f32_e32 v8, v8
	v_mul_f32_e32 v26, v27, v27
	v_add_f32_e32 v8, 1.0, v8
	v_rcp_f32_e32 v8, v8
	s_nop 0
	v_mul_f32_e32 v29, v8, v0
	v_lshlrev_b32_e32 v0, 16, v9
	v_mul_f32_e32 v8, v0, v0
	v_fmamk_f32 v8, v8, 0xbdd2d3e7, v129
	v_mul_f32_e32 v8, v8, v0
	v_exp_f32_e32 v8, v8
	v_mul_f32_e32 v28, v29, v29
	v_add_f32_e32 v8, 1.0, v8
	v_rcp_f32_e32 v19, v8
	v_mul_f32_e32 v8, v32, v32
	v_fmamk_f32 v8, v8, 0xbdd2d3e7, v129
	v_mul_f32_e32 v8, v8, v32
	v_exp_f32_e32 v8, v8
	s_nop 0
	v_add_f32_e32 v8, 1.0, v8
	v_rcp_f32_e32 v33, v8
	v_pk_add_f32 v[8:9], v[20:21], v[22:23]
	s_nop 0
	v_pk_add_f32 v[8:9], v[14:15], v[8:9]
	v_mul_f32_e32 v15, v33, v32
	v_pk_add_f32 v[6:7], v[8:9], v[6:7]
	v_pk_add_f32 v[8:9], v[26:27], v[28:29]
	v_mul_f32_e32 v14, v15, v15
	v_pk_add_f32 v[6:7], v[6:7], v[8:9]
	v_mul_f32_e32 v9, v19, v0
	v_mul_f32_e32 v8, v9, v9
	v_pk_add_f32 v[8:9], v[8:9], v[14:15]
	v_lshlrev_b32_e32 v0, 16, v2
	v_pk_add_f32 v[6:7], v[6:7], v[8:9]
	v_mul_f32_e32 v8, v0, v0
	v_fmamk_f32 v8, v8, 0xbdd2d3e7, v129
	v_mul_f32_e32 v8, v8, v0
	v_exp_f32_e32 v8, v8
	v_and_b32_e32 v26, 0xffff0000, v5
	v_add_f32_e32 v8, 1.0, v8
	v_rcp_f32_e32 v8, v8
	s_nop 0
	v_mul_f32_e32 v9, v8, v0
	v_and_b32_e32 v0, 0xffff0000, v2
	v_mul_f32_e32 v2, v0, v0
	v_fmamk_f32 v2, v2, 0xbdd2d3e7, v129
	v_mul_f32_e32 v2, v2, v0
	v_exp_f32_e32 v2, v2
	v_mul_f32_e32 v8, v9, v9
	v_add_f32_e32 v2, 1.0, v2
	v_rcp_f32_e32 v2, v2
	s_nop 0
	v_mul_f32_e32 v15, v2, v0
	v_lshlrev_b32_e32 v0, 16, v3
	v_mul_f32_e32 v2, v0, v0
	v_fmamk_f32 v2, v2, 0xbdd2d3e7, v129
	v_mul_f32_e32 v2, v2, v0
	v_exp_f32_e32 v2, v2
	v_mul_f32_e32 v14, v15, v15
	v_add_f32_e32 v2, 1.0, v2
	v_rcp_f32_e32 v2, v2
	s_nop 0
	v_mul_f32_e32 v21, v2, v0
	v_and_b32_e32 v0, 0xffff0000, v3
	v_mul_f32_e32 v2, v0, v0
	v_fmamk_f32 v2, v2, 0xbdd2d3e7, v129
	v_mul_f32_e32 v2, v2, v0
	v_exp_f32_e32 v2, v2
	v_mul_f32_e32 v20, v21, v21
	v_add_f32_e32 v2, 1.0, v2
	v_rcp_f32_e32 v2, v2
	s_nop 0
	v_mul_f32_e32 v3, v2, v0
	v_lshlrev_b32_e32 v0, 16, v4
	v_mul_f32_e32 v19, v0, v0
	v_fmamk_f32 v19, v19, 0xbdd2d3e7, v129
	v_mul_f32_e32 v19, v19, v0
	v_exp_f32_e32 v19, v19
	v_mul_f32_e32 v2, v3, v3
	v_pk_add_f32 v[2:3], v[20:21], v[2:3]
	v_add_f32_e32 v19, 1.0, v19
	v_rcp_f32_e32 v19, v19
	s_nop 0
	v_mul_f32_e32 v23, v19, v0
	v_and_b32_e32 v0, 0xffff0000, v4
	v_mul_f32_e32 v4, v0, v0
	v_fmamk_f32 v4, v4, 0xbdd2d3e7, v129
	v_mul_f32_e32 v4, v4, v0
	v_exp_f32_e32 v4, v4
	v_mul_f32_e32 v22, v23, v23
	v_add_f32_e32 v4, 1.0, v4
	v_rcp_f32_e32 v4, v4
	s_nop 0
	v_mul_f32_e32 v25, v4, v0
	v_lshlrev_b32_e32 v0, 16, v5
	v_mul_f32_e32 v4, v0, v0
	v_fmamk_f32 v4, v4, 0xbdd2d3e7, v129
	v_mul_f32_e32 v4, v4, v0
	v_exp_f32_e32 v4, v4
	v_mul_f32_e32 v24, v25, v25
	v_add_f32_e32 v4, 1.0, v4
	v_rcp_f32_e32 v19, v4
	v_mul_f32_e32 v4, v26, v26
	v_fmamk_f32 v4, v4, 0xbdd2d3e7, v129
	v_mul_f32_e32 v4, v4, v26
	v_exp_f32_e32 v4, v4
	s_nop 0
	v_add_f32_e32 v4, 1.0, v4
	v_rcp_f32_e32 v27, v4
	v_pk_add_f32 v[4:5], v[8:9], v[14:15]
	s_nop 0
	v_pk_add_f32 v[4:5], v[6:7], v[4:5]
	v_mul_f32_e32 v7, v27, v26
	v_pk_add_f32 v[2:3], v[4:5], v[2:3]
	v_pk_add_f32 v[4:5], v[22:23], v[24:25]
	v_mul_f32_e32 v6, v7, v7
	v_pk_add_f32 v[2:3], v[2:3], v[4:5]
	v_mul_f32_e32 v5, v19, v0
	v_mul_f32_e32 v4, v5, v5
	v_pk_add_f32 v[4:5], v[4:5], v[6:7]
	s_nop 0
	v_pk_add_f32 v[24:25], v[2:3], v[4:5]
	s_waitcnt vmcnt(4)
	v_mov_b32_e32 v2, v140
	v_mov_b32_e32 v3, v141
	v_mov_b32_e32 v4, v142
	v_mov_b32_e32 v5, v143
	v_mov_b32_e32 v6, v144
	v_mov_b32_e32 v7, v145
	v_mov_b32_e32 v8, v146
	v_mov_b32_e32 v9, v147
	v_mov_b32_e32 v20, v148
	v_mov_b32_e32 v21, v149
	v_mov_b32_e32 v22, v150
	v_mov_b32_e32 v23, v151
	v_mov_b32_e32 v14, v152
	v_mov_b32_e32 v15, v153
	v_mov_b32_e32 v16, v154
	v_mov_b32_e32 v17, v155
	global_load_dwordx4 v[140:143], v[172:173], off offset:1136
	global_load_dwordx4 v[144:147], v[172:173], off offset:1120
	global_load_dwordx4 v[148:151], v[172:173], off offset:1104
	global_load_dwordx4 v[152:155], v[172:173], off offset:1088
	v_lshlrev_b32_e32 v0, 16, v14
	v_mul_f32_e32 v19, v0, v0
	v_fmamk_f32 v19, v19, 0xbdd2d3e7, v129
	v_mul_f32_e32 v19, v19, v0
	v_exp_f32_e32 v19, v19
	v_and_b32_e32 v38, 0xffff0000, v17
	v_add_f32_e32 v19, 1.0, v19
	v_rcp_f32_e32 v19, v19
	s_nop 0
	v_mul_f32_e32 v27, v19, v0
	v_and_b32_e32 v0, 0xffff0000, v14
	v_mul_f32_e32 v14, v0, v0
	v_fmamk_f32 v14, v14, 0xbdd2d3e7, v129
	v_mul_f32_e32 v14, v14, v0
	v_exp_f32_e32 v14, v14
	v_mul_f32_e32 v26, v27, v27
	v_add_f32_e32 v14, 1.0, v14
	v_rcp_f32_e32 v14, v14
	s_nop 0
	v_mul_f32_e32 v29, v14, v0
	v_lshlrev_b32_e32 v0, 16, v15
	v_mul_f32_e32 v14, v0, v0
	v_fmamk_f32 v14, v14, 0xbdd2d3e7, v129
	v_mul_f32_e32 v14, v14, v0
	v_exp_f32_e32 v14, v14
	v_mul_f32_e32 v28, v29, v29
	v_add_f32_e32 v14, 1.0, v14
	v_rcp_f32_e32 v14, v14
	s_nop 0
	v_mul_f32_e32 v33, v14, v0
	v_and_b32_e32 v0, 0xffff0000, v15
	v_mul_f32_e32 v14, v0, v0
	v_fmamk_f32 v14, v14, 0xbdd2d3e7, v129
	v_mul_f32_e32 v14, v14, v0
	v_exp_f32_e32 v14, v14
	v_mul_f32_e32 v32, v33, v33
	v_add_f32_e32 v14, 1.0, v14
	v_rcp_f32_e32 v14, v14
	s_nop 0
	v_mul_f32_e32 v15, v14, v0
	v_lshlrev_b32_e32 v0, 16, v16
	v_mul_f32_e32 v19, v0, v0
	v_fmamk_f32 v19, v19, 0xbdd2d3e7, v129
	v_mul_f32_e32 v19, v19, v0
	v_exp_f32_e32 v19, v19
	v_mul_f32_e32 v14, v15, v15
	v_pk_add_f32 v[14:15], v[32:33], v[14:15]
	v_add_f32_e32 v19, 1.0, v19
	v_rcp_f32_e32 v19, v19
	s_nop 0
	v_mul_f32_e32 v35, v19, v0
	v_and_b32_e32 v0, 0xffff0000, v16
	v_mul_f32_e32 v16, v0, v0
	v_fmamk_f32 v16, v16, 0xbdd2d3e7, v129
	v_mul_f32_e32 v16, v16, v0
	v_exp_f32_e32 v16, v16
	v_mul_f32_e32 v34, v35, v35
	v_add_f32_e32 v16, 1.0, v16
	v_rcp_f32_e32 v16, v16
	s_nop 0
	v_mul_f32_e32 v37, v16, v0
	v_lshlrev_b32_e32 v0, 16, v17
	v_mul_f32_e32 v16, v0, v0
	v_fmamk_f32 v16, v16, 0xbdd2d3e7, v129
	v_mul_f32_e32 v16, v16, v0
	v_exp_f32_e32 v16, v16
	v_mul_f32_e32 v36, v37, v37
	v_add_f32_e32 v16, 1.0, v16
	v_rcp_f32_e32 v19, v16
	v_mul_f32_e32 v16, v38, v38
	v_fmamk_f32 v16, v16, 0xbdd2d3e7, v129
	v_mul_f32_e32 v16, v16, v38
	v_exp_f32_e32 v16, v16
	s_nop 0
	v_add_f32_e32 v16, 1.0, v16
	v_rcp_f32_e32 v39, v16
	v_pk_add_f32 v[16:17], v[26:27], v[28:29]
	s_nop 0
	v_pk_add_f32 v[16:17], v[24:25], v[16:17]
	v_mul_f32_e32 v25, v39, v38
	v_pk_add_f32 v[14:15], v[16:17], v[14:15]
	v_pk_add_f32 v[16:17], v[34:35], v[36:37]
	v_mul_f32_e32 v24, v25, v25
	v_pk_add_f32 v[14:15], v[14:15], v[16:17]
	v_mul_f32_e32 v17, v19, v0
	v_mul_f32_e32 v16, v17, v17
	v_pk_add_f32 v[16:17], v[16:17], v[24:25]
	v_lshlrev_b32_e32 v0, 16, v20
	v_pk_add_f32 v[14:15], v[14:15], v[16:17]
	v_mul_f32_e32 v16, v0, v0
	v_fmamk_f32 v16, v16, 0xbdd2d3e7, v129
	v_mul_f32_e32 v16, v16, v0
	v_exp_f32_e32 v16, v16
	s_nop 0
	v_add_f32_e32 v16, 1.0, v16
	v_rcp_f32_e32 v16, v16
	s_nop 0
	v_mul_f32_e32 v17, v16, v0
	v_and_b32_e32 v0, 0xffff0000, v20
	v_mul_f32_e32 v16, v0, v0
	v_fmamk_f32 v16, v16, 0xbdd2d3e7, v129
	v_mul_f32_e32 v16, v16, v0
	v_exp_f32_e32 v16, v16
	s_nop 0
	v_add_f32_e32 v16, 1.0, v16
	v_rcp_f32_e32 v16, v16
	s_nop 0
	v_mul_f32_e32 v25, v16, v0
	v_lshlrev_b32_e32 v0, 16, v21
	v_mul_f32_e32 v19, v0, v0
	v_fmamk_f32 v19, v19, 0xbdd2d3e7, v129
	v_mul_f32_e32 v19, v19, v0
	v_exp_f32_e32 v19, v19
	v_mul_f32_e32 v16, v17, v17
	v_mul_f32_e32 v24, v25, v25
	v_pk_add_f32 v[16:17], v[16:17], v[24:25]
	v_add_f32_e32 v19, 1.0, v19
	v_rcp_f32_e32 v19, v19
	v_pk_add_f32 v[14:15], v[14:15], v[16:17]
	v_mul_f32_e32 v27, v19, v0
	v_and_b32_e32 v0, 0xffff0000, v21
	v_mul_f32_e32 v19, v0, v0
	v_fmamk_f32 v19, v19, 0xbdd2d3e7, v129
	v_mul_f32_e32 v19, v19, v0
	v_exp_f32_e32 v19, v19
	v_mul_f32_e32 v26, v27, v27
	v_add_f32_e32 v19, 1.0, v19
	v_rcp_f32_e32 v19, v19
	s_nop 0
	v_mul_f32_e32 v21, v19, v0
	v_lshlrev_b32_e32 v0, 16, v22
	v_mul_f32_e32 v19, v0, v0
	v_fmamk_f32 v19, v19, 0xbdd2d3e7, v129
	v_mul_f32_e32 v19, v19, v0
	v_exp_f32_e32 v19, v19
	v_mul_f32_e32 v20, v21, v21
	v_pk_add_f32 v[16:17], v[26:27], v[20:21]
	v_add_f32_e32 v19, 1.0, v19
	v_rcp_f32_e32 v19, v19
	v_pk_add_f32 v[14:15], v[14:15], v[16:17]
	v_mul_f32_e32 v29, v19, v0
	v_and_b32_e32 v0, 0xffff0000, v22
	v_mul_f32_e32 v19, v0, v0
	v_fmamk_f32 v19, v19, 0xbdd2d3e7, v129
	v_mul_f32_e32 v19, v19, v0
	v_exp_f32_e32 v19, v19
	v_and_b32_e32 v22, 0xffff0000, v23
	v_mul_f32_e32 v28, v29, v29
	v_add_f32_e32 v19, 1.0, v19
	v_rcp_f32_e32 v19, v19
	s_nop 0
	v_mul_f32_e32 v33, v19, v0
	v_lshlrev_b32_e32 v0, 16, v23
	v_mul_f32_e32 v19, v0, v0
	v_mul_f32_e32 v23, v22, v22
	v_fmamk_f32 v19, v19, 0xbdd2d3e7, v129
	v_fmamk_f32 v23, v23, 0xbdd2d3e7, v129
	v_mul_f32_e32 v19, v19, v0
	v_mul_f32_e32 v23, v23, v22
	v_exp_f32_e32 v19, v19
	v_exp_f32_e32 v23, v23
	v_mul_f32_e32 v32, v33, v33
	v_pk_add_f32 v[16:17], v[28:29], v[32:33]
	v_add_f32_e32 v19, 1.0, v19
	v_add_f32_e32 v23, 1.0, v23
	v_rcp_f32_e32 v19, v19
	v_rcp_f32_e32 v23, v23
	v_pk_add_f32 v[14:15], v[14:15], v[16:17]
	v_and_b32_e32 v28, 0xffff0000, v9
	v_mul_f32_e32 v17, v19, v0
	v_mul_f32_e32 v21, v23, v22
	v_mul_f32_e32 v16, v17, v17
	v_mul_f32_e32 v20, v21, v21
	v_pk_add_f32 v[16:17], v[16:17], v[20:21]
	v_lshlrev_b32_e32 v0, 16, v6
	v_pk_add_f32 v[14:15], v[14:15], v[16:17]
	v_mul_f32_e32 v16, v0, v0
	v_fmamk_f32 v16, v16, 0xbdd2d3e7, v129
	v_mul_f32_e32 v16, v16, v0
	v_exp_f32_e32 v16, v16
	s_nop 0
	v_add_f32_e32 v16, 1.0, v16
	v_rcp_f32_e32 v16, v16
	s_nop 0
	v_mul_f32_e32 v17, v16, v0
	v_and_b32_e32 v0, 0xffff0000, v6
	v_mul_f32_e32 v6, v0, v0
	v_fmamk_f32 v6, v6, 0xbdd2d3e7, v129
	v_mul_f32_e32 v6, v6, v0
	v_exp_f32_e32 v6, v6
	v_mul_f32_e32 v16, v17, v17
	v_add_f32_e32 v6, 1.0, v6
	v_rcp_f32_e32 v6, v6
	s_nop 0
	v_mul_f32_e32 v21, v6, v0
	v_lshlrev_b32_e32 v0, 16, v7
	v_mul_f32_e32 v6, v0, v0
	v_fmamk_f32 v6, v6, 0xbdd2d3e7, v129
	v_mul_f32_e32 v6, v6, v0
	v_exp_f32_e32 v6, v6
	v_mul_f32_e32 v20, v21, v21
	v_add_f32_e32 v6, 1.0, v6
	v_rcp_f32_e32 v6, v6
	s_nop 0
	v_mul_f32_e32 v23, v6, v0
	v_and_b32_e32 v0, 0xffff0000, v7
	v_mul_f32_e32 v6, v0, v0
	v_fmamk_f32 v6, v6, 0xbdd2d3e7, v129
	v_mul_f32_e32 v6, v6, v0
	v_exp_f32_e32 v6, v6
	v_mul_f32_e32 v22, v23, v23
	v_add_f32_e32 v6, 1.0, v6
	v_rcp_f32_e32 v6, v6
	s_nop 0
	v_mul_f32_e32 v7, v6, v0
	v_lshlrev_b32_e32 v0, 16, v8
	v_mul_f32_e32 v19, v0, v0
	v_fmamk_f32 v19, v19, 0xbdd2d3e7, v129
	v_mul_f32_e32 v19, v19, v0
	v_exp_f32_e32 v19, v19
	v_mul_f32_e32 v6, v7, v7
	v_pk_add_f32 v[6:7], v[22:23], v[6:7]
	v_add_f32_e32 v19, 1.0, v19
	v_rcp_f32_e32 v19, v19
	s_nop 0
	v_mul_f32_e32 v25, v19, v0
	v_and_b32_e32 v0, 0xffff0000, v8
	v_mul_f32_e32 v8, v0, v0
	v_fmamk_f32 v8, v8, 0xbdd2d3e7, v129
	v_mul_f32_e32 v8, v8, v0
	v_exp_f32_e32 v8, v8
	v_mul_f32_e32 v24, v25, v25
	v_add_f32_e32 v8, 1.0, v8
	v_rcp_f32_e32 v8, v8
	s_nop 0
	v_mul_f32_e32 v27, v8, v0
	v_lshlrev_b32_e32 v0, 16, v9
	v_mul_f32_e32 v8, v0, v0
	v_fmamk_f32 v8, v8, 0xbdd2d3e7, v129
	v_mul_f32_e32 v8, v8, v0
	v_exp_f32_e32 v8, v8
	v_mul_f32_e32 v26, v27, v27
	v_add_f32_e32 v8, 1.0, v8
	v_rcp_f32_e32 v19, v8
	v_mul_f32_e32 v8, v28, v28
	v_fmamk_f32 v8, v8, 0xbdd2d3e7, v129
	v_mul_f32_e32 v8, v8, v28
	v_exp_f32_e32 v8, v8
	s_nop 0
	v_add_f32_e32 v8, 1.0, v8
	v_rcp_f32_e32 v29, v8
	v_pk_add_f32 v[8:9], v[16:17], v[20:21]
	s_nop 0
	v_pk_add_f32 v[8:9], v[14:15], v[8:9]
	v_mul_f32_e32 v15, v29, v28
	v_pk_add_f32 v[6:7], v[8:9], v[6:7]
	v_pk_add_f32 v[8:9], v[24:25], v[26:27]
	v_mul_f32_e32 v14, v15, v15
	v_pk_add_f32 v[6:7], v[6:7], v[8:9]
	v_mul_f32_e32 v9, v19, v0
	v_mul_f32_e32 v8, v9, v9
	v_pk_add_f32 v[8:9], v[8:9], v[14:15]
	v_lshlrev_b32_e32 v0, 16, v2
	v_pk_add_f32 v[6:7], v[6:7], v[8:9]
	v_mul_f32_e32 v8, v0, v0
	v_fmamk_f32 v8, v8, 0xbdd2d3e7, v129
	v_mul_f32_e32 v8, v8, v0
	v_exp_f32_e32 v8, v8
	v_and_b32_e32 v24, 0xffff0000, v5
	v_add_f32_e32 v8, 1.0, v8
	v_rcp_f32_e32 v8, v8
	s_nop 0
	v_mul_f32_e32 v9, v8, v0
	v_and_b32_e32 v0, 0xffff0000, v2
	v_mul_f32_e32 v2, v0, v0
	v_fmamk_f32 v2, v2, 0xbdd2d3e7, v129
	v_mul_f32_e32 v2, v2, v0
	v_exp_f32_e32 v2, v2
	v_mul_f32_e32 v8, v9, v9
	v_add_f32_e32 v2, 1.0, v2
	v_rcp_f32_e32 v2, v2
	s_nop 0
	v_mul_f32_e32 v15, v2, v0
	v_lshlrev_b32_e32 v0, 16, v3
	v_mul_f32_e32 v2, v0, v0
	v_fmamk_f32 v2, v2, 0xbdd2d3e7, v129
	v_mul_f32_e32 v2, v2, v0
	v_exp_f32_e32 v2, v2
	v_mul_f32_e32 v14, v15, v15
	v_add_f32_e32 v2, 1.0, v2
	v_rcp_f32_e32 v2, v2
	s_nop 0
	v_mul_f32_e32 v17, v2, v0
	v_and_b32_e32 v0, 0xffff0000, v3
	v_mul_f32_e32 v2, v0, v0
	v_fmamk_f32 v2, v2, 0xbdd2d3e7, v129
	v_mul_f32_e32 v2, v2, v0
	v_exp_f32_e32 v2, v2
	v_mul_f32_e32 v16, v17, v17
	v_add_f32_e32 v2, 1.0, v2
	v_rcp_f32_e32 v2, v2
	s_nop 0
	v_mul_f32_e32 v3, v2, v0
	v_lshlrev_b32_e32 v0, 16, v4
	v_mul_f32_e32 v19, v0, v0
	v_fmamk_f32 v19, v19, 0xbdd2d3e7, v129
	v_mul_f32_e32 v19, v19, v0
	v_exp_f32_e32 v19, v19
	v_mul_f32_e32 v2, v3, v3
	v_pk_add_f32 v[2:3], v[16:17], v[2:3]
	v_add_f32_e32 v19, 1.0, v19
	v_rcp_f32_e32 v19, v19
	s_nop 0
	v_mul_f32_e32 v21, v19, v0
	v_and_b32_e32 v0, 0xffff0000, v4
	v_mul_f32_e32 v4, v0, v0
	v_fmamk_f32 v4, v4, 0xbdd2d3e7, v129
	v_mul_f32_e32 v4, v4, v0
	v_exp_f32_e32 v4, v4
	v_mul_f32_e32 v20, v21, v21
	v_add_f32_e32 v4, 1.0, v4
	v_rcp_f32_e32 v4, v4
	s_nop 0
	v_mul_f32_e32 v23, v4, v0
	v_lshlrev_b32_e32 v0, 16, v5
	v_mul_f32_e32 v4, v0, v0
	v_fmamk_f32 v4, v4, 0xbdd2d3e7, v129
	v_mul_f32_e32 v4, v4, v0
	v_exp_f32_e32 v4, v4
	v_mul_f32_e32 v22, v23, v23
	v_add_f32_e32 v4, 1.0, v4
	v_rcp_f32_e32 v19, v4
	v_mul_f32_e32 v4, v24, v24
	v_fmamk_f32 v4, v4, 0xbdd2d3e7, v129
	v_mul_f32_e32 v4, v4, v24
	v_exp_f32_e32 v4, v4
	s_nop 0
	v_add_f32_e32 v4, 1.0, v4
	v_rcp_f32_e32 v25, v4
	v_pk_add_f32 v[4:5], v[8:9], v[14:15]
	s_nop 0
	v_pk_add_f32 v[4:5], v[6:7], v[4:5]
	v_mul_f32_e32 v7, v25, v24
	v_pk_add_f32 v[2:3], v[4:5], v[2:3]
	v_pk_add_f32 v[4:5], v[20:21], v[22:23]
	v_mul_f32_e32 v6, v7, v7
	v_pk_add_f32 v[2:3], v[2:3], v[4:5]
	v_mul_f32_e32 v5, v19, v0
	v_mul_f32_e32 v4, v5, v5
	v_pk_add_f32 v[4:5], v[4:5], v[6:7]
	s_nop 0
	v_pk_add_f32 v[14:15], v[2:3], v[4:5]
	s_cbranch_scc1 .LBB0_621
	v_and_b32_e32 v171, 0xff, v194
	v_lshlrev_b32_e32 v171, 3, v171
	s_mul_i32 s66, s64, 0x12000
	s_add_i32 s66, s66, 0x11000
	s_xor_b32 s67, s64, 1
	s_mul_i32 s67, s67, 0x12000
	s_add_i32 s67, s67, 0x11000
	v_add_u32_e32 v172, s66, v171
	v_add_u32_e32 v173, s67, v171
	ds_write_b64 v172, v[14:15]
	s_waitcnt lgkmcnt(0)
	s_barrier
	ds_read_b64 v[174:175], v173
	s_waitcnt lgkmcnt(0)
	v_add_f32_e32 v14, v14, v174
	v_add_f32_e32 v15, v15, v175
	v_readlane_b32 s0, v254, 51
	s_lshl_b32 s88, s0, 9
	v_readlane_b32 s40, v251, 6
	s_lshl_b64 s[6:7], s[88:89], 2
	v_readlane_b32 s52, v251, 18
	v_readlane_b32 s53, v251, 19
	s_add_u32 s1, s52, s6
	s_addc_u32 s2, s53, s7
	s_lshl_b32 s0, s10, 7
	s_and_b32 s0, s0, 0x180
	s_lshl_b32 s5, s0, 2
	s_add_u32 s16, s1, s5
	v_readlane_b32 s54, v251, 20
	s_addc_u32 s17, s2, 0
	v_readlane_b32 s55, v251, 21
	s_add_u32 s1, s54, s6
	s_addc_u32 s2, s55, s7
	s_add_u32 s20, s1, s5
	s_addc_u32 s21, s2, 0
	s_lshl_b32 s8, s0, 1
	s_mov_b32 s9, s89
	v_lshl_add_u64 v[2:3], v[10:11], 0, s[8:9]
	v_lshlrev_b32_e32 v0, 7, v18
	v_lshl_add_u64 v[22:23], v[2:3], 0, v[0:1]
	global_load_dwordx4 v[10:13], v[22:23], off offset:1024
	v_lshlrev_b32_e32 v20, 8, v18
	global_load_dwordx2 v[28:29], v20, s[16:17]
	global_load_dwordx2 v[36:37], v20, s[20:21]
	global_load_dwordx2 v[40:41], v20, s[16:17] offset:16
	global_load_dwordx2 v[42:43], v20, s[16:17] offset:32
	global_load_dwordx2 v[24:25], v20, s[16:17] offset:48
	global_load_dwordx2 v[44:45], v20, s[20:21] offset:16
	global_load_dwordx2 v[46:47], v20, s[20:21] offset:32
	global_load_dwordx2 v[26:27], v20, s[20:21] offset:48
	v_xor_b32_e32 v2, 1, v234
	v_cmp_lt_i32_e32 vcc, v2, v235
	s_mov_b32 s2, 0x3b000000
	v_lshlrev_b32_e32 v34, 6, v18
	v_cndmask_b32_e32 v2, v234, v2, vcc
	v_lshlrev_b32_e32 v80, 2, v2
	ds_bpermute_b32 v3, v80, v15
	ds_bpermute_b32 v2, v80, v14
	v_mul_u32_u24_e32 v4, 0x4400, v18
	v_lshlrev_b32_e32 v33, 1, v31
	s_mov_b32 s11, 0x800000
	v_add3_u32 v38, s15, v4, v33
	s_waitcnt lgkmcnt(0)
	v_pk_add_f32 v[2:3], v[14:15], v[2:3]
	v_or_b32_e32 v4, 1, v34
	v_pk_mul_f32 v[18:19], v[2:3], s[2:3] op_sel_hi:[1,0]
	v_mul_u32_u24_e32 v4, 0x110, v4
	v_fma_f32 v2, -v19, v19, v18
	v_max_f32_e32 v2, 0, v2
	v_add_f32_e32 v2, 0x358637bd, v2
	v_mul_f32_e32 v3, 0x4b800000, v2
	v_cmp_gt_f32_e32 vcc, s11, v2
	v_add3_u32 v35, s15, v4, v33
	v_or_b32_e32 v78, 7, v34
	v_cndmask_b32_e32 v2, v2, v3, vcc
	v_rsq_f32_e32 v18, v2
	global_load_dwordx4 v[14:17], v[22:23], off offset:1040
	global_load_dwordx4 v[2:5], v[22:23], off offset:1072
	global_load_dwordx4 v[6:9], v[22:23], off offset:1056
	v_or_b32_e32 v81, 10, v34
	v_or_b32_e32 v79, 11, v34
	v_mul_f32_e32 v39, 0x45800000, v18
	v_cndmask_b32_e32 v39, v18, v39, vcc
	v_readlane_b32 s41, v251, 7
	v_readlane_b32 s42, v251, 8
	v_readlane_b32 s43, v251, 9
	v_readlane_b32 s44, v251, 10
	v_readlane_b32 s45, v251, 11
	v_readlane_b32 s46, v251, 12
	v_readlane_b32 s47, v251, 13
	v_readlane_b32 s48, v251, 14
	v_readlane_b32 s49, v251, 15
	v_readlane_b32 s50, v251, 16
	v_readlane_b32 s51, v251, 17
	s_or_b32 s88, s0, s88
	v_readlane_b32 s40, v251, 22
	v_readlane_b32 s41, v251, 23
	v_mov_b32_e32 v21, v1
	v_mul_u32_u24_e32 v84, 0x110, v31
	v_add3_u32 v0, s15, v84, v0
	v_or_b32_e32 v101, 31, v34
	v_cmp_gt_u32_e32 vcc, v31, v34
	v_or_b32_e32 v57, 48, v34
	v_and_b32_e32 v32, 15, v50
	v_readlane_b32 s44, v251, 26
	v_readlane_b32 s45, v251, 27
	v_readlane_b32 s46, v251, 28
	v_readlane_b32 s47, v251, 29
	v_readlane_b32 s48, v251, 30
	v_readlane_b32 s49, v251, 31
	v_readlane_b32 s50, v251, 32
	v_readlane_b32 s51, v251, 33
	v_readlane_b32 s52, v251, 34
	v_readlane_b32 s53, v251, 35
	v_readlane_b32 s54, v251, 36
	v_readlane_b32 s55, v251, 37
	v_readlane_b32 s44, v251, 54
	v_readlane_b32 s50, v251, 60
	v_readlane_b32 s51, v251, 61
	s_add_u32 s6, s50, s8
	s_addc_u32 s7, s51, 0
	v_readlane_b32 s42, v251, 24
	v_readlane_b32 s43, v251, 25
	v_readlane_b32 s52, v251, 62
	v_readlane_b32 s53, v251, 63
	v_readlane_b32 s54, v252, 0
	v_readlane_b32 s55, v252, 1
	v_readlane_b32 s45, v251, 55
	s_waitcnt vmcnt(11)
	v_lshlrev_b32_e32 v48, 16, v11
	v_and_b32_e32 v11, 0xffff0000, v11
	v_mul_f32_e32 v54, v11, v11
	v_fmamk_f32 v54, v54, 0xbdd2d3e7, v129
	v_mul_f32_e32 v54, v54, v11
	v_lshlrev_b32_e32 v18, 16, v10
	v_and_b32_e32 v10, 0xffff0000, v10
	v_mul_f32_e32 v51, v18, v18
	v_mul_f32_e32 v52, v10, v10
	v_fmamk_f32 v51, v51, 0xbdd2d3e7, v129
	v_exp_f32_e32 v54, v54
	v_fmamk_f32 v52, v52, 0xbdd2d3e7, v129
	v_mul_f32_e32 v51, v51, v18
	v_mul_f32_e32 v52, v52, v10
	v_exp_f32_e32 v51, v51
	v_add_f32_e32 v54, 1.0, v54
	v_exp_f32_e32 v52, v52
	v_rcp_f32_e32 v54, v54
	v_lshlrev_b32_e32 v49, 16, v12
	v_mul_f32_e32 v55, v49, v49
	v_fmamk_f32 v55, v55, 0xbdd2d3e7, v129
	v_add_f32_e32 v51, 1.0, v51
	v_mul_f32_e32 v55, v55, v49
	v_add_f32_e32 v52, 1.0, v52
	v_rcp_f32_e32 v51, v51
	v_fma_f32 v11, v54, v11, -v19
	v_rcp_f32_e32 v52, v52
	v_mul_f32_e32 v59, v39, v11
	v_and_b32_e32 v11, 0xffff0000, v12
	v_mul_f32_e32 v12, v11, v11
	v_exp_f32_e32 v55, v55
	v_fmamk_f32 v12, v12, 0xbdd2d3e7, v129
	v_fma_f32 v18, v51, v18, -v19
	v_mul_f32_e32 v12, v12, v11
	v_fma_f32 v10, v52, v10, -v19
	v_mul_f32_e32 v18, v39, v18
	v_mul_f32_e32 v10, v39, v10
	s_waitcnt vmcnt(9)
	v_fma_f32 v18, v28, v18, v36
	v_lshlrev_b32_e32 v28, 16, v13
	v_add_f32_e32 v55, 1.0, v55
	v_fmac_f32_e32 v37, v29, v10
	v_exp_f32_e32 v12, v12
	v_mul_f32_e32 v29, v28, v28
	v_rcp_f32_e32 v55, v55
	v_fmamk_f32 v29, v29, 0xbdd2d3e7, v129
	v_mul_f32_e32 v29, v29, v28
	v_cvt_pk_bf16_f32 v10, v18, s0
	v_add_f32_e32 v12, 1.0, v12
	v_cvt_pk_bf16_f32 v18, v37, s0
	ds_write_b16 v38, v10 offset:34816
	ds_write_b16 v35, v18 offset:34816
	v_fma_f32 v10, v55, v49, -v19
	v_rcp_f32_e32 v12, v12
	v_exp_f32_e32 v29, v29
	v_mul_f32_e32 v10, v39, v10
	s_waitcnt vmcnt(5)
	v_fma_f32 v10, v40, v10, v44
	v_cvt_pk_bf16_f32 v10, v10, s0
	ds_write_b16 v35, v10 offset:35632
	v_fma_f32 v10, v12, v11, -v19
	v_add_f32_e32 v11, 1.0, v29
	v_rcp_f32_e32 v11, v11
	v_mul_f32_e32 v10, v39, v10
	v_fmac_f32_e32 v45, v10, v41
	v_cvt_pk_bf16_f32 v10, v45, s0
	ds_write_b16 v35, v10 offset:35904
	v_fma_f32 v10, v11, v28, -v19
	v_and_b32_e32 v11, 0xffff0000, v13
	v_mul_f32_e32 v12, v11, v11
	v_fmamk_f32 v12, v12, 0xbdd2d3e7, v129
	v_mul_f32_e32 v12, v12, v11
	v_exp_f32_e32 v12, v12
	s_waitcnt vmcnt(2)
	v_lshlrev_b32_e32 v13, 16, v14
	v_mul_f32_e32 v28, v13, v13
	v_fmamk_f32 v28, v28, 0xbdd2d3e7, v129
	v_add_f32_e32 v12, 1.0, v12
	v_rcp_f32_e32 v12, v12
	v_mul_f32_e32 v28, v28, v13
	v_fma_f32 v11, v12, v11, -v19
	v_exp_f32_e32 v28, v28
	v_mul_f32_e32 v44, v39, v11
	v_and_b32_e32 v11, 0xffff0000, v14
	v_mul_f32_e32 v12, v11, v11
	v_fmamk_f32 v12, v12, 0xbdd2d3e7, v129
	v_mul_f32_e32 v12, v12, v11
	v_mul_f32_e32 v45, v39, v10
	v_add_f32_e32 v10, 1.0, v28
	v_rcp_f32_e32 v10, v10
	v_exp_f32_e32 v12, v12
	v_lshlrev_b32_e32 v29, 16, v16
	v_fma_f32 v10, v10, v13, -v19
	v_lshlrev_b32_e32 v13, 16, v15
	v_add_f32_e32 v12, 1.0, v12
	v_mul_f32_e32 v14, v13, v13
	v_rcp_f32_e32 v12, v12
	v_fmamk_f32 v14, v14, 0xbdd2d3e7, v129
	v_mul_f32_e32 v10, v39, v10
	v_mul_f32_e32 v14, v14, v13
	v_fma_f32 v10, v42, v10, v46
	v_cvt_pk_bf16_f32 v10, v10, s0
	v_exp_f32_e32 v14, v14
	ds_write_b16 v35, v10 offset:36720
	v_fma_f32 v10, v12, v11, -v19
	v_mul_f32_e32 v10, v39, v10
	v_fmac_f32_e32 v47, v43, v10
	v_cvt_pk_bf16_f32 v10, v47, s0
	v_and_b32_e32 v15, 0xffff0000, v15
	v_add_f32_e32 v11, 1.0, v14
	ds_write_b16 v35, v10 offset:36992
	v_mul_f32_e32 v10, v15, v15
	v_rcp_f32_e32 v11, v11
	v_fmamk_f32 v10, v10, 0xbdd2d3e7, v129
	v_mul_f32_e32 v10, v10, v15
	v_fma_f32 v14, v11, v13, -v19
	v_exp_f32_e32 v28, v10
	global_load_dwordx2 v[10:11], v20, s[16:17] offset:64
	global_load_dwordx2 v[12:13], v20, s[20:21] offset:64
	v_mul_f32_e32 v37, v29, v29
	v_fmamk_f32 v37, v37, 0xbdd2d3e7, v129
	v_add_f32_e32 v28, 1.0, v28
	v_mul_f32_e32 v37, v37, v29
	v_rcp_f32_e32 v28, v28
	v_exp_f32_e32 v37, v37
	v_fma_f32 v15, v28, v15, -v19
	v_mul_f32_e32 v46, v39, v15
	v_and_b32_e32 v15, 0xffff0000, v16
	v_mul_f32_e32 v16, v15, v15
	v_mul_f32_e32 v47, v39, v14
	v_add_f32_e32 v14, 1.0, v37
	v_fmamk_f32 v16, v16, 0xbdd2d3e7, v129
	v_rcp_f32_e32 v14, v14
	v_mul_f32_e32 v16, v16, v15
	v_exp_f32_e32 v16, v16
	v_fma_f32 v14, v14, v29, -v19
	v_mul_f32_e32 v14, v39, v14
	v_fma_f32 v14, v24, v14, v26
	v_lshlrev_b32_e32 v24, 16, v17
	v_add_f32_e32 v16, 1.0, v16
	v_mul_f32_e32 v26, v24, v24
	v_rcp_f32_e32 v16, v16
	v_fmamk_f32 v26, v26, 0xbdd2d3e7, v129
	v_mul_f32_e32 v26, v26, v24
	v_cvt_pk_bf16_f32 v14, v14, s0
	v_exp_f32_e32 v26, v26
	ds_write_b16 v35, v14 offset:37808
	v_fma_f32 v14, v16, v15, -v19
	v_mul_f32_e32 v14, v39, v14
	v_fmac_f32_e32 v27, v14, v25
	v_cvt_pk_bf16_f32 v14, v27, s0
	v_and_b32_e32 v25, 0xffff0000, v17
	v_add_f32_e32 v15, 1.0, v26
	ds_write_b16 v35, v14 offset:38080
	v_mul_f32_e32 v14, v25, v25
	v_rcp_f32_e32 v15, v15
	v_fmamk_f32 v14, v14, 0xbdd2d3e7, v129
	v_mul_f32_e32 v14, v14, v25
	v_fma_f32 v24, v15, v24, -v19
	v_exp_f32_e32 v26, v14
	global_load_dwordx2 v[14:15], v20, s[16:17] offset:80
	global_load_dwordx2 v[16:17], v20, s[20:21] offset:80
	s_waitcnt vmcnt(4)
	v_lshlrev_b32_e32 v27, 16, v6
	v_mul_f32_e32 v28, v27, v27
	v_fmamk_f32 v28, v28, 0xbdd2d3e7, v129
	v_mul_f32_e32 v28, v28, v27
	v_exp_f32_e32 v28, v28
	v_mul_f32_e32 v55, v39, v24
	v_mul_f32_e32 v53, v48, v48
	v_fmamk_f32 v53, v53, 0xbdd2d3e7, v129
	v_add_f32_e32 v24, 1.0, v28
	v_rcp_f32_e32 v24, v24
	v_and_b32_e32 v6, 0xffff0000, v6
	v_mul_f32_e32 v53, v53, v48
	v_fma_f32 v24, v24, v27, -v19
	v_mul_f32_e32 v40, v39, v24
	v_mul_f32_e32 v24, v6, v6
	v_fmamk_f32 v24, v24, 0xbdd2d3e7, v129
	v_mul_f32_e32 v24, v24, v6
	v_exp_f32_e32 v53, v53
	v_exp_f32_e32 v41, v24
	v_add_f32_e32 v53, 1.0, v53
	v_add_f32_e32 v26, 1.0, v26
	v_rcp_f32_e32 v53, v53
	v_rcp_f32_e32 v26, v26
	s_waitcnt vmcnt(2)
	v_fma_f32 v10, v10, v40, v12
	v_lshlrev_b32_e32 v40, 16, v7
	v_add_f32_e32 v12, 1.0, v41
	v_mul_f32_e32 v41, v40, v40
	v_fmamk_f32 v41, v41, 0xbdd2d3e7, v129
	v_mul_f32_e32 v41, v41, v40
	v_fma_f32 v48, v53, v48, -v19
	v_fma_f32 v25, v26, v25, -v19
	v_mul_f32_e32 v65, v39, v48
	v_mul_f32_e32 v54, v39, v25
	global_load_dwordx2 v[24:25], v20, s[16:17] offset:96
	global_load_dwordx2 v[28:29], v20, s[16:17] offset:112
	global_load_dwordx2 v[26:27], v20, s[20:21] offset:96
	global_load_dwordx2 v[48:49], v20, s[20:21] offset:112
	v_exp_f32_e32 v41, v41
	v_rcp_f32_e32 v12, v12
	v_cvt_pk_bf16_f32 v10, v10, s0
	ds_write_b16 v35, v10 offset:38896
	v_add_f32_e32 v10, 1.0, v41
	v_fma_f32 v6, v12, v6, -v19
	v_rcp_f32_e32 v10, v10
	v_mul_f32_e32 v6, v39, v6
	v_fmac_f32_e32 v13, v11, v6
	v_cvt_pk_bf16_f32 v6, v13, s0
	v_and_b32_e32 v7, 0xffff0000, v7
	ds_write_b16 v35, v6 offset:39168
	v_fma_f32 v6, v10, v40, -v19
	v_mul_f32_e32 v10, v7, v7
	v_fmamk_f32 v10, v10, 0xbdd2d3e7, v129
	v_mul_f32_e32 v10, v10, v7
	v_exp_f32_e32 v10, v10
	v_lshlrev_b32_e32 v11, 16, v8
	v_mul_f32_e32 v12, v11, v11
	v_fmamk_f32 v12, v12, 0xbdd2d3e7, v129
	v_mul_f32_e32 v12, v12, v11
	v_add_f32_e32 v10, 1.0, v10
	v_rcp_f32_e32 v10, v10
	v_exp_f32_e32 v12, v12
	v_mul_f32_e32 v53, v39, v6
	v_fma_f32 v7, v10, v7, -v19
	v_mul_f32_e32 v52, v39, v7
	v_and_b32_e32 v7, 0xffff0000, v8
	v_add_f32_e32 v6, 1.0, v12
	v_mul_f32_e32 v8, v7, v7
	v_rcp_f32_e32 v6, v6
	v_fmamk_f32 v8, v8, 0xbdd2d3e7, v129
	v_mul_f32_e32 v8, v8, v7
	v_lshlrev_b32_e32 v10, 16, v9
	v_fma_f32 v6, v6, v11, -v19
	v_exp_f32_e32 v8, v8
	v_mul_f32_e32 v11, v10, v10
	v_fmamk_f32 v11, v11, 0xbdd2d3e7, v129
	v_mul_f32_e32 v11, v11, v10
	v_add_f32_e32 v8, 1.0, v8
	v_rcp_f32_e32 v8, v8
	v_exp_f32_e32 v11, v11
	v_mul_f32_e32 v6, v39, v6
	s_waitcnt vmcnt(4)
	v_fma_f32 v6, v14, v6, v16
	v_cvt_pk_bf16_f32 v6, v6, s0
	ds_write_b16 v35, v6 offset:39984
	v_fma_f32 v6, v8, v7, -v19
	v_add_f32_e32 v7, 1.0, v11
	v_rcp_f32_e32 v7, v7
	v_mul_f32_e32 v6, v39, v6
	v_fmac_f32_e32 v17, v6, v15
	v_cvt_pk_bf16_f32 v6, v17, s0
	ds_write_b16 v35, v6 offset:40256
	v_fma_f32 v6, v7, v10, -v19
	v_and_b32_e32 v7, 0xffff0000, v9
	v_lshlrev_b32_e32 v9, 16, v2
	v_mul_f32_e32 v10, v9, v9
	v_fmamk_f32 v10, v10, 0xbdd2d3e7, v129
	v_mul_f32_e32 v8, v7, v7
	v_mul_f32_e32 v10, v10, v9
	v_fmamk_f32 v8, v8, 0xbdd2d3e7, v129
	v_mul_f32_e32 v8, v8, v7
	v_exp_f32_e32 v10, v10
	v_exp_f32_e32 v8, v8
	v_mul_f32_e32 v58, v39, v6
	v_add_f32_e32 v6, 1.0, v10
	global_load_dwordx4 v[10:13], v[22:23], off offset:1104
	global_load_dwordx4 v[14:17], v[22:23], off offset:1088
	v_add_f32_e32 v8, 1.0, v8
	v_rcp_f32_e32 v8, v8
	v_and_b32_e32 v2, 0xffff0000, v2
	v_rcp_f32_e32 v6, v6
	v_or_b32_e32 v18, 4, v34
	v_fma_f32 v7, v8, v7, -v19
	v_mul_f32_e32 v56, v39, v7
	v_mul_f32_e32 v7, v2, v2
	v_fmamk_f32 v7, v7, 0xbdd2d3e7, v129
	v_mul_f32_e32 v7, v7, v2
	v_exp_f32_e32 v7, v7
	v_lshlrev_b32_e32 v8, 16, v3
	v_fma_f32 v6, v6, v9, -v19
	v_mul_f32_e32 v9, v8, v8
	v_add_f32_e32 v7, 1.0, v7
	v_rcp_f32_e32 v7, v7
	v_fmamk_f32 v9, v9, 0xbdd2d3e7, v129
	v_mul_f32_e32 v9, v9, v8
	v_fma_f32 v2, v7, v2, -v19
	v_mul_f32_e32 v6, v39, v6
	v_mul_f32_e32 v2, v39, v2
	s_waitcnt vmcnt(3)
	v_fma_f32 v6, v24, v6, v26
	v_exp_f32_e32 v9, v9
	v_fmac_f32_e32 v27, v25, v2
	v_cvt_pk_bf16_f32 v6, v6, s0
	v_cvt_pk_bf16_f32 v2, v27, s0
	ds_write_b16 v35, v6 offset:41072
	ds_write_b16 v35, v2 offset:41344
	global_load_dwordx2 v[24:25], v20, s[16:17] offset:128
	global_load_dwordx2 v[26:27], v20, s[20:21] offset:128
	v_add_f32_e32 v6, 1.0, v9
	v_rcp_f32_e32 v6, v6
	v_and_b32_e32 v3, 0xffff0000, v3
	v_lshlrev_b32_e32 v7, 16, v4
	v_or_b32_e32 v36, 8, v34
	v_fma_f32 v2, v6, v8, -v19
	v_mul_f32_e32 v6, v3, v3
	v_fmamk_f32 v6, v6, 0xbdd2d3e7, v129
	v_mul_f32_e32 v6, v6, v3
	v_exp_f32_e32 v6, v6
	v_mul_f32_e32 v8, v7, v7
	v_fmamk_f32 v8, v8, 0xbdd2d3e7, v129
	v_mul_f32_e32 v8, v8, v7
	v_add_f32_e32 v6, 1.0, v6
	v_rcp_f32_e32 v6, v6
	v_exp_f32_e32 v8, v8
	v_mul_f32_e32 v64, v39, v2
	v_fma_f32 v3, v6, v3, -v19
	v_mul_f32_e32 v63, v39, v3
	v_and_b32_e32 v3, 0xffff0000, v4
	v_add_f32_e32 v2, 1.0, v8
	v_mul_f32_e32 v4, v3, v3
	v_rcp_f32_e32 v2, v2
	v_fmamk_f32 v4, v4, 0xbdd2d3e7, v129
	v_mul_f32_e32 v4, v4, v3
	v_fma_f32 v2, v2, v7, -v19
	v_exp_f32_e32 v4, v4
	v_mul_f32_e32 v2, v39, v2
	s_waitcnt vmcnt(4)
	v_fma_f32 v2, v28, v2, v48
	v_cvt_pk_bf16_f32 v2, v2, s0
	ds_write_b16 v35, v2 offset:42160
	v_add_f32_e32 v2, 1.0, v4
	v_lshlrev_b32_e32 v4, 16, v5
	v_mul_f32_e32 v6, v4, v4
	v_fmamk_f32 v6, v6, 0xbdd2d3e7, v129
	v_rcp_f32_e32 v2, v2
	v_mul_f32_e32 v6, v6, v4
	v_exp_f32_e32 v6, v6
	v_fma_f32 v2, v2, v3, -v19
	v_mul_f32_e32 v2, v39, v2
	v_fmac_f32_e32 v49, v2, v29
	v_add_f32_e32 v2, 1.0, v6
	v_cvt_pk_bf16_f32 v6, v49, s0
	ds_write_b16 v35, v6 offset:42432
	global_load_dwordx2 v[60:61], v20, s[16:17] offset:144
	global_load_dwordx2 v[66:67], v20, s[20:21] offset:144
	v_and_b32_e32 v3, 0xffff0000, v5
	v_mul_f32_e32 v5, v3, v3
	v_fmamk_f32 v5, v5, 0xbdd2d3e7, v129
	v_mul_f32_e32 v5, v5, v3
	v_rcp_f32_e32 v2, v2
	v_exp_f32_e32 v5, v5
	s_waitcnt vmcnt(4)
	v_lshlrev_b32_e32 v28, 16, v14
	v_and_b32_e32 v14, 0xffff0000, v14
	v_fma_f32 v2, v2, v4, -v19
	v_add_f32_e32 v4, 1.0, v5
	v_mul_f32_e32 v5, v28, v28
	v_fmamk_f32 v5, v5, 0xbdd2d3e7, v129
	v_mul_f32_e32 v5, v5, v28
	v_rcp_f32_e32 v4, v4
	v_exp_f32_e32 v5, v5
	v_mul_f32_e32 v69, v39, v2
	v_fma_f32 v2, v4, v3, -v19
	v_mul_f32_e32 v68, v39, v2
	v_add_f32_e32 v2, 1.0, v5
	v_rcp_f32_e32 v29, v2
	global_load_dwordx4 v[2:5], v[22:23], off offset:1136
	global_load_dwordx4 v[6:9], v[22:23], off offset:1120
	v_or_b32_e32 v37, 12, v34
	v_or_b32_e32 v38, 16, v34
	v_fma_f32 v22, v29, v28, -v19
	v_mul_f32_e32 v48, v39, v22
	v_mul_f32_e32 v22, v14, v14
	v_fmamk_f32 v22, v22, 0xbdd2d3e7, v129
	v_mul_f32_e32 v22, v22, v14
	v_exp_f32_e32 v49, v22
	global_load_dwordx2 v[74:75], v20, s[16:17] offset:160
	global_load_dwordx2 v[22:23], v20, s[16:17] offset:176
	global_load_dwordx2 v[76:77], v20, s[20:21] offset:160
	global_load_dwordx2 v[28:29], v20, s[20:21] offset:176
	s_waitcnt vmcnt(8)
	v_fma_f32 v24, v24, v48, v26
	v_lshlrev_b32_e32 v48, 16, v15
	v_add_f32_e32 v26, 1.0, v49
	v_mul_f32_e32 v49, v48, v48
	v_fmamk_f32 v49, v49, 0xbdd2d3e7, v129
	v_mul_f32_e32 v49, v49, v48
	v_exp_f32_e32 v49, v49
	v_rcp_f32_e32 v26, v26
	v_cvt_pk_bf16_f32 v24, v24, s0
	ds_write_b16 v35, v24 offset:43248
	v_add_f32_e32 v24, 1.0, v49
	v_fma_f32 v14, v26, v14, -v19
	v_rcp_f32_e32 v24, v24
	v_mul_f32_e32 v14, v39, v14
	v_fmac_f32_e32 v27, v25, v14
	v_cvt_pk_bf16_f32 v14, v27, s0
	v_and_b32_e32 v15, 0xffff0000, v15
	ds_write_b16 v35, v14 offset:43520
	v_fma_f32 v14, v24, v48, -v19
	v_mul_f32_e32 v24, v15, v15
	v_fmamk_f32 v24, v24, 0xbdd2d3e7, v129
	v_mul_f32_e32 v24, v24, v15
	v_exp_f32_e32 v24, v24
	v_lshlrev_b32_e32 v25, 16, v16
	v_mul_f32_e32 v26, v25, v25
	v_fmamk_f32 v26, v26, 0xbdd2d3e7, v129
	v_mul_f32_e32 v26, v26, v25
	v_add_f32_e32 v24, 1.0, v24
	v_rcp_f32_e32 v24, v24
	v_exp_f32_e32 v26, v26
	v_mul_f32_e32 v73, v39, v14
	v_fma_f32 v15, v24, v15, -v19
	v_mul_f32_e32 v72, v39, v15
	v_and_b32_e32 v15, 0xffff0000, v16
	v_add_f32_e32 v14, 1.0, v26
	v_mul_f32_e32 v16, v15, v15
	v_rcp_f32_e32 v14, v14
	v_fmamk_f32 v16, v16, 0xbdd2d3e7, v129
	v_mul_f32_e32 v16, v16, v15
	v_lshlrev_b32_e32 v24, 16, v17
	v_fma_f32 v14, v14, v25, -v19
	v_exp_f32_e32 v16, v16
	v_mul_f32_e32 v25, v24, v24
	v_fmamk_f32 v25, v25, 0xbdd2d3e7, v129
	v_mul_f32_e32 v25, v25, v24
	v_add_f32_e32 v16, 1.0, v16
	v_rcp_f32_e32 v16, v16
	v_exp_f32_e32 v25, v25
	v_mul_f32_e32 v14, v39, v14
	s_waitcnt vmcnt(6)
	v_fma_f32 v14, v60, v14, v66
	v_cvt_pk_bf16_f32 v14, v14, s0
	ds_write_b16 v35, v14 offset:44336
	v_fma_f32 v14, v16, v15, -v19
	v_add_f32_e32 v15, 1.0, v25
	v_rcp_f32_e32 v15, v15
	v_mul_f32_e32 v14, v39, v14
	v_fmac_f32_e32 v67, v14, v61
	v_cvt_pk_bf16_f32 v14, v67, s0
	ds_write_b16 v35, v14 offset:44608
	v_fma_f32 v14, v15, v24, -v19
	v_and_b32_e32 v15, 0xffff0000, v17
	v_mul_f32_e32 v16, v15, v15
	v_fmamk_f32 v16, v16, 0xbdd2d3e7, v129
	v_mul_f32_e32 v16, v16, v15
	v_exp_f32_e32 v16, v16
	v_lshlrev_b32_e32 v17, 16, v10
	v_mul_f32_e32 v24, v17, v17
	v_fmamk_f32 v24, v24, 0xbdd2d3e7, v129
	v_mul_f32_e32 v24, v24, v17
	v_add_f32_e32 v16, 1.0, v16
	v_rcp_f32_e32 v16, v16
	v_exp_f32_e32 v24, v24
	v_and_b32_e32 v10, 0xffff0000, v10
	v_mul_f32_e32 v71, v39, v14
	v_fma_f32 v15, v16, v15, -v19
	v_add_f32_e32 v14, 1.0, v24
	v_mul_f32_e32 v70, v39, v15
	v_mul_f32_e32 v15, v10, v10
	v_rcp_f32_e32 v14, v14
	v_fmamk_f32 v15, v15, 0xbdd2d3e7, v129
	v_mul_f32_e32 v15, v15, v10
	v_fma_f32 v14, v14, v17, -v19
	v_exp_f32_e32 v15, v15
	v_mul_f32_e32 v14, v39, v14
	s_waitcnt vmcnt(1)
	v_fma_f32 v14, v74, v14, v76
	v_cvt_pk_bf16_f32 v14, v14, s0
	ds_write_b16 v35, v14 offset:45424
	v_add_f32_e32 v14, 1.0, v15
	v_lshlrev_b32_e32 v15, 16, v11
	v_rcp_f32_e32 v14, v14
	v_mul_f32_e32 v16, v15, v15
	v_fmamk_f32 v16, v16, 0xbdd2d3e7, v129
	v_mul_f32_e32 v16, v16, v15
	v_and_b32_e32 v11, 0xffff0000, v11
	v_fma_f32 v10, v14, v10, -v19
	v_mul_f32_e32 v14, v11, v11
	v_exp_f32_e32 v16, v16
	v_fmamk_f32 v14, v14, 0xbdd2d3e7, v129
	v_mul_f32_e32 v14, v14, v11
	v_mul_f32_e32 v10, v39, v10
	v_fmac_f32_e32 v77, v75, v10
	v_add_f32_e32 v10, 1.0, v16
	v_exp_f32_e32 v14, v14
	v_rcp_f32_e32 v10, v10
	v_cvt_pk_bf16_f32 v16, v77, s0
	ds_write_b16 v35, v16 offset:45696
	v_add_f32_e32 v14, 1.0, v14
	v_fma_f32 v10, v10, v15, -v19
	v_rcp_f32_e32 v14, v14
	v_lshlrev_b32_e32 v15, 16, v12
	v_mul_f32_e32 v16, v15, v15
	v_fmamk_f32 v16, v16, 0xbdd2d3e7, v129
	v_mul_f32_e32 v16, v16, v15
	v_mul_f32_e32 v67, v39, v10
	v_fma_f32 v10, v14, v11, -v19
	v_and_b32_e32 v11, 0xffff0000, v12
	v_mul_f32_e32 v12, v11, v11
	v_exp_f32_e32 v16, v16
	v_fmamk_f32 v12, v12, 0xbdd2d3e7, v129
	v_mul_f32_e32 v12, v12, v11
	v_mul_f32_e32 v66, v39, v10
	v_add_f32_e32 v10, 1.0, v16
	v_exp_f32_e32 v12, v12
	v_rcp_f32_e32 v10, v10
	v_or_b32_e32 v76, 2, v34
	v_lshlrev_b32_e32 v14, 2, v76
	v_add_f32_e32 v12, 1.0, v12
	v_fma_f32 v10, v10, v15, -v19
	v_rcp_f32_e32 v12, v12
	v_mul_f32_e32 v10, v39, v10
	s_waitcnt vmcnt(0)
	v_fma_f32 v10, v22, v10, v28
	v_cvt_pk_bf16_f32 v10, v10, s0
	ds_write_b16 v35, v10 offset:46512
	v_fma_f32 v10, v12, v11, -v19
	v_lshlrev_b32_e32 v11, 16, v13
	v_mul_f32_e32 v12, v11, v11
	v_fmamk_f32 v12, v12, 0xbdd2d3e7, v129
	v_mul_f32_e32 v12, v12, v11
	v_exp_f32_e32 v12, v12
	v_mul_f32_e32 v10, v39, v10
	v_fmac_f32_e32 v29, v10, v23
	v_cvt_pk_bf16_f32 v10, v29, s0
	global_load_dword v15, v14, s[16:17]
	s_nop 0
	global_load_dword v14, v14, s[20:21]
	ds_write_b16 v35, v10 offset:46784
	v_add_f32_e32 v10, 1.0, v12
	v_rcp_f32_e32 v10, v10
	v_or_b32_e32 v77, 3, v34
	v_lshlrev_b32_e32 v12, 2, v77
	global_load_dword v16, v12, s[16:17]
	global_load_dword v17, v12, s[20:21]
	v_fma_f32 v10, v10, v11, -v19
	v_and_b32_e32 v11, 0xffff0000, v13
	v_mul_f32_e32 v12, v11, v11
	v_fmamk_f32 v12, v12, 0xbdd2d3e7, v129
	v_mul_f32_e32 v12, v12, v11
	v_lshlrev_b32_e32 v13, 16, v6
	v_exp_f32_e32 v12, v12
	v_mul_f32_e32 v22, v13, v13
	v_fmamk_f32 v22, v22, 0xbdd2d3e7, v129
	v_mul_f32_e32 v22, v22, v13
	v_add_f32_e32 v12, 1.0, v12
	v_exp_f32_e32 v22, v22
	v_rcp_f32_e32 v12, v12
	v_mul_f32_e32 v75, v39, v10
	v_and_b32_e32 v6, 0xffff0000, v6
	v_add_f32_e32 v10, 1.0, v22
	v_fma_f32 v11, v12, v11, -v19
	v_rcp_f32_e32 v10, v10
	v_mul_f32_e32 v74, v39, v11
	v_mul_f32_e32 v11, v6, v6
	v_fmamk_f32 v11, v11, 0xbdd2d3e7, v129
	v_mul_f32_e32 v11, v11, v6
	v_fma_f32 v10, v10, v13, -v19
	v_exp_f32_e32 v22, v11
	v_mul_f32_e32 v82, v39, v10
	global_load_dwordx2 v[10:11], v20, s[16:17] offset:192
	global_load_dwordx2 v[12:13], v20, s[20:21] offset:192
	v_lshlrev_b32_e32 v23, 16, v7
	v_mul_f32_e32 v24, v23, v23
	v_and_b32_e32 v7, 0xffff0000, v7
	v_fmamk_f32 v24, v24, 0xbdd2d3e7, v129
	v_mul_f32_e32 v25, v7, v7
	v_mul_f32_e32 v24, v24, v23
	v_fmamk_f32 v25, v25, 0xbdd2d3e7, v129
	v_mul_f32_e32 v25, v25, v7
	v_add_f32_e32 v22, 1.0, v22
	v_rcp_f32_e32 v22, v22
	v_exp_f32_e32 v24, v24
	v_exp_f32_e32 v25, v25
	v_fma_f32 v6, v22, v6, -v19
	v_add_f32_e32 v22, 1.0, v24
	v_rcp_f32_e32 v22, v22
	v_add_f32_e32 v24, 1.0, v25
	v_rcp_f32_e32 v24, v24
	v_mul_f32_e32 v83, v39, v6
	v_fma_f32 v6, v22, v23, -v19
	v_mul_f32_e32 v62, v39, v6
	v_fma_f32 v6, v24, v7, -v19
	v_lshlrev_b32_e32 v91, 16, v8
	v_mul_f32_e32 v61, v39, v6
	v_or_b32_e32 v6, s88, v31
	v_lshlrev_b32_e32 v6, 7, v6
	v_mov_b32_e32 v7, v1
	v_lshl_add_u64 v[6:7], v[6:7], 2, s[40:41]
	v_lshl_add_u64 v[6:7], v[6:7], 0, v[20:21]
	v_and_b32_e32 v8, 0xffff0000, v8
	v_mul_f32_e32 v98, v8, v8
	v_fmamk_f32 v98, v98, 0xbdd2d3e7, v129
	v_mul_f32_e32 v98, v98, v8
	v_exp_f32_e32 v98, v98
	v_and_b32_e32 v99, 0xffff0000, v9
	v_and_b32_e32 v105, 0xffff0000, v5
	s_waitcnt vmcnt(4)
	v_fmac_f32_e32 v14, v15, v65
	v_mul_u32_u24_e32 v15, 0x110, v76
	v_cvt_pk_bf16_f32 v14, v14, s0
	v_add3_u32 v15, s15, v15, v33
	v_or_b32_e32 v65, 6, v34
	ds_write_b16 v15, v14 offset:34816
	v_lshlrev_b32_e32 v14, 2, v65
	global_load_dword v85, v14, s[16:17]
	global_load_dword v86, v14, s[20:21]
	s_waitcnt vmcnt(4)
	v_fmac_f32_e32 v17, v16, v59
	v_lshlrev_b32_e32 v14, 2, v78
	v_mul_u32_u24_e32 v15, 0x110, v77
	global_load_dword v87, v14, s[16:17]
	global_load_dword v88, v14, s[20:21]
	v_cvt_pk_bf16_f32 v14, v17, s0
	v_add3_u32 v15, s15, v15, v33
	ds_write_b16 v15, v14 offset:34816
	v_lshlrev_b32_e32 v14, 2, v81
	global_load_dwordx2 v[22:23], v20, s[16:17] offset:208
	global_load_dwordx2 v[24:25], v20, s[20:21] offset:208
	global_load_dword v89, v14, s[16:17]
	global_load_dword v90, v14, s[20:21]
	v_lshlrev_b32_e32 v14, 2, v79
	global_load_dword v92, v14, s[16:17]
	global_load_dword v93, v14, s[20:21]
	v_mul_f32_e32 v14, v91, v91
	v_fmamk_f32 v14, v14, 0xbdd2d3e7, v129
	v_mul_f32_e32 v14, v14, v91
	v_or_b32_e32 v59, 14, v34
	v_lshlrev_b32_e32 v15, 2, v59
	global_load_dword v94, v15, s[16:17]
	global_load_dword v95, v15, s[20:21]
	v_exp_f32_e32 v96, v14
	global_load_dwordx2 v[14:15], v20, s[16:17] offset:224
	global_load_dwordx2 v[16:17], v20, s[16:17] offset:240
	global_load_dwordx2 v[26:27], v20, s[20:21] offset:224
	s_nop 0
	global_load_dwordx2 v[20:21], v20, s[20:21] offset:240
	v_or_b32_e32 v40, 20, v34
	v_or_b32_e32 v41, 24, v34
	v_or_b32_e32 v42, 28, v34
	v_or_b32_e32 v43, 32, v34
	v_or_b32_e32 v48, 36, v34
	v_or_b32_e32 v49, 40, v34
	v_or_b32_e32 v51, 44, v34
	v_or_b32_e32 v60, 52, v34
	s_waitcnt vmcnt(16)
	v_fma_f32 v10, v10, v82, v12
	v_cvt_pk_bf16_f32 v12, v10, s0
	v_or_b32_e32 v10, 15, v34
	v_add_f32_e32 v82, 1.0, v96
	v_lshlrev_b32_e32 v96, 2, v10
	global_load_dword v97, v96, s[16:17]
	s_nop 0
	global_load_dword v96, v96, s[20:21]
	v_rcp_f32_e32 v82, v82
	ds_write_b16 v35, v12 offset:47600
	v_fmac_f32_e32 v13, v11, v83
	v_cvt_pk_bf16_f32 v11, v13, s0
	v_fma_f32 v12, v82, v91, -v19
	v_lshlrev_b32_e32 v91, 16, v9
	v_add_f32_e32 v82, 1.0, v98
	v_mul_f32_e32 v98, v91, v91
	v_fmamk_f32 v98, v98, 0xbdd2d3e7, v129
	v_mul_f32_e32 v98, v98, v91
	v_rcp_f32_e32 v82, v82
	v_exp_f32_e32 v98, v98
	v_mul_f32_e32 v12, v39, v12
	v_mul_u32_u24_e32 v13, 0x110, v81
	v_fma_f32 v8, v82, v8, -v19
	v_add_f32_e32 v82, 1.0, v98
	v_rcp_f32_e32 v82, v82
	v_mul_f32_e32 v100, v39, v8
	v_add3_u32 v13, s15, v13, v33
	v_mul_f32_e32 v9, v99, v99
	v_fma_f32 v8, v82, v91, -v19
	v_mul_u32_u24_e32 v82, 0x110, v65
	v_add3_u32 v82, s15, v82, v33
	v_fmamk_f32 v9, v9, 0xbdd2d3e7, v129
	v_mul_f32_e32 v9, v9, v99
	v_exp_f32_e32 v9, v9
	v_or_b32_e32 v91, 26, v34
	v_or_b32_e32 v29, 56, v34
	v_or_b32_e32 v28, 60, v34
	v_add_f32_e32 v9, 1.0, v9
	v_rcp_f32_e32 v98, v9
	v_mul_f32_e32 v9, v39, v8
	v_readlane_b32 s46, v251, 56
	v_readlane_b32 s47, v251, 57
	v_fma_f32 v8, v98, v99, -v19
	v_or_b32_e32 v98, 30, v34
	v_mul_f32_e32 v8, v39, v8
	v_readlane_b32 s48, v251, 58
	v_readlane_b32 s49, v251, 59
	s_waitcnt vmcnt(16)
	v_fmac_f32_e32 v86, v45, v85
	v_cvt_pk_bf16_f32 v45, v86, s0
	ds_write_b16 v82, v45 offset:34816
	v_mul_u32_u24_e32 v45, 0x110, v78
	s_waitcnt vmcnt(14)
	v_fmac_f32_e32 v88, v44, v87
	v_cvt_pk_bf16_f32 v44, v88, s0
	v_add3_u32 v45, s15, v45, v33
	ds_write_b16 v45, v44 offset:34816
	ds_write_b16 v35, v11 offset:47872
	s_waitcnt vmcnt(12)
	v_fma_f32 v11, v22, v12, v24
	s_waitcnt vmcnt(10)
	v_fmac_f32_e32 v90, v89, v47
	v_cvt_pk_bf16_f32 v12, v90, s0
	ds_write_b16 v13, v12 offset:34816
	s_waitcnt vmcnt(8)
	v_fmac_f32_e32 v93, v92, v46
	v_mul_u32_u24_e32 v13, 0x110, v79
	v_cvt_pk_bf16_f32 v12, v93, s0
	v_add3_u32 v13, s15, v13, v33
	v_cvt_pk_bf16_f32 v11, v11, s0
	ds_write_b16 v13, v12 offset:34816
	ds_write_b16 v35, v11 offset:48688
	v_lshlrev_b32_e32 v13, 16, v2
	v_mul_f32_e32 v22, v13, v13
	v_fmamk_f32 v22, v22, 0xbdd2d3e7, v129
	v_mul_f32_e32 v22, v22, v13
	v_exp_f32_e32 v22, v22
	v_fmac_f32_e32 v25, v100, v23
	v_cvt_pk_bf16_f32 v11, v25, s0
	s_waitcnt vmcnt(6)
	v_fmac_f32_e32 v95, v55, v94
	v_mul_u32_u24_e32 v12, 0x110, v59
	ds_write_b16 v35, v11 offset:48960
	v_cvt_pk_bf16_f32 v11, v95, s0
	v_add3_u32 v12, s15, v12, v33
	ds_write_b16 v12, v11 offset:34816
	v_add_f32_e32 v12, 1.0, v22
	v_rcp_f32_e32 v12, v12
	s_waitcnt vmcnt(0)
	v_fmac_f32_e32 v96, v54, v97
	v_mul_u32_u24_e32 v22, 0x110, v10
	v_cvt_pk_bf16_f32 v11, v96, s0
	v_add3_u32 v22, s15, v22, v33
	v_and_b32_e32 v2, 0xffff0000, v2
	ds_write_b16 v22, v11 offset:34816
	v_fma_f32 v11, v12, v13, -v19
	v_mul_f32_e32 v12, v2, v2
	v_lshlrev_b32_e32 v13, 16, v3
	v_fmamk_f32 v12, v12, 0xbdd2d3e7, v129
	v_mul_f32_e32 v22, v13, v13
	v_mul_f32_e32 v12, v12, v2
	v_fmamk_f32 v22, v22, 0xbdd2d3e7, v129
	v_mul_f32_e32 v22, v22, v13
	v_exp_f32_e32 v12, v12
	v_exp_f32_e32 v22, v22
	v_mul_f32_e32 v11, v39, v11
	v_add_f32_e32 v12, 1.0, v12
	v_fma_f32 v11, v14, v11, v26
	v_rcp_f32_e32 v12, v12
	v_add_f32_e32 v14, 1.0, v22
	v_rcp_f32_e32 v14, v14
	v_and_b32_e32 v3, 0xffff0000, v3
	v_fma_f32 v2, v12, v2, -v19
	v_mul_f32_e32 v12, v39, v2
	v_fma_f32 v2, v14, v13, -v19
	v_mul_f32_e32 v13, v3, v3
	v_fmamk_f32 v13, v13, 0xbdd2d3e7, v129
	v_mul_f32_e32 v13, v13, v3
	v_or_b32_e32 v86, 18, v34
	v_or_b32_e32 v87, 19, v34
	v_lshlrev_b32_e32 v14, 2, v86
	v_lshlrev_b32_e32 v22, 2, v87
	global_load_dword v26, v14, s[16:17]
	s_nop 0
	global_load_dword v14, v14, s[20:21]
	s_nop 0
	global_load_dword v54, v22, s[16:17]
	global_load_dword v55, v22, s[20:21]
	v_lshlrev_b32_e32 v22, 16, v4
	v_exp_f32_e32 v13, v13
	v_mul_f32_e32 v23, v22, v22
	v_fmamk_f32 v23, v23, 0xbdd2d3e7, v129
	v_mul_f32_e32 v23, v23, v22
	v_add_f32_e32 v13, 1.0, v13
	v_rcp_f32_e32 v13, v13
	v_exp_f32_e32 v23, v23
	v_or_b32_e32 v88, 22, v34
	v_lshlrev_b32_e32 v24, 2, v88
	v_fma_f32 v3, v13, v3, -v19
	v_add_f32_e32 v13, 1.0, v23
	global_load_dword v82, v24, s[16:17]
	global_load_dword v83, v24, s[20:21]
	v_or_b32_e32 v89, 23, v34
	v_rcp_f32_e32 v13, v13
	v_and_b32_e32 v4, 0xffff0000, v4
	v_lshlrev_b32_e32 v24, 2, v89
	v_mul_f32_e32 v23, v4, v4
	global_load_dword v84, v24, s[16:17]
	global_load_dword v85, v24, s[20:21]
	v_fmamk_f32 v23, v23, 0xbdd2d3e7, v129
	v_mul_f32_e32 v23, v23, v4
	v_fma_f32 v13, v13, v22, -v19
	v_lshlrev_b32_e32 v22, 2, v91
	global_load_dword v92, v22, s[16:17]
	global_load_dword v93, v22, s[20:21]
	v_or_b32_e32 v94, 27, v34
	v_exp_f32_e32 v23, v23
	v_lshlrev_b32_e32 v22, 2, v94
	global_load_dword v95, v22, s[16:17]
	global_load_dword v96, v22, s[20:21]
	v_lshlrev_b32_e32 v97, 16, v5
	v_lshlrev_b32_e32 v22, 2, v98
	global_load_dword v99, v22, s[16:17]
	global_load_dword v100, v22, s[20:21]
	v_mul_f32_e32 v22, 0x3d372713, v97
	v_mul_f32_e32 v90, v39, v13
	v_add_f32_e32 v13, 1.0, v23
	v_lshlrev_b32_e32 v23, 2, v101
	v_mul_f32_e32 v22, v22, v97
	global_load_dword v102, v23, s[16:17]
	global_load_dword v103, v23, s[20:21]
	v_fma_f32 v22, v22, v97, v97
	v_mul_f32_e32 v22, 0xbfcc422a, v22
	v_mul_f32_e32 v104, 0x3fb8aa3b, v22
	global_load_dwordx4 v[22:25], v[6:7], off offset:16
	global_load_dwordx4 v[44:47], v[6:7], off
	v_rcp_f32_e32 v13, v13
	v_exp_f32_e32 v104, v104
	v_mul_f32_e32 v5, v105, v105
	v_fmamk_f32 v5, v5, 0xbdd2d3e7, v129
	v_mul_f32_e32 v5, v5, v105
	v_fma_f32 v4, v13, v4, -v19
	v_add_f32_e32 v13, 1.0, v104
	v_rcp_f32_e32 v13, v13
	v_exp_f32_e32 v5, v5
	v_mul_f32_e32 v106, v39, v4
	v_cvt_pk_bf16_f32 v11, v11, s0
	v_fma_f32 v4, v13, v97, -v19
	v_add_f32_e32 v5, 1.0, v5
	v_rcp_f32_e32 v104, v5
	v_fmac_f32_e32 v27, v15, v12
	v_mul_f32_e32 v5, v39, v4
	v_fma_f32 v16, v16, v90, v20
	v_fma_f32 v4, v104, v105, -v19
	v_mul_u32_u24_e32 v19, 0x110, v88
	v_add3_u32 v19, s15, v19, v33
	v_cvt_pk_bf16_f32 v16, v16, s0
	v_fmac_f32_e32 v21, v106, v17
	v_mul_f32_e32 v2, v39, v2
	v_mul_f32_e32 v3, v39, v3
	v_mul_f32_e32 v4, v39, v4
	v_mul_u32_u24_e32 v17, 0x110, v91
	v_add3_u32 v17, s15, v17, v33
	v_readlane_b32 s56, v252, 2
	v_readlane_b32 s57, v252, 3
	v_readlane_b32 s58, v252, 4
	v_readlane_b32 s59, v252, 5
	s_waitcnt vmcnt(16)
	v_fmac_f32_e32 v14, v26, v53
	v_cvt_pk_bf16_f32 v13, v14, s0
	v_mul_u32_u24_e32 v14, 0x110, v86
	v_add3_u32 v14, s15, v14, v33
	ds_write_b16 v14, v13 offset:34816
	s_waitcnt vmcnt(14)
	v_fmac_f32_e32 v55, v54, v52
	v_mul_u32_u24_e32 v14, 0x110, v87
	v_cvt_pk_bf16_f32 v13, v55, s0
	v_add3_u32 v14, s15, v14, v33
	ds_write_b16 v14, v13 offset:34816
	ds_write_b16 v35, v11 offset:49776
	v_cvt_pk_bf16_f32 v11, v27, s0
	ds_write_b16 v35, v11 offset:50048
	global_load_dwordx4 v[12:15], v[6:7], off offset:48
	global_load_dwordx4 v[52:55], v[6:7], off offset:32
	s_waitcnt vmcnt(14)
	v_fmac_f32_e32 v83, v58, v82
	v_cvt_pk_bf16_f32 v11, v83, s0
	ds_write_b16 v19, v11 offset:34816
	v_mul_u32_u24_e32 v19, 0x110, v89
	v_add3_u32 v19, s15, v19, v33
	v_or_b32_e32 v58, 35, v34
	s_waitcnt vmcnt(12)
	v_fmac_f32_e32 v85, v56, v84
	v_cvt_pk_bf16_f32 v11, v85, s0
	v_or_b32_e32 v56, 34, v34
	ds_write_b16 v19, v11 offset:34816
	v_lshlrev_b32_e32 v11, 2, v56
	v_lshlrev_b32_e32 v19, 2, v58
	global_load_dword v39, v11, s[16:17]
	s_nop 0
	global_load_dword v11, v11, s[20:21]
	s_nop 0
	global_load_dword v90, v19, s[16:17]
	global_load_dword v97, v19, s[20:21]
	ds_write_b16 v35, v16 offset:50864
	v_cvt_pk_bf16_f32 v16, v21, s0
	s_waitcnt vmcnt(14)
	v_fmac_f32_e32 v93, v92, v64
	ds_write_b16 v35, v16 offset:51136
	v_cvt_pk_bf16_f32 v16, v93, s0
	ds_write_b16 v17, v16 offset:34816
	s_waitcnt vmcnt(12)
	v_fmac_f32_e32 v96, v95, v63
	v_mul_u32_u24_e32 v17, 0x110, v94
	v_cvt_pk_bf16_f32 v16, v96, s0
	v_add3_u32 v17, s15, v17, v33
	ds_write_b16 v17, v16 offset:34816
	s_waitcnt vmcnt(10)
	v_fmac_f32_e32 v100, v69, v99
	v_mul_u32_u24_e32 v17, 0x110, v98
	v_cvt_pk_bf16_f32 v16, v100, s0
	v_add3_u32 v17, s15, v17, v33
	ds_write_b16 v17, v16 offset:34816
	s_waitcnt vmcnt(8)
	v_fmac_f32_e32 v103, v68, v102
	v_mul_u32_u24_e32 v17, 0x110, v101
	v_cvt_pk_bf16_f32 v16, v103, s0
	v_add3_u32 v17, s15, v17, v33
	ds_write_b16 v17, v16 offset:34816
	s_waitcnt vmcnt(6)
	v_cndmask_b32_e32 v16, 0, v45, vcc
	v_cmp_le_u32_e32 vcc, v34, v31
	v_or_b32_e32 v35, 38, v34
	v_or_b32_e32 v68, 39, v34
	v_cndmask_b32_e32 v17, 0, v44, vcc
	v_cvt_pk_bf16_f32 v16, v17, v16
	v_lshlrev_b32_e32 v17, 2, v35
	global_load_dword v63, v17, s[16:17]
	global_load_dword v64, v17, s[20:21]
	v_lshlrev_b32_e32 v19, 2, v68
	global_load_dword v69, v19, s[16:17]
	global_load_dword v92, v19, s[20:21]
	v_cvt_pk_bf16_f32 v17, v46, v47
	v_cmp_le_u32_e32 vcc, v76, v31
	global_load_dwordx4 v[44:47], v[6:7], off offset:80
	global_load_dwordx4 v[82:85], v[6:7], off offset:64
	v_cndmask_b32_e32 v19, 0, v17, vcc
	v_lshrrev_b32_e32 v17, 16, v17
	v_cmp_le_u32_e32 vcc, v77, v31
	v_or_b32_e32 v77, 47, v34
	s_waitcnt vmcnt(8)
	v_fmac_f32_e32 v11, v39, v73
	v_cndmask_b32_e32 v17, 0, v17, vcc
	v_cmp_gt_u32_e32 vcc, v31, v18
	v_perm_b32 v17, v17, v19, s19
	v_cvt_pk_bf16_f32 v11, v11, s0
	v_cndmask_b32_e32 v19, 0, v23, vcc
	v_cmp_le_u32_e32 vcc, v18, v31
	s_waitcnt vmcnt(6)
	v_fmac_f32_e32 v97, v90, v72
	s_waitcnt vmcnt(4)
	v_fmac_f32_e32 v64, v71, v63
	v_cndmask_b32_e32 v18, 0, v22, vcc
	v_cvt_pk_bf16_f32 v18, v18, v19
	v_cvt_pk_bf16_f32 v19, v24, v25
	v_cmp_le_u32_e32 vcc, v65, v31
	s_waitcnt vmcnt(2)
	v_fmac_f32_e32 v92, v70, v69
	v_cndmask_b32_e32 v20, 0, v19, vcc
	v_lshrrev_b32_e32 v19, 16, v19
	v_cmp_le_u32_e32 vcc, v78, v31
	s_nop 1
	v_cndmask_b32_e32 v19, 0, v19, vcc
	v_perm_b32 v19, v19, v20, s19
	ds_write_b128 v0, v[16:19]
	global_load_dwordx4 v[20:23], v[6:7], off offset:112
	global_load_dwordx4 v[24:27], v[6:7], off offset:96
	v_cmp_gt_u32_e32 vcc, v31, v36
	s_nop 1
	v_cndmask_b32_e32 v16, 0, v53, vcc
	v_cmp_le_u32_e32 vcc, v36, v31
	s_nop 1
	v_cndmask_b32_e32 v17, 0, v52, vcc
	v_cvt_pk_bf16_f32 v16, v17, v16
	v_cvt_pk_bf16_f32 v17, v54, v55
	v_cmp_le_u32_e32 vcc, v81, v31
	v_or_b32_e32 v52, 42, v34
	v_or_b32_e32 v55, 43, v34
	v_cndmask_b32_e32 v18, 0, v17, vcc
	v_lshrrev_b32_e32 v17, 16, v17
	v_cmp_le_u32_e32 vcc, v79, v31
	v_lshlrev_b32_e32 v19, 2, v55
	v_and_or_b32 v81, v30, 64, v32
	v_cndmask_b32_e32 v17, 0, v17, vcc
	v_perm_b32 v17, v17, v18, s19
	v_mul_u32_u24_e32 v18, 0x110, v56
	v_add3_u32 v18, s15, v18, v33
	ds_write_b16 v18, v11 offset:34816
	v_lshlrev_b32_e32 v18, 2, v52
	global_load_dword v53, v18, s[16:17]
	global_load_dword v54, v18, s[20:21]
	v_mul_u32_u24_e32 v18, 0x110, v58
	v_cvt_pk_bf16_f32 v11, v97, s0
	v_add3_u32 v18, s15, v18, v33
	v_cmp_gt_u32_e32 vcc, v31, v37
	global_load_dword v65, v19, s[16:17]
	global_load_dword v72, v19, s[20:21]
	ds_write_b16 v18, v11 offset:34816
	v_cndmask_b32_e32 v11, 0, v13, vcc
	v_cmp_le_u32_e32 vcc, v37, v31
	s_waitcnt vmcnt(2)
	v_fmac_f32_e32 v54, v53, v67
	v_cndmask_b32_e32 v12, 0, v12, vcc
	v_cvt_pk_bf16_f32 v18, v12, v11
	v_cvt_pk_bf16_f32 v11, v14, v15
	v_cmp_le_u32_e32 vcc, v59, v31
	v_or_b32_e32 v59, 46, v34
	s_waitcnt vmcnt(0)
	v_fmac_f32_e32 v72, v65, v66
	v_cndmask_b32_e32 v12, 0, v11, vcc
	v_lshrrev_b32_e32 v11, 16, v11
	v_cmp_le_u32_e32 vcc, v10, v31
	s_nop 1
	v_cndmask_b32_e32 v10, 0, v11, vcc
	v_perm_b32 v19, v10, v12, s19
	v_lshlrev_b32_e32 v10, 2, v59
	global_load_dword v73, v10, s[16:17]
	global_load_dword v76, v10, s[20:21]
	ds_write_b128 v0, v[16:19] offset:16
	v_lshlrev_b32_e32 v10, 2, v77
	v_mul_u32_u24_e32 v11, 0x110, v35
	global_load_dword v78, v10, s[16:17]
	global_load_dword v79, v10, s[20:21]
	v_cvt_pk_bf16_f32 v10, v64, s0
	v_add3_u32 v11, s15, v11, v33
	ds_write_b16 v11, v10 offset:34816
	global_load_dwordx4 v[10:13], v[6:7], off offset:144
	global_load_dwordx4 v[14:17], v[6:7], off offset:128
	v_mul_u32_u24_e32 v19, 0x110, v68
	v_cvt_pk_bf16_f32 v18, v92, s0
	v_add3_u32 v19, s15, v19, v33
	v_cmp_gt_u32_e32 vcc, v31, v38
	ds_write_b16 v19, v18 offset:34816
	s_waitcnt vmcnt(4)
	v_fmac_f32_e32 v76, v75, v73
	v_cndmask_b32_e32 v18, 0, v83, vcc
	v_cmp_le_u32_e32 vcc, v38, v31
	s_waitcnt vmcnt(2)
	v_fmac_f32_e32 v79, v74, v78
	v_cndmask_b32_e32 v19, 0, v82, vcc
	v_cvt_pk_bf16_f32 v36, v19, v18
	v_cvt_pk_bf16_f32 v18, v84, v85
	v_cmp_le_u32_e32 vcc, v86, v31
	v_or_b32_e32 v82, s4, v81
	s_nop 0
	v_cndmask_b32_e32 v19, 0, v18, vcc
	v_lshrrev_b32_e32 v18, 16, v18
	v_cmp_le_u32_e32 vcc, v87, v31
	s_nop 1
	v_cndmask_b32_e32 v18, 0, v18, vcc
	v_cmp_gt_u32_e32 vcc, v31, v40
	v_perm_b32 v37, v18, v19, s19
	s_nop 0
	v_cndmask_b32_e32 v18, 0, v45, vcc
	v_cmp_le_u32_e32 vcc, v40, v31
	s_nop 1
	v_cndmask_b32_e32 v19, 0, v44, vcc
	v_cvt_pk_bf16_f32 v38, v19, v18
	v_cvt_pk_bf16_f32 v18, v46, v47
	v_cmp_le_u32_e32 vcc, v88, v31
	s_nop 1
	v_cndmask_b32_e32 v19, 0, v18, vcc
	v_lshrrev_b32_e32 v18, 16, v18
	v_cmp_le_u32_e32 vcc, v89, v31
	s_nop 1
	v_cndmask_b32_e32 v18, 0, v18, vcc
	v_cmp_gt_u32_e32 vcc, v31, v41
	v_perm_b32 v39, v18, v19, s19
	ds_write_b128 v0, v[36:39] offset:32
	v_cndmask_b32_e32 v18, 0, v25, vcc
	v_cmp_le_u32_e32 vcc, v41, v31
	v_mul_u32_u24_e32 v41, 0x110, v52
	v_add3_u32 v41, s15, v41, v33
	v_cndmask_b32_e32 v19, 0, v24, vcc
	v_cvt_pk_bf16_f32 v18, v19, v18
	v_cvt_pk_bf16_f32 v19, v26, v27
	global_load_dwordx4 v[24:27], v[6:7], off offset:176
	global_load_dwordx4 v[36:39], v[6:7], off offset:160
	v_cmp_le_u32_e32 vcc, v91, v31
	s_nop 1
	v_cndmask_b32_e32 v40, 0, v19, vcc
	v_lshrrev_b32_e32 v19, 16, v19
	v_cmp_le_u32_e32 vcc, v94, v31
	s_nop 1
	v_cndmask_b32_e32 v19, 0, v19, vcc
	v_cmp_gt_u32_e32 vcc, v31, v42
	v_perm_b32 v19, v19, v40, s19
	v_cvt_pk_bf16_f32 v40, v54, s0
	v_cndmask_b32_e32 v21, 0, v21, vcc
	v_cmp_le_u32_e32 vcc, v42, v31
	ds_write_b16 v41, v40 offset:34816
	v_mul_u32_u24_e32 v41, 0x110, v55
	v_cndmask_b32_e32 v20, 0, v20, vcc
	v_cvt_pk_bf16_f32 v20, v20, v21
	v_cvt_pk_bf16_f32 v21, v22, v23
	v_cmp_le_u32_e32 vcc, v98, v31
	v_cvt_pk_bf16_f32 v40, v72, s0
	v_add3_u32 v41, s15, v41, v33
	v_cndmask_b32_e32 v22, 0, v21, vcc
	v_lshrrev_b32_e32 v21, 16, v21
	v_cmp_le_u32_e32 vcc, v101, v31
	ds_write_b16 v41, v40 offset:34816
	v_mul_u32_u24_e32 v23, 0x110, v77
	v_cndmask_b32_e32 v21, 0, v21, vcc
	v_perm_b32 v21, v21, v22, s19
	ds_write_b128 v0, v[18:21] offset:48
	v_mul_u32_u24_e32 v19, 0x110, v59
	v_cvt_pk_bf16_f32 v18, v76, s0
	v_add3_u32 v19, s15, v19, v33
	v_cmp_gt_u32_e32 vcc, v31, v43
	ds_write_b16 v19, v18 offset:34816
	v_cvt_pk_bf16_f32 v22, v79, s0
	v_add3_u32 v23, s15, v23, v33
	s_waitcnt vmcnt(2)
	v_cndmask_b32_e32 v15, 0, v15, vcc
	v_cmp_le_u32_e32 vcc, v43, v31
	global_load_dwordx4 v[18:21], v[6:7], off offset:208
	global_load_dwordx4 v[44:47], v[6:7], off offset:192
	ds_write_b16 v23, v22 offset:34816
	v_cndmask_b32_e32 v14, 0, v14, vcc
	v_or_b32_e32 v23, 50, v34
	v_cvt_pk_bf16_f32 v14, v14, v15
	v_cvt_pk_bf16_f32 v15, v16, v17
	v_or_b32_e32 v22, 51, v34
	v_lshlrev_b32_e32 v17, 2, v23
	v_cmp_le_u32_e32 vcc, v56, v31
	global_load_dword v40, v17, s[16:17]
	global_load_dword v41, v17, s[20:21]
	v_lshlrev_b32_e32 v17, 2, v22
	v_cndmask_b32_e32 v16, 0, v15, vcc
	v_lshrrev_b32_e32 v15, 16, v15
	global_load_dword v42, v17, s[16:17]
	global_load_dword v43, v17, s[20:21]
	v_cmp_le_u32_e32 vcc, v58, v31
	s_waitcnt vmcnt(2)
	v_fmac_f32_e32 v41, v40, v62
	v_cndmask_b32_e32 v15, 0, v15, vcc
	v_cmp_gt_u32_e32 vcc, v31, v48
	v_perm_b32 v15, v15, v16, s19
	s_waitcnt vmcnt(0)
	v_fmac_f32_e32 v43, v42, v61
	v_cndmask_b32_e32 v11, 0, v11, vcc
	v_cmp_le_u32_e32 vcc, v48, v31
	v_or_b32_e32 v48, 54, v34
	s_nop 0
	v_cndmask_b32_e32 v10, 0, v10, vcc
	v_cvt_pk_bf16_f32 v16, v10, v11
	v_cvt_pk_bf16_f32 v10, v12, v13
	v_cmp_le_u32_e32 vcc, v35, v31
	v_or_b32_e32 v35, 55, v34
	s_nop 0
	v_cndmask_b32_e32 v11, 0, v10, vcc
	v_lshrrev_b32_e32 v10, 16, v10
	v_cmp_le_u32_e32 vcc, v68, v31
	s_nop 1
	v_cndmask_b32_e32 v10, 0, v10, vcc
	v_perm_b32 v17, v10, v11, s19
	v_lshlrev_b32_e32 v10, 2, v48
	global_load_dword v53, v10, s[16:17]
	global_load_dword v54, v10, s[20:21]
	v_lshlrev_b32_e32 v10, 2, v35
	global_load_dword v56, v10, s[16:17]
	global_load_dword v58, v10, s[20:21]
	v_cmp_gt_u32_e32 vcc, v31, v49
	ds_write_b128 v0, v[14:17] offset:64
	s_waitcnt vmcnt(2)
	v_fmac_f32_e32 v54, v9, v53
	v_cndmask_b32_e32 v10, 0, v37, vcc
	v_cmp_le_u32_e32 vcc, v49, v31
	v_or_b32_e32 v49, 59, v34
	v_cvt_pk_bf16_f32 v9, v54, s0
	v_cndmask_b32_e32 v11, 0, v36, vcc
	v_cvt_pk_bf16_f32 v10, v11, v10
	v_cvt_pk_bf16_f32 v11, v38, v39
	v_cmp_le_u32_e32 vcc, v52, v31
	global_load_dwordx4 v[14:17], v[6:7], off offset:240
	global_load_dwordx4 v[36:39], v[6:7], off offset:224
	v_cndmask_b32_e32 v12, 0, v11, vcc
	v_lshrrev_b32_e32 v11, 16, v11
	v_cmp_le_u32_e32 vcc, v55, v31
	v_or_b32_e32 v52, 58, v34
	s_waitcnt vmcnt(2)
	v_fmac_f32_e32 v58, v8, v56
	v_cndmask_b32_e32 v6, 0, v11, vcc
	v_perm_b32 v11, v6, v12, s19
	v_lshlrev_b32_e32 v6, 2, v52
	global_load_dword v55, v6, s[16:17]
	global_load_dword v63, v6, s[20:21]
	v_lshlrev_b32_e32 v6, 2, v49
	v_cmp_gt_u32_e32 vcc, v31, v51
	global_load_dword v64, v6, s[16:17]
	global_load_dword v65, v6, s[20:21]
	v_cndmask_b32_e32 v6, 0, v25, vcc
	v_cmp_le_u32_e32 vcc, v51, v31
	s_waitcnt vmcnt(2)
	v_fmac_f32_e32 v63, v55, v2
	v_cndmask_b32_e32 v7, 0, v24, vcc
	v_cvt_pk_bf16_f32 v12, v7, v6
	v_cvt_pk_bf16_f32 v6, v26, v27
	v_cmp_le_u32_e32 vcc, v59, v31
	v_mul_u32_u24_e32 v26, 0x110, v22
	v_cvt_pk_bf16_f32 v27, v41, s0
	v_cndmask_b32_e32 v7, 0, v6, vcc
	v_lshrrev_b32_e32 v6, 16, v6
	v_cmp_le_u32_e32 vcc, v77, v31
	v_add3_u32 v26, s15, v26, v33
	v_cvt_pk_bf16_f32 v2, v63, s0
	v_cndmask_b32_e32 v6, 0, v6, vcc
	v_perm_b32 v13, v6, v7, s19
	ds_write_b128 v0, v[10:13] offset:80
	v_or_b32_e32 v11, 62, v34
	v_or_b32_e32 v10, 63, v34
	v_lshlrev_b32_e32 v7, 2, v11
	global_load_dword v12, v7, s[16:17]
	global_load_dword v13, v7, s[20:21]
	v_lshlrev_b32_e32 v7, 2, v10
	global_load_dword v24, v7, s[16:17]
	global_load_dword v25, v7, s[20:21]
	v_cmp_gt_u32_e32 vcc, v31, v57
	s_waitcnt vmcnt(4)
	v_fmac_f32_e32 v65, v64, v3
	s_waitcnt vmcnt(2)
	v_fmac_f32_e32 v13, v5, v12
	v_cndmask_b32_e32 v6, 0, v45, vcc
	v_cmp_le_u32_e32 vcc, v57, v31
	v_cvt_pk_bf16_f32 v5, v13, s0
	s_waitcnt vmcnt(0)
	v_fmac_f32_e32 v25, v4, v24
	v_cndmask_b32_e32 v7, 0, v44, vcc
	v_cvt_pk_bf16_f32 v6, v7, v6
	v_mul_u32_u24_e32 v7, 0x110, v23
	v_add3_u32 v7, s15, v7, v33
	ds_write_b16 v7, v27 offset:34816
	v_cvt_pk_bf16_f32 v7, v43, s0
	ds_write_b16 v26, v7 offset:34816
	v_cvt_pk_bf16_f32 v7, v46, v47
	v_cmp_le_u32_e32 vcc, v23, v31
	s_nop 1
	v_cndmask_b32_e32 v23, 0, v7, vcc
	v_lshrrev_b32_e32 v7, 16, v7
	v_cmp_le_u32_e32 vcc, v22, v31
	s_nop 1
	v_cndmask_b32_e32 v7, 0, v7, vcc
	v_perm_b32 v7, v7, v23, s19
	v_cmp_gt_u32_e32 vcc, v31, v60
	ds_write_b64 v0, v[6:7] offset:96
	s_nop 0
	v_cndmask_b32_e32 v6, 0, v19, vcc
	v_cmp_le_u32_e32 vcc, v60, v31
	s_nop 1
	v_cndmask_b32_e32 v7, 0, v18, vcc
	v_cvt_pk_bf16_f32 v6, v7, v6
	v_mul_u32_u24_e32 v7, 0x110, v48
	v_add3_u32 v7, s15, v7, v33
	v_mul_u32_u24_e32 v18, 0x110, v35
	v_add3_u32 v18, s15, v18, v33
	ds_write_b16 v7, v9 offset:34816
	v_cvt_pk_bf16_f32 v7, v58, s0
	ds_write_b16 v18, v7 offset:34816
	v_cvt_pk_bf16_f32 v7, v20, v21
	v_cmp_le_u32_e32 vcc, v48, v31
	s_nop 1
	v_cndmask_b32_e32 v8, 0, v7, vcc
	v_lshrrev_b32_e32 v7, 16, v7
	v_cmp_le_u32_e32 vcc, v35, v31
	s_nop 1
	v_cndmask_b32_e32 v7, 0, v7, vcc
	v_perm_b32 v7, v7, v8, s19
	v_cmp_gt_u32_e32 vcc, v31, v29
	ds_write_b64 v0, v[6:7] offset:104
	v_mul_u32_u24_e32 v8, 0x110, v49
	v_cndmask_b32_e32 v6, 0, v37, vcc
	v_cmp_le_u32_e32 vcc, v29, v31
	v_add3_u32 v8, s15, v8, v33
	s_nop 0
	v_cndmask_b32_e32 v7, 0, v36, vcc
	v_cvt_pk_bf16_f32 v6, v7, v6
	v_mul_u32_u24_e32 v7, 0x110, v52
	v_add3_u32 v7, s15, v7, v33
	ds_write_b16 v7, v2 offset:34816
	v_cvt_pk_bf16_f32 v2, v65, s0
	ds_write_b16 v8, v2 offset:34816
	v_cvt_pk_bf16_f32 v2, v38, v39
	v_cmp_le_u32_e32 vcc, v52, v31
	s_nop 1
	v_cndmask_b32_e32 v3, 0, v2, vcc
	v_lshrrev_b32_e32 v2, 16, v2
	v_cmp_le_u32_e32 vcc, v49, v31
	s_nop 1
	v_cndmask_b32_e32 v2, 0, v2, vcc
	v_cmp_gt_u32_e32 vcc, v31, v28
	v_perm_b32 v7, v2, v3, s19
	ds_write_b64 v0, v[6:7] offset:112
	v_cndmask_b32_e32 v2, 0, v15, vcc
	v_cmp_le_u32_e32 vcc, v28, v31
	v_mul_u32_u24_e32 v6, 0x110, v10
	v_add3_u32 v6, s15, v6, v33
	v_cndmask_b32_e32 v3, 0, v14, vcc
	v_cvt_pk_bf16_f32 v2, v3, v2
	v_mul_u32_u24_e32 v3, 0x110, v11
	v_add3_u32 v3, s15, v3, v33
	ds_write_b16 v3, v5 offset:34816
	v_cvt_pk_bf16_f32 v3, v25, s0
	ds_write_b16 v6, v3 offset:34816
	v_cvt_pk_bf16_f32 v3, v16, v17
	v_cmp_le_u32_e32 vcc, v11, v31
	v_mul_u32_u24_e32 v7, 0x88, v81
	v_lshlrev_b32_e32 v81, 2, v81
	v_cndmask_b32_e32 v4, 0, v3, vcc
	v_lshrrev_b32_e32 v3, 16, v3
	v_cmp_le_u32_e32 vcc, v10, v31
	s_nop 1
	v_cndmask_b32_e32 v3, 0, v3, vcc
	v_perm_b32 v3, v3, v4, s19
	ds_write_b64 v0, v[2:3] offset:120
	v_bfe_u32 v0, v50, 4, 2
	v_and_b32_e32 v2, 0x4f, v50
	v_lshl_add_u32 v6, v0, 4, s15
	v_mul_u32_u24_e32 v2, 0x88, v2
	v_lshl_add_u32 v51, v2, 1, v6
	s_waitcnt lgkmcnt(0)
	s_barrier
	ds_read_b128 v[2:5], v51 offset:34816
	ds_read_b128 v[72:75], v51 offset:34880
	ds_read_b128 v[14:17], v51 offset:39168
	ds_read_b128 v[76:79], v51 offset:39232
	ds_read_b128 v[22:25], v51 offset:43520
	ds_read_b128 v[84:87], v51 offset:43584
	ds_read_b128 v[30:33], v51 offset:47872
	ds_read_b128 v[88:91], v51 offset:47936
	v_lshl_add_u32 v83, v7, 1, v6
	ds_read_b128 v[6:9], v83
	ds_read_b128 v[34:37], v83 offset:4352
	ds_read_b128 v[52:55], v83 offset:8704
	ds_read_b128 v[68:71], v83 offset:13056
	s_waitcnt lgkmcnt(3)
	v_mfma_f32_16x16x32_bf16 v[10:13], v[2:5], v[6:9], 0
	ds_read_b128 v[100:103], v51 offset:48000
	v_and_b32_e32 v50, 64, v50
	v_mfma_f32_16x16x32_bf16 v[18:21], v[14:17], v[6:9], 0
	v_mfma_f32_16x16x32_bf16 v[26:29], v[22:25], v[6:9], 0
	v_mfma_f32_16x16x32_bf16 v[6:9], v[30:33], v[6:9], 0
	s_waitcnt lgkmcnt(3)
	v_mfma_f32_16x16x32_bf16 v[38:41], v[2:5], v[34:37], 0
	v_mfma_f32_16x16x32_bf16 v[42:45], v[14:17], v[34:37], 0
	v_mfma_f32_16x16x32_bf16 v[46:49], v[22:25], v[34:37], 0
	v_mfma_f32_16x16x32_bf16 v[34:37], v[30:33], v[34:37], 0
	s_waitcnt lgkmcnt(2)
	v_mfma_f32_16x16x32_bf16 v[56:59], v[2:5], v[52:55], 0
	v_mfma_f32_16x16x32_bf16 v[60:63], v[14:17], v[52:55], 0
	v_mfma_f32_16x16x32_bf16 v[64:67], v[22:25], v[52:55], 0
	v_mfma_f32_16x16x32_bf16 v[52:55], v[30:33], v[52:55], 0
	s_waitcnt lgkmcnt(1)
	v_mfma_f32_16x16x32_bf16 v[2:5], v[2:5], v[68:71], 0
	v_mfma_f32_16x16x32_bf16 v[14:17], v[14:17], v[68:71], 0
	v_mfma_f32_16x16x32_bf16 v[22:25], v[22:25], v[68:71], 0
	v_mfma_f32_16x16x32_bf16 v[30:33], v[30:33], v[68:71], 0
	ds_read_b128 v[68:71], v83 offset:64
	s_waitcnt lgkmcnt(0)
	v_mfma_f32_16x16x32_bf16 v[10:13], v[72:75], v[68:71], v[10:13]
	v_mfma_f32_16x16x32_bf16 v[18:21], v[76:79], v[68:71], v[18:21]
	v_mfma_f32_16x16x32_bf16 v[26:29], v[84:87], v[68:71], v[26:29]
	v_mfma_f32_16x16x32_bf16 v[6:9], v[88:91], v[68:71], v[6:9]
	ds_read_b128 v[68:71], v83 offset:4416
	s_waitcnt lgkmcnt(0)
	v_mfma_f32_16x16x32_bf16 v[38:41], v[72:75], v[68:71], v[38:41]
	v_mfma_f32_16x16x32_bf16 v[42:45], v[76:79], v[68:71], v[42:45]
	v_mfma_f32_16x16x32_bf16 v[46:49], v[84:87], v[68:71], v[46:49]
	v_mfma_f32_16x16x32_bf16 v[34:37], v[88:91], v[68:71], v[34:37]
	ds_read_b128 v[68:71], v83 offset:8768
	s_waitcnt lgkmcnt(0)
	v_mfma_f32_16x16x32_bf16 v[92:95], v[76:79], v[68:71], v[60:63]
	s_nop 2
	ds_read_b128 v[60:63], v83 offset:13120
	v_mfma_f32_16x16x32_bf16 v[56:59], v[72:75], v[68:71], v[56:59]
	v_mfma_f32_16x16x32_bf16 v[96:99], v[84:87], v[68:71], v[64:67]
	v_mfma_f32_16x16x32_bf16 v[52:55], v[88:91], v[68:71], v[52:55]
	s_nop 1
	ds_read_b128 v[66:69], v51 offset:34944
	s_waitcnt lgkmcnt(1)
	v_mfma_f32_16x16x32_bf16 v[2:5], v[72:75], v[60:63], v[2:5]
	v_mfma_f32_16x16x32_bf16 v[70:73], v[88:91], v[60:63], v[30:33]
	s_nop 2
	ds_read_b128 v[30:33], v83 offset:128
	v_mfma_f32_16x16x32_bf16 v[14:17], v[76:79], v[60:63], v[14:17]
	s_waitcnt lgkmcnt(0)
	v_mfma_f32_16x16x32_bf16 v[74:77], v[66:69], v[30:33], v[10:13]
	s_nop 2
	ds_read_b128 v[10:13], v51 offset:39296
	v_mfma_f32_16x16x32_bf16 v[22:25], v[84:87], v[60:63], v[22:25]
	v_mfma_f32_16x16x32_bf16 v[104:107], v[100:103], v[30:33], v[6:9]
	s_nop 2
	ds_read_b128 v[6:9], v83 offset:4480
	s_waitcnt lgkmcnt(1)
	v_mfma_f32_16x16x32_bf16 v[84:87], v[10:13], v[30:33], v[18:21]
	s_nop 2
	ds_read_b128 v[18:21], v51 offset:43648
	s_waitcnt lgkmcnt(1)
	v_mfma_f32_16x16x32_bf16 v[108:111], v[66:69], v[6:9], v[38:41]
	v_mfma_f32_16x16x32_bf16 v[112:115], v[10:13], v[6:9], v[42:45]
	s_waitcnt lgkmcnt(0)
	v_mfma_f32_16x16x32_bf16 v[116:119], v[18:21], v[6:9], v[46:49]
	v_mfma_f32_16x16x32_bf16 v[62:65], v[100:103], v[6:9], v[34:37]
	ds_read_b128 v[6:9], v83 offset:8832
	s_waitcnt lgkmcnt(0)
	v_mfma_f32_16x16x32_bf16 v[42:45], v[100:103], v[6:9], v[52:55]
	s_nop 2
	ds_read_b128 v[52:55], v83 offset:13184
	v_mfma_f32_16x16x32_bf16 v[88:91], v[18:21], v[30:33], v[26:29]
	ds_read_b128 v[30:33], v51 offset:35008
	v_mfma_f32_16x16x32_bf16 v[46:49], v[18:21], v[6:9], v[96:99]
	s_waitcnt lgkmcnt(1)
	v_mfma_f32_16x16x32_bf16 v[26:29], v[66:69], v[52:55], v[2:5]
	v_mfma_f32_16x16x32_bf16 v[2:5], v[18:21], v[52:55], v[22:25]
	ds_read_b128 v[18:21], v51 offset:39360
	v_mfma_f32_16x16x32_bf16 v[38:41], v[66:69], v[6:9], v[56:59]
	v_mfma_f32_16x16x32_bf16 v[34:37], v[10:13], v[6:9], v[92:95]
	v_mfma_f32_16x16x32_bf16 v[6:9], v[10:13], v[52:55], v[14:17]
	v_mfma_f32_16x16x32_bf16 v[10:13], v[100:103], v[52:55], v[70:73]
	ds_read_b128 v[52:55], v83 offset:192
	ds_read_b128 v[22:25], v51 offset:43712
	ds_read_b128 v[14:17], v51 offset:48064
	v_lshlrev_b32_e32 v70, 3, v0
	v_lshlrev_b32_e32 v0, 1, v50
	v_lshl_add_u64 v[50:51], s[6:7], 0, v[0:1]
	v_mov_b32_e32 v71, v1
	s_waitcnt lgkmcnt(2)
	v_mfma_f32_16x16x32_bf16 v[92:95], v[30:33], v[52:55], v[74:77]
	ds_read_b128 v[100:103], v83 offset:4544
	s_nop 1
	v_lshl_add_u64 v[74:75], v[50:51], 0, v[70:71]
	v_mad_u64_u32 v[72:73], s[0:1], v82, s3, v[74:75]
	v_mfma_f32_16x16x32_bf16 v[96:99], v[18:21], v[52:55], v[84:87]
	s_lshl_b64 s[0:1], s[88:89], 2
	s_add_u32 s12, s42, s0
	s_addc_u32 s13, s43, s1
	s_waitcnt lgkmcnt(2)
	v_mfma_f32_16x16x32_bf16 v[86:89], v[22:25], v[52:55], v[88:91]
	global_load_dword v85, v81, s[12:13]
	v_or_b32_e32 v84, 16, v82
	v_mad_u64_u32 v[78:79], s[0:1], v84, s3, v[74:75]
	global_load_dwordx2 v[90:91], v[72:73], off
	s_waitcnt lgkmcnt(1)
	v_mfma_f32_16x16x32_bf16 v[66:69], v[14:17], v[52:55], v[104:107]
	s_cmpk_gt_u32 s10, 0xff
	s_waitcnt vmcnt(1)
	v_add_f32_e32 v87, v87, v85
	global_load_dwordx2 v[104:105], v[72:73], off offset:32
	s_waitcnt lgkmcnt(0)
	v_mfma_f32_16x16x32_bf16 v[58:61], v[30:33], v[100:103], v[108:111]
	global_load_dwordx2 v[106:107], v[72:73], off offset:64
	s_nop 1
	global_load_dwordx2 v[108:109], v[72:73], off offset:96
	s_waitcnt vmcnt(3)
	v_lshlrev_b32_e32 v72, 16, v90
	v_mul_f32_e32 v73, v72, v72
	v_and_b32_e32 v90, 0xffff0000, v90
	v_fmamk_f32 v73, v73, 0xbdd2d3e7, v129
	v_mul_f32_e32 v76, v90, v90
	v_mul_f32_e32 v73, v73, v72
	v_fmamk_f32 v76, v76, 0xbdd2d3e7, v129
	v_mul_f32_e32 v76, v76, v90
	v_exp_f32_e32 v73, v73
	v_exp_f32_e32 v110, v76
	v_add_f32_e32 v86, v86, v85
	v_add_f32_e32 v73, 1.0, v73
	v_rcp_f32_e32 v73, v73
	v_add_f32_e32 v110, 1.0, v110
	v_rcp_f32_e32 v110, v110
	v_add_f32_e32 v88, v88, v85
	v_mul_f32_e32 v72, v73, v72
	v_add_f32_e32 v73, v92, v85
	v_mul_f32_e32 v72, v72, v73
	v_mul_f32_e32 v73, v110, v90
	v_add_f32_e32 v90, v93, v85
	v_lshlrev_b32_e32 v92, 16, v91
	v_mul_f32_e32 v73, v73, v90
	v_mul_f32_e32 v90, v92, v92
	v_and_b32_e32 v91, 0xffff0000, v91
	v_fmamk_f32 v90, v90, 0xbdd2d3e7, v129
	v_mul_f32_e32 v93, v91, v91
	v_mul_f32_e32 v90, v90, v92
	v_fmamk_f32 v93, v93, 0xbdd2d3e7, v129
	v_mul_f32_e32 v93, v93, v91
	v_exp_f32_e32 v90, v90
	v_exp_f32_e32 v93, v93
	v_add_f32_e32 v89, v89, v85
	v_add_f32_e32 v90, 1.0, v90
	v_rcp_f32_e32 v110, v90
	v_cvt_pk_bf16_f32 v90, v72, v73
	v_add_f32_e32 v72, 1.0, v93
	v_rcp_f32_e32 v72, v72
	v_mul_f32_e32 v73, v110, v92
	v_add_f32_e32 v92, v94, v85
	v_mul_f32_e32 v73, v73, v92
	v_mul_f32_e32 v72, v72, v91
	v_add_f32_e32 v91, v95, v85
	v_mul_f32_e32 v72, v72, v91
	v_cvt_pk_bf16_f32 v91, v73, v72
	v_mov_b64_e32 v[72:73], s[50:51]
	v_mad_u64_u32 v[92:93], s[0:1], v82, s3, v[72:73]
	v_lshl_add_u64 v[92:93], v[92:93], 0, s[8:9]
	v_lshl_add_u64 v[92:93], v[92:93], 0, v[0:1]
	v_lshl_add_u64 v[92:93], v[92:93], 0, v[70:71]
	global_store_dwordx2 v[92:93], v[90:91], off
	v_add_f32_e32 v67, v67, v85
	v_add_f32_e32 v66, v66, v85
	global_load_dwordx2 v[76:77], v[78:79], off
	v_add_f32_e32 v68, v68, v85
	v_add_f32_e32 v69, v69, v85
	v_mfma_f32_16x16x32_bf16 v[54:57], v[18:21], v[100:103], v[112:115]
	s_waitcnt vmcnt(4)
	v_lshlrev_b32_e32 v94, 16, v104
	v_mul_f32_e32 v95, v94, v94
	v_and_b32_e32 v104, 0xffff0000, v104
	v_fmamk_f32 v95, v95, 0xbdd2d3e7, v129
	v_mul_f32_e32 v110, v104, v104
	v_mul_f32_e32 v95, v95, v94
	v_fmamk_f32 v110, v110, 0xbdd2d3e7, v129
	v_mul_f32_e32 v110, v110, v104
	v_exp_f32_e32 v95, v95
	v_exp_f32_e32 v110, v110
	v_mfma_f32_16x16x32_bf16 v[50:53], v[22:25], v[100:103], v[116:119]
	v_add_f32_e32 v95, 1.0, v95
	v_rcp_f32_e32 v95, v95
	v_add_f32_e32 v90, 1.0, v110
	v_rcp_f32_e32 v90, v90
	v_mfma_f32_16x16x32_bf16 v[62:65], v[14:17], v[100:103], v[62:65]
	v_mul_f32_e32 v91, v95, v94
	v_add_f32_e32 v94, v96, v85
	v_mul_f32_e32 v91, v91, v94
	v_mul_f32_e32 v90, v90, v104
	v_add_f32_e32 v94, v97, v85
	v_mul_f32_e32 v90, v90, v94
	v_lshlrev_b32_e32 v94, 16, v105
	v_mul_f32_e32 v95, v94, v94
	v_and_b32_e32 v96, 0xffff0000, v105
	v_fmamk_f32 v95, v95, 0xbdd2d3e7, v129
	v_mul_f32_e32 v97, v96, v96
	v_mul_f32_e32 v95, v95, v94
	v_fmamk_f32 v97, v97, 0xbdd2d3e7, v129
	v_mul_f32_e32 v97, v97, v96
	v_exp_f32_e32 v95, v95
	v_exp_f32_e32 v97, v97
	v_cvt_pk_bf16_f32 v90, v91, v90
	v_add_f32_e32 v95, 1.0, v95
	v_rcp_f32_e32 v95, v95
	v_add_f32_e32 v91, 1.0, v97
	v_rcp_f32_e32 v91, v91
	v_mul_f32_e32 v94, v95, v94
	v_add_f32_e32 v95, v98, v85
	v_mul_f32_e32 v94, v94, v95
	v_mul_f32_e32 v91, v91, v96
	v_add_f32_e32 v95, v99, v85
	v_mul_f32_e32 v91, v91, v95
	s_waitcnt vmcnt(3)
	v_and_b32_e32 v96, 0xffff0000, v106
	v_cvt_pk_bf16_f32 v91, v94, v91
	v_lshlrev_b32_e32 v94, 16, v106
	v_mul_f32_e32 v97, v96, v96
	v_mul_f32_e32 v95, v94, v94
	v_fmamk_f32 v97, v97, 0xbdd2d3e7, v129
	v_fmamk_f32 v95, v95, 0xbdd2d3e7, v129
	v_mul_f32_e32 v97, v97, v96
	v_mul_f32_e32 v95, v95, v94
	v_exp_f32_e32 v97, v97
	v_exp_f32_e32 v95, v95
	global_store_dwordx2 v[92:93], v[90:91], off offset:32
	v_add_f32_e32 v90, 1.0, v97
	v_add_f32_e32 v95, 1.0, v95
	v_rcp_f32_e32 v90, v90
	v_rcp_f32_e32 v95, v95
	v_mul_f32_e32 v90, v90, v96
	v_mul_f32_e32 v91, v95, v94
	v_mul_f32_e32 v87, v90, v87
	v_lshlrev_b32_e32 v90, 16, v107
	v_and_b32_e32 v94, 0xffff0000, v107
	v_mul_f32_e32 v86, v91, v86
	v_mul_f32_e32 v91, v90, v90
	v_mul_f32_e32 v95, v94, v94
	v_fmamk_f32 v91, v91, 0xbdd2d3e7, v129
	v_fmamk_f32 v95, v95, 0xbdd2d3e7, v129
	v_mul_f32_e32 v91, v91, v90
	v_mul_f32_e32 v95, v95, v94
	v_exp_f32_e32 v91, v91
	v_exp_f32_e32 v95, v95
	v_cvt_pk_bf16_f32 v86, v86, v87
	v_add_f32_e32 v91, 1.0, v91
	v_add_f32_e32 v87, 1.0, v95
	v_rcp_f32_e32 v91, v91
	v_rcp_f32_e32 v87, v87
	v_mul_f32_e32 v90, v91, v90
	v_mul_f32_e32 v87, v87, v94
	v_mul_f32_e32 v88, v90, v88
	v_mul_f32_e32 v87, v87, v89
	s_waitcnt vmcnt(3)
	v_and_b32_e32 v90, 0xffff0000, v108
	v_cvt_pk_bf16_f32 v87, v88, v87
	v_lshlrev_b32_e32 v88, 16, v108
	v_mul_f32_e32 v91, v90, v90
	v_mul_f32_e32 v89, v88, v88
	v_fmamk_f32 v91, v91, 0xbdd2d3e7, v129
	v_fmamk_f32 v89, v89, 0xbdd2d3e7, v129
	v_mul_f32_e32 v91, v91, v90
	v_mul_f32_e32 v89, v89, v88
	v_exp_f32_e32 v91, v91
	v_exp_f32_e32 v89, v89
	global_store_dwordx2 v[92:93], v[86:87], off offset:64
	v_add_f32_e32 v86, 1.0, v91
	v_add_f32_e32 v89, 1.0, v89
	v_rcp_f32_e32 v86, v86
	v_rcp_f32_e32 v89, v89
	v_mul_f32_e32 v86, v86, v90
	v_mul_f32_e32 v87, v89, v88
	v_mul_f32_e32 v67, v86, v67
	v_lshlrev_b32_e32 v86, 16, v109
	v_and_b32_e32 v88, 0xffff0000, v109
	v_mul_f32_e32 v66, v87, v66
	v_mul_f32_e32 v87, v86, v86
	v_mul_f32_e32 v89, v88, v88
	v_fmamk_f32 v87, v87, 0xbdd2d3e7, v129
	v_fmamk_f32 v89, v89, 0xbdd2d3e7, v129
	v_mul_f32_e32 v87, v87, v86
	v_mul_f32_e32 v89, v89, v88
	v_exp_f32_e32 v87, v87
	v_exp_f32_e32 v89, v89
	v_cvt_pk_bf16_f32 v66, v66, v67
	global_load_dwordx2 v[90:91], v[78:79], off offset:32
	v_add_f32_e32 v87, 1.0, v87
	v_add_f32_e32 v67, 1.0, v89
	v_rcp_f32_e32 v87, v87
	v_rcp_f32_e32 v67, v67
	v_mul_f32_e32 v86, v87, v86
	v_mul_f32_e32 v67, v67, v88
	v_mul_f32_e32 v68, v68, v86
	v_mul_f32_e32 v67, v69, v67
	v_cvt_pk_bf16_f32 v67, v68, v67
	global_store_dwordx2 v[92:93], v[66:67], off offset:96
	global_load_dword v85, v81, s[12:13] offset:64
	ds_read_b128 v[86:89], v83 offset:8896
	global_load_dwordx2 v[92:93], v[78:79], off offset:64
	global_load_dwordx2 v[94:95], v[78:79], off offset:96
	s_waitcnt vmcnt(7)
	v_lshlrev_b32_e32 v79, 16, v76
	v_and_b32_e32 v76, 0xffff0000, v76
	v_mul_f32_e32 v67, v76, v76
	v_mul_f32_e32 v66, v79, v79
	v_fmamk_f32 v67, v67, 0xbdd2d3e7, v129
	v_fmamk_f32 v66, v66, 0xbdd2d3e7, v129
	v_mul_f32_e32 v67, v67, v76
	v_mul_f32_e32 v66, v66, v79
	v_exp_f32_e32 v96, v67
	v_exp_f32_e32 v66, v66
	v_or_b32_e32 v78, 32, v82
	v_mad_u64_u32 v[68:69], s[0:1], v78, s3, v[74:75]
	v_add_f32_e32 v96, 1.0, v96
	v_add_f32_e32 v66, 1.0, v66
	v_rcp_f32_e32 v96, v96
	v_rcp_f32_e32 v97, v66
	global_load_dwordx2 v[66:67], v[68:69], off
	s_waitcnt lgkmcnt(0)
	v_mfma_f32_16x16x32_bf16 v[38:41], v[30:33], v[86:89], v[38:41]
	v_mul_f32_e32 v76, v96, v76
	v_mul_f32_e32 v79, v97, v79
	s_waitcnt vmcnt(3)
	v_add_f32_e32 v59, v59, v85
	v_add_f32_e32 v58, v58, v85
	v_mul_f32_e32 v59, v76, v59
	v_lshlrev_b32_e32 v76, 16, v77
	v_and_b32_e32 v77, 0xffff0000, v77
	v_mul_f32_e32 v58, v79, v58
	v_mul_f32_e32 v79, v76, v76
	v_mul_f32_e32 v96, v77, v77
	v_fmamk_f32 v79, v79, 0xbdd2d3e7, v129
	v_fmamk_f32 v96, v96, 0xbdd2d3e7, v129
	v_mul_f32_e32 v79, v79, v76
	v_mul_f32_e32 v96, v96, v77
	v_exp_f32_e32 v79, v79
	v_exp_f32_e32 v96, v96
	v_cvt_pk_bf16_f32 v58, v58, v59
	v_add_f32_e32 v60, v60, v85
	v_add_f32_e32 v79, 1.0, v79
	v_add_f32_e32 v59, 1.0, v96
	v_rcp_f32_e32 v79, v79
	v_rcp_f32_e32 v59, v59
	v_add_f32_e32 v61, v61, v85
	v_add_f32_e32 v55, v55, v85
	v_mul_f32_e32 v76, v79, v76
	v_mul_f32_e32 v59, v59, v77
	v_mul_f32_e32 v60, v76, v60
	v_mul_f32_e32 v59, v59, v61
	v_and_b32_e32 v79, 0xffff0000, v90
	v_cvt_pk_bf16_f32 v59, v60, v59
	v_mad_u64_u32 v[60:61], s[0:1], v84, s3, v[72:73]
	v_lshlrev_b32_e32 v76, 16, v90
	v_mul_f32_e32 v84, v79, v79
	v_mul_f32_e32 v77, v76, v76
	v_fmamk_f32 v84, v84, 0xbdd2d3e7, v129
	v_fmamk_f32 v77, v77, 0xbdd2d3e7, v129
	v_mul_f32_e32 v84, v84, v79
	v_mul_f32_e32 v77, v77, v76
	v_exp_f32_e32 v84, v84
	v_lshl_add_u64 v[60:61], v[60:61], 0, s[8:9]
	v_exp_f32_e32 v77, v77
	v_lshl_add_u64 v[60:61], v[60:61], 0, v[0:1]
	v_lshl_add_u64 v[60:61], v[60:61], 0, v[70:71]
	global_store_dwordx2 v[60:61], v[58:59], off
	v_add_f32_e32 v58, 1.0, v84
	v_add_f32_e32 v77, 1.0, v77
	v_rcp_f32_e32 v58, v58
	v_rcp_f32_e32 v77, v77
	v_add_f32_e32 v54, v54, v85
	v_add_f32_e32 v56, v56, v85
	v_mul_f32_e32 v58, v58, v79
	v_mul_f32_e32 v59, v77, v76
	v_mul_f32_e32 v55, v58, v55
	v_lshlrev_b32_e32 v58, 16, v91
	v_and_b32_e32 v76, 0xffff0000, v91
	v_mul_f32_e32 v54, v59, v54
	v_mul_f32_e32 v59, v58, v58
	v_mul_f32_e32 v77, v76, v76
	v_fmamk_f32 v59, v59, 0xbdd2d3e7, v129
	v_fmamk_f32 v77, v77, 0xbdd2d3e7, v129
	v_mul_f32_e32 v59, v59, v58
	v_mul_f32_e32 v77, v77, v76
	v_exp_f32_e32 v59, v59
	v_exp_f32_e32 v77, v77
	v_cvt_pk_bf16_f32 v54, v54, v55
	v_add_f32_e32 v57, v57, v85
	v_add_f32_e32 v59, 1.0, v59
	v_add_f32_e32 v55, 1.0, v77
	v_rcp_f32_e32 v59, v59
	v_rcp_f32_e32 v55, v55
	v_add_f32_e32 v51, v51, v85
	v_add_f32_e32 v50, v50, v85
	v_mul_f32_e32 v58, v59, v58
	v_mul_f32_e32 v55, v55, v76
	v_mul_f32_e32 v56, v58, v56
	v_mul_f32_e32 v55, v55, v57
	s_waitcnt vmcnt(3)
	v_and_b32_e32 v58, 0xffff0000, v92
	v_cvt_pk_bf16_f32 v55, v56, v55
	v_lshlrev_b32_e32 v56, 16, v92
	v_mul_f32_e32 v59, v58, v58
	v_mul_f32_e32 v57, v56, v56
	v_fmamk_f32 v59, v59, 0xbdd2d3e7, v129
	v_fmamk_f32 v57, v57, 0xbdd2d3e7, v129
	v_mul_f32_e32 v59, v59, v58
	v_mul_f32_e32 v57, v57, v56
	v_exp_f32_e32 v59, v59
	v_exp_f32_e32 v57, v57
	global_store_dwordx2 v[60:61], v[54:55], off offset:32
	v_add_f32_e32 v52, v52, v85
	v_add_f32_e32 v54, 1.0, v59
	v_add_f32_e32 v57, 1.0, v57
	v_rcp_f32_e32 v54, v54
	v_rcp_f32_e32 v57, v57
	v_add_f32_e32 v53, v53, v85
	v_mfma_f32_16x16x32_bf16 v[34:37], v[18:21], v[86:89], v[34:37]
	v_mul_f32_e32 v54, v54, v58
	v_mul_f32_e32 v55, v57, v56
	v_mul_f32_e32 v51, v54, v51
	v_lshlrev_b32_e32 v54, 16, v93
	v_and_b32_e32 v56, 0xffff0000, v93
	v_mul_f32_e32 v50, v55, v50
	v_mul_f32_e32 v55, v54, v54
	v_mul_f32_e32 v57, v56, v56
	v_fmamk_f32 v55, v55, 0xbdd2d3e7, v129
	v_fmamk_f32 v57, v57, 0xbdd2d3e7, v129
	v_mul_f32_e32 v55, v55, v54
	v_mul_f32_e32 v57, v57, v56
	v_exp_f32_e32 v55, v55
	v_exp_f32_e32 v57, v57
	v_cvt_pk_bf16_f32 v50, v50, v51
	v_mfma_f32_16x16x32_bf16 v[46:49], v[22:25], v[86:89], v[46:49]
	v_add_f32_e32 v55, 1.0, v55
	v_add_f32_e32 v51, 1.0, v57
	v_rcp_f32_e32 v55, v55
	v_rcp_f32_e32 v51, v51
	v_mfma_f32_16x16x32_bf16 v[42:45], v[14:17], v[86:89], v[42:45]
	v_or_b32_e32 v57, 48, v82
	v_mul_f32_e32 v54, v55, v54
	v_mul_f32_e32 v51, v51, v56
	v_mul_f32_e32 v52, v54, v52
	v_mul_f32_e32 v51, v51, v53
	v_cvt_pk_bf16_f32 v51, v52, v51
	s_waitcnt vmcnt(3)
	v_lshlrev_b32_e32 v52, 16, v94
	v_mul_f32_e32 v53, v52, v52
	v_and_b32_e32 v54, 0xffff0000, v94
	v_fmamk_f32 v53, v53, 0xbdd2d3e7, v129
	v_mul_f32_e32 v55, v54, v54
	v_mul_f32_e32 v53, v53, v52
	v_fmamk_f32 v55, v55, 0xbdd2d3e7, v129
	v_mul_f32_e32 v55, v55, v54
	v_exp_f32_e32 v53, v53
	v_exp_f32_e32 v55, v55
	global_store_dwordx2 v[60:61], v[50:51], off offset:64
	v_add_f32_e32 v53, 1.0, v53
	v_rcp_f32_e32 v53, v53
	v_add_f32_e32 v50, 1.0, v55
	v_rcp_f32_e32 v50, v50
	v_mul_f32_e32 v51, v53, v52
	v_add_f32_e32 v52, v62, v85
	v_mul_f32_e32 v51, v51, v52
	v_mul_f32_e32 v50, v50, v54
	v_add_f32_e32 v52, v63, v85
	v_mul_f32_e32 v50, v50, v52
	v_lshlrev_b32_e32 v52, 16, v95
	v_mul_f32_e32 v53, v52, v52
	v_and_b32_e32 v54, 0xffff0000, v95
	v_fmamk_f32 v53, v53, 0xbdd2d3e7, v129
	v_mul_f32_e32 v55, v54, v54
	v_mul_f32_e32 v53, v53, v52
	v_fmamk_f32 v55, v55, 0xbdd2d3e7, v129
	v_mul_f32_e32 v55, v55, v54
	v_exp_f32_e32 v53, v53
	v_exp_f32_e32 v55, v55
	v_cvt_pk_bf16_f32 v50, v51, v50
	v_add_f32_e32 v53, 1.0, v53
	v_rcp_f32_e32 v53, v53
	v_add_f32_e32 v51, 1.0, v55
	v_rcp_f32_e32 v51, v51
	v_mul_f32_e32 v52, v53, v52
	v_add_f32_e32 v53, v64, v85
	v_mul_f32_e32 v52, v52, v53
	v_mul_f32_e32 v51, v51, v54
	v_add_f32_e32 v53, v65, v85
	v_mul_f32_e32 v51, v51, v53
	v_cvt_pk_bf16_f32 v51, v52, v51
	global_store_dwordx2 v[60:61], v[50:51], off offset:96
	global_load_dword v56, v81, s[12:13] offset:128
	global_load_dwordx2 v[54:55], v[68:69], off offset:32
	ds_read_b128 v[50:53], v83 offset:13248
	global_load_dwordx2 v[58:59], v[68:69], off offset:64
	global_load_dwordx2 v[60:61], v[68:69], off offset:96
	s_waitcnt vmcnt(8)
	v_lshlrev_b32_e32 v62, 16, v66
	s_waitcnt lgkmcnt(0)
	v_mfma_f32_16x16x32_bf16 v[26:29], v[30:33], v[50:53], v[26:29]
	v_mul_f32_e32 v30, v62, v62
	v_and_b32_e32 v63, 0xffff0000, v66
	v_fmamk_f32 v30, v30, 0xbdd2d3e7, v129
	v_mul_f32_e32 v31, v63, v63
	v_mul_f32_e32 v30, v30, v62
	v_fmamk_f32 v31, v31, 0xbdd2d3e7, v129
	v_mul_f32_e32 v31, v31, v63
	v_exp_f32_e32 v30, v30
	v_exp_f32_e32 v64, v31
	v_mad_u64_u32 v[32:33], s[0:1], v57, s3, v[74:75]
	v_add_f32_e32 v30, 1.0, v30
	v_rcp_f32_e32 v65, v30
	v_add_f32_e32 v64, 1.0, v64
	v_rcp_f32_e32 v64, v64
	global_load_dwordx2 v[30:31], v[32:33], off
	v_mul_f32_e32 v62, v65, v62
	v_mfma_f32_16x16x32_bf16 v[6:9], v[18:21], v[50:53], v[6:9]
	global_load_dwordx2 v[18:19], v[32:33], off offset:32
	s_waitcnt vmcnt(5)
	v_add_f32_e32 v38, v38, v56
	v_mul_f32_e32 v38, v62, v38
	v_mul_f32_e32 v62, v64, v63
	v_add_f32_e32 v39, v39, v56
	v_mul_f32_e32 v39, v62, v39
	v_lshlrev_b32_e32 v62, 16, v67
	v_mul_f32_e32 v63, v62, v62
	v_fmamk_f32 v63, v63, 0xbdd2d3e7, v129
	v_and_b32_e32 v64, 0xffff0000, v67
	v_mul_f32_e32 v63, v63, v62
	v_mul_f32_e32 v65, v64, v64
	v_fmamk_f32 v65, v65, 0xbdd2d3e7, v129
	v_mul_f32_e32 v65, v65, v64
	v_exp_f32_e32 v63, v63
	v_exp_f32_e32 v65, v65
	v_add_f32_e32 v63, 1.0, v63
	v_rcp_f32_e32 v63, v63
	v_cvt_pk_bf16_f32 v38, v38, v39
	v_add_f32_e32 v39, 1.0, v65
	v_rcp_f32_e32 v39, v39
	v_mul_f32_e32 v62, v63, v62
	v_add_f32_e32 v40, v40, v56
	v_mul_f32_e32 v40, v62, v40
	s_waitcnt vmcnt(4)
	v_lshlrev_b32_e32 v62, 16, v54
	v_and_b32_e32 v54, 0xffff0000, v54
	v_mul_f32_e32 v39, v39, v64
	v_mul_f32_e32 v64, v54, v54
	v_mul_f32_e32 v63, v62, v62
	v_fmamk_f32 v64, v64, 0xbdd2d3e7, v129
	v_fmamk_f32 v63, v63, 0xbdd2d3e7, v129
	v_mul_f32_e32 v64, v64, v54
	v_add_f32_e32 v41, v41, v56
	v_mul_f32_e32 v63, v63, v62
	v_mul_f32_e32 v39, v39, v41
	v_cvt_pk_bf16_f32 v39, v40, v39
	v_mad_u64_u32 v[40:41], s[0:1], v78, s3, v[72:73]
	v_exp_f32_e32 v64, v64
	v_lshl_add_u64 v[40:41], v[40:41], 0, s[8:9]
	v_exp_f32_e32 v63, v63
	v_lshl_add_u64 v[40:41], v[40:41], 0, v[0:1]
	v_lshl_add_u64 v[40:41], v[40:41], 0, v[70:71]
	global_store_dwordx2 v[40:41], v[38:39], off
	v_add_f32_e32 v38, 1.0, v64
	v_add_f32_e32 v63, 1.0, v63
	v_rcp_f32_e32 v38, v38
	v_rcp_f32_e32 v63, v63
	v_add_f32_e32 v35, v35, v56
	v_add_f32_e32 v34, v34, v56
	v_mul_f32_e32 v38, v38, v54
	v_mul_f32_e32 v39, v63, v62
	v_mul_f32_e32 v35, v38, v35
	v_lshlrev_b32_e32 v38, 16, v55
	v_and_b32_e32 v54, 0xffff0000, v55
	v_mul_f32_e32 v34, v39, v34
	v_mul_f32_e32 v39, v38, v38
	v_mul_f32_e32 v55, v54, v54
	v_fmamk_f32 v39, v39, 0xbdd2d3e7, v129
	v_fmamk_f32 v55, v55, 0xbdd2d3e7, v129
	v_mul_f32_e32 v39, v39, v38
	v_mul_f32_e32 v55, v55, v54
	v_exp_f32_e32 v39, v39
	v_exp_f32_e32 v55, v55
	v_cvt_pk_bf16_f32 v34, v34, v35
	v_add_f32_e32 v36, v36, v56
	v_add_f32_e32 v39, 1.0, v39
	v_add_f32_e32 v35, 1.0, v55
	v_rcp_f32_e32 v39, v39
	v_rcp_f32_e32 v35, v35
	v_add_f32_e32 v37, v37, v56
	v_mfma_f32_16x16x32_bf16 v[2:5], v[22:25], v[50:53], v[2:5]
	v_mul_f32_e32 v38, v39, v38
	v_mul_f32_e32 v35, v35, v54
	v_mul_f32_e32 v36, v38, v36
	v_mul_f32_e32 v35, v35, v37
	v_cvt_pk_bf16_f32 v35, v36, v35
	s_waitcnt vmcnt(4)
	v_lshlrev_b32_e32 v36, 16, v58
	v_mul_f32_e32 v37, v36, v36
	v_and_b32_e32 v38, 0xffff0000, v58
	v_fmamk_f32 v37, v37, 0xbdd2d3e7, v129
	v_mul_f32_e32 v39, v38, v38
	v_mul_f32_e32 v37, v37, v36
	v_fmamk_f32 v39, v39, 0xbdd2d3e7, v129
	v_mul_f32_e32 v39, v39, v38
	v_exp_f32_e32 v37, v37
	v_exp_f32_e32 v39, v39
	global_store_dwordx2 v[40:41], v[34:35], off offset:32
	v_add_f32_e32 v37, 1.0, v37
	v_rcp_f32_e32 v37, v37
	v_add_f32_e32 v34, 1.0, v39
	v_rcp_f32_e32 v34, v34
	s_waitcnt vmcnt(3)
	v_lshlrev_b32_e32 v24, 16, v30
	v_mul_f32_e32 v35, v37, v36
	v_add_f32_e32 v36, v46, v56
	v_mul_f32_e32 v35, v35, v36
	v_mul_f32_e32 v34, v34, v38
	v_add_f32_e32 v36, v47, v56
	v_mul_f32_e32 v34, v34, v36
	v_lshlrev_b32_e32 v36, 16, v59
	v_mul_f32_e32 v37, v36, v36
	v_and_b32_e32 v38, 0xffff0000, v59
	v_fmamk_f32 v37, v37, 0xbdd2d3e7, v129
	v_mul_f32_e32 v39, v38, v38
	v_mul_f32_e32 v37, v37, v36
	v_fmamk_f32 v39, v39, 0xbdd2d3e7, v129
	v_mul_f32_e32 v39, v39, v38
	v_exp_f32_e32 v37, v37
	v_exp_f32_e32 v39, v39
	v_cvt_pk_bf16_f32 v34, v35, v34
	v_add_f32_e32 v37, 1.0, v37
	v_rcp_f32_e32 v37, v37
	v_add_f32_e32 v35, 1.0, v39
	v_rcp_f32_e32 v35, v35
	v_mul_f32_e32 v25, 0x3d372713, v24
	v_mul_f32_e32 v36, v37, v36
	v_add_f32_e32 v37, v48, v56
	v_mul_f32_e32 v36, v36, v37
	v_mul_f32_e32 v35, v35, v38
	v_add_f32_e32 v37, v49, v56
	v_mul_f32_e32 v35, v35, v37
	v_cvt_pk_bf16_f32 v35, v36, v35
	v_lshlrev_b32_e32 v36, 16, v60
	v_mul_f32_e32 v37, v36, v36
	v_and_b32_e32 v38, 0xffff0000, v60
	v_fmamk_f32 v37, v37, 0xbdd2d3e7, v129
	v_mul_f32_e32 v39, v38, v38
	v_mul_f32_e32 v37, v37, v36
	v_fmamk_f32 v39, v39, 0xbdd2d3e7, v129
	v_mul_f32_e32 v39, v39, v38
	v_exp_f32_e32 v37, v37
	v_exp_f32_e32 v39, v39
	global_store_dwordx2 v[40:41], v[34:35], off offset:64
	v_add_f32_e32 v37, 1.0, v37
	v_rcp_f32_e32 v37, v37
	v_add_f32_e32 v34, 1.0, v39
	v_rcp_f32_e32 v34, v34
	v_and_b32_e32 v30, 0xffff0000, v30
	v_mul_f32_e32 v35, v37, v36
	v_add_f32_e32 v36, v42, v56
	v_mul_f32_e32 v35, v35, v36
	v_mul_f32_e32 v34, v34, v38
	v_add_f32_e32 v36, v43, v56
	v_mul_f32_e32 v34, v34, v36
	v_lshlrev_b32_e32 v36, 16, v61
	v_mul_f32_e32 v37, v36, v36
	v_and_b32_e32 v38, 0xffff0000, v61
	v_fmamk_f32 v37, v37, 0xbdd2d3e7, v129
	v_mul_f32_e32 v39, v38, v38
	v_mul_f32_e32 v37, v37, v36
	v_fmamk_f32 v39, v39, 0xbdd2d3e7, v129
	v_mul_f32_e32 v39, v39, v38
	v_exp_f32_e32 v37, v37
	v_exp_f32_e32 v39, v39
	v_cvt_pk_bf16_f32 v34, v35, v34
	v_add_f32_e32 v37, 1.0, v37
	v_rcp_f32_e32 v37, v37
	v_add_f32_e32 v35, 1.0, v39
	v_rcp_f32_e32 v35, v35
	v_mul_f32_e32 v25, v25, v24
	v_mul_f32_e32 v36, v37, v36
	v_add_f32_e32 v37, v44, v56
	v_mul_f32_e32 v36, v36, v37
	v_mul_f32_e32 v35, v35, v38
	v_add_f32_e32 v37, v45, v56
	v_mul_f32_e32 v35, v35, v37
	v_cvt_pk_bf16_f32 v35, v36, v35
	global_store_dwordx2 v[40:41], v[34:35], off offset:96
	global_load_dword v34, v81, s[12:13] offset:192
	s_nop 0
	global_load_dwordx2 v[20:21], v[32:33], off offset:64
	global_load_dwordx2 v[22:23], v[32:33], off offset:96
	v_mul_f32_e32 v32, v30, v30
	v_fma_f32 v25, v25, v24, v24
	v_fmamk_f32 v32, v32, 0xbdd2d3e7, v129
	v_mul_f32_e32 v25, 0xbfcc422a, v25
	v_mul_f32_e32 v32, v32, v30
	v_mul_f32_e32 v25, 0x3fb8aa3b, v25
	v_exp_f32_e32 v25, v25
	v_exp_f32_e32 v32, v32
	v_mfma_f32_16x16x32_bf16 v[10:13], v[14:17], v[50:53], v[10:13]
	v_add_f32_e32 v25, 1.0, v25
	v_rcp_f32_e32 v25, v25
	v_add_f32_e32 v14, 1.0, v32
	v_rcp_f32_e32 v14, v14
	v_mul_f32_e32 v15, v25, v24
	v_and_b32_e32 v24, 0xffff0000, v31
	v_mul_f32_e32 v14, v14, v30
	v_mul_f32_e32 v25, v24, v24
	v_fmamk_f32 v25, v25, 0xbdd2d3e7, v129
	v_mul_f32_e32 v25, v25, v24
	v_exp_f32_e32 v25, v25
	s_waitcnt vmcnt(2)
	v_add_f32_e32 v16, v26, v34
	v_mul_f32_e32 v15, v15, v16
	v_add_f32_e32 v16, v27, v34
	v_mul_f32_e32 v14, v14, v16
	v_lshlrev_b32_e32 v16, 16, v31
	v_mul_f32_e32 v17, v16, v16
	v_fmamk_f32 v17, v17, 0xbdd2d3e7, v129
	v_mul_f32_e32 v17, v17, v16
	v_exp_f32_e32 v17, v17
	v_cvt_pk_bf16_f32 v14, v15, v14
	v_add_f32_e32 v15, 1.0, v25
	v_rcp_f32_e32 v15, v15
	v_add_f32_e32 v17, 1.0, v17
	v_rcp_f32_e32 v17, v17
	v_add_f32_e32 v6, v6, v34
	v_mul_f32_e32 v15, v15, v24
	v_add_f32_e32 v7, v7, v34
	v_mul_f32_e32 v16, v17, v16
	v_add_f32_e32 v17, v28, v34
	v_mul_f32_e32 v16, v16, v17
	v_add_f32_e32 v17, v29, v34
	v_mul_f32_e32 v15, v15, v17
	v_cvt_pk_bf16_f32 v15, v16, v15
	v_mad_u64_u32 v[16:17], s[0:1], v57, s3, v[72:73]
	v_lshl_add_u64 v[16:17], v[16:17], 0, s[8:9]
	v_lshl_add_u64 v[16:17], v[16:17], 0, v[0:1]
	v_lshlrev_b32_e32 v0, 16, v18
	v_mul_f32_e32 v24, v0, v0
	v_and_b32_e32 v18, 0xffff0000, v18
	v_fmamk_f32 v24, v24, 0xbdd2d3e7, v129
	v_mul_f32_e32 v25, v18, v18
	v_mul_f32_e32 v24, v24, v0
	v_fmamk_f32 v25, v25, 0xbdd2d3e7, v129
	v_mul_f32_e32 v25, v25, v18
	v_exp_f32_e32 v24, v24
	v_exp_f32_e32 v25, v25
	v_lshl_add_u64 v[16:17], v[16:17], 0, v[70:71]
	v_add_f32_e32 v24, 1.0, v24
	v_rcp_f32_e32 v24, v24
	global_store_dwordx2 v[16:17], v[14:15], off
	v_add_f32_e32 v14, 1.0, v25
	v_rcp_f32_e32 v14, v14
	v_mul_f32_e32 v0, v24, v0
	v_mul_f32_e32 v0, v0, v6
	v_and_b32_e32 v15, 0xffff0000, v19
	v_mul_f32_e32 v6, v14, v18
	v_mul_f32_e32 v6, v6, v7
	v_lshlrev_b32_e32 v7, 16, v19
	v_mul_f32_e32 v14, v7, v7
	v_fmamk_f32 v14, v14, 0xbdd2d3e7, v129
	v_mul_f32_e32 v18, v15, v15
	v_mul_f32_e32 v14, v14, v7
	v_fmamk_f32 v18, v18, 0xbdd2d3e7, v129
	v_mul_f32_e32 v18, v18, v15
	v_exp_f32_e32 v14, v14
	v_exp_f32_e32 v18, v18
	v_cvt_pk_bf16_f32 v6, v0, v6
	v_add_f32_e32 v14, 1.0, v14
	v_rcp_f32_e32 v14, v14
	v_add_f32_e32 v0, 1.0, v18
	v_rcp_f32_e32 v0, v0
	v_add_f32_e32 v8, v8, v34
	v_mul_f32_e32 v7, v14, v7
	v_mul_f32_e32 v7, v7, v8
	v_mul_f32_e32 v0, v0, v15
	v_add_f32_e32 v8, v9, v34
	v_mul_f32_e32 v0, v0, v8
	v_cvt_pk_bf16_f32 v7, v7, v0
	s_waitcnt vmcnt(2)
	v_lshlrev_b32_e32 v0, 16, v20
	v_mul_f32_e32 v8, v0, v0
	v_and_b32_e32 v9, 0xffff0000, v20
	v_fmamk_f32 v8, v8, 0xbdd2d3e7, v129
	v_mul_f32_e32 v14, v9, v9
	v_mul_f32_e32 v8, v8, v0
	v_fmamk_f32 v14, v14, 0xbdd2d3e7, v129
	v_mul_f32_e32 v14, v14, v9
	v_exp_f32_e32 v8, v8
	v_exp_f32_e32 v14, v14
	global_store_dwordx2 v[16:17], v[6:7], off offset:32
	v_add_f32_e32 v8, 1.0, v8
	v_rcp_f32_e32 v8, v8
	v_add_f32_e32 v6, 1.0, v14
	v_rcp_f32_e32 v6, v6
	v_add_f32_e32 v2, v2, v34
	v_mul_f32_e32 v0, v8, v0
	v_mul_f32_e32 v0, v0, v2
	v_mul_f32_e32 v2, v6, v9
	v_add_f32_e32 v3, v3, v34
	v_mul_f32_e32 v2, v2, v3
	v_lshlrev_b32_e32 v3, 16, v21
	v_mul_f32_e32 v6, v3, v3
	v_and_b32_e32 v7, 0xffff0000, v21
	v_fmamk_f32 v6, v6, 0xbdd2d3e7, v129
	v_mul_f32_e32 v8, v7, v7
	v_mul_f32_e32 v6, v6, v3
	v_fmamk_f32 v8, v8, 0xbdd2d3e7, v129
	v_mul_f32_e32 v8, v8, v7
	v_exp_f32_e32 v6, v6
	v_exp_f32_e32 v8, v8
	v_cvt_pk_bf16_f32 v2, v0, v2
	v_add_f32_e32 v6, 1.0, v6
	v_rcp_f32_e32 v6, v6
	v_add_f32_e32 v0, 1.0, v8
	v_rcp_f32_e32 v0, v0
	v_add_f32_e32 v4, v4, v34
	v_mul_f32_e32 v3, v6, v3
	v_mul_f32_e32 v3, v3, v4
	v_mul_f32_e32 v0, v0, v7
	v_add_f32_e32 v4, v5, v34
	v_mul_f32_e32 v0, v0, v4
	v_cvt_pk_bf16_f32 v3, v3, v0
	s_waitcnt vmcnt(2)
	v_lshlrev_b32_e32 v0, 16, v22
	v_mul_f32_e32 v4, v0, v0
	v_and_b32_e32 v5, 0xffff0000, v22
	v_fmamk_f32 v4, v4, 0xbdd2d3e7, v129
	v_mul_f32_e32 v6, v5, v5
	v_mul_f32_e32 v4, v4, v0
	v_fmamk_f32 v6, v6, 0xbdd2d3e7, v129
	v_mul_f32_e32 v6, v6, v5
	v_exp_f32_e32 v4, v4
	v_exp_f32_e32 v6, v6
	global_store_dwordx2 v[16:17], v[2:3], off offset:64
	v_add_f32_e32 v4, 1.0, v4
	v_rcp_f32_e32 v4, v4
	v_add_f32_e32 v2, 1.0, v6
	v_rcp_f32_e32 v2, v2
	v_add_f32_e32 v3, v10, v34
	v_mul_f32_e32 v0, v4, v0
	v_mul_f32_e32 v0, v0, v3
	v_mul_f32_e32 v2, v2, v5
	v_add_f32_e32 v3, v11, v34
	v_mul_f32_e32 v2, v2, v3
	v_lshlrev_b32_e32 v3, 16, v23
	v_mul_f32_e32 v4, v3, v3
	v_and_b32_e32 v5, 0xffff0000, v23
	v_fmamk_f32 v4, v4, 0xbdd2d3e7, v129
	v_mul_f32_e32 v6, v5, v5
	v_mul_f32_e32 v4, v4, v3
	v_fmamk_f32 v6, v6, 0xbdd2d3e7, v129
	v_mul_f32_e32 v6, v6, v5
	v_exp_f32_e32 v4, v4
	v_exp_f32_e32 v6, v6
	v_cvt_pk_bf16_f32 v2, v0, v2
	v_add_f32_e32 v4, 1.0, v4
	v_rcp_f32_e32 v4, v4
	v_add_f32_e32 v0, 1.0, v6
	v_rcp_f32_e32 v0, v0
	v_mul_f32_e32 v3, v4, v3
	v_add_f32_e32 v4, v12, v34
	v_mul_f32_e32 v3, v3, v4
	v_mul_f32_e32 v0, v0, v5
	v_add_f32_e32 v4, v13, v34
	v_mul_f32_e32 v0, v0, v4
	v_cvt_pk_bf16_f32 v3, v3, v0
	global_store_dwordx2 v[16:17], v[2:3], off offset:96
	s_barrier
	s_cbranch_scc0 .LBB0_626
	s_and_b32 s0, s10, 3
	s_lshl_b32 s1, s10, 5
	v_mov_b32_e32 v38, v194
	v_cvt_f32_ubyte0_e32 v0, s0
	s_and_b32 s1, s1, 0x7fffff80
	v_sub_f32_e32 v37, 0xc0a00000, v0
	v_bfe_u32 v36, v38, 1, 7
	s_mov_b32 s2, 0xc2fc0000
	v_cmp_gt_f32_e32 vcc, s2, v37
	v_or_b32_e32 v0, s1, v36
	v_mov_b64_e32 v[2:3], s[50:51]
	s_and_b64 s[4:5], vcc, exec
	v_mad_u64_u32 v[34:35], s[4:5], v0, s3, v[2:3]
	v_and_b32_e32 v40, 1, v38
	s_cselect_b32 s2, 0xffffffc0, 0
	s_lshl_b32 s4, s0, 8
	s_mov_b32 s5, s89
	v_lshl_add_u64 v[2:3], v[34:35], 0, s[4:5]
	v_lshlrev_b32_e32 v4, 7, v40
	v_mov_b32_e32 v5, v1
	v_lshl_add_u64 v[2:3], v[2:3], 0, v[4:5]
	global_load_dwordx4 v[30:33], v[2:3], off offset:3072
	global_load_dwordx4 v[26:29], v[2:3], off offset:3088
	global_load_dwordx4 v[22:25], v[2:3], off offset:3104
	global_load_dwordx4 v[18:21], v[2:3], off offset:3120
	global_load_dwordx4 v[14:17], v[2:3], off offset:3136
	global_load_dwordx4 v[10:13], v[2:3], off offset:3152
	global_load_dwordx4 v[6:9], v[2:3], off offset:3168
	s_nop 0
	global_load_dwordx4 v[2:5], v[2:3], off offset:3184
	s_mov_b32 s1, s89
	s_lshl_b32 s0, s0, 7
	v_lshlrev_b32_e32 v0, 6, v40
	v_mul_u32_u24_e32 v41, 0x2200, v40
	v_cndmask_b32_e32 v42, 0, v248, vcc
	v_lshl_add_u64 v[34:35], v[34:35], 0, s[0:1]
	v_lshlrev_b32_e32 v36, 1, v36
	v_lshlrev_b32_e32 v41, 1, v41
	v_add_f32_e32 v37, v37, v42
	v_lshl_add_u64 v[42:43], v[34:35], 0, v[0:1]
	v_add3_u32 v44, s15, v41, v36
	v_add3_u32 v41, s15, v36, v41
	v_exp_f32_e32 v45, v37
	global_load_dwordx4 v[34:37], v[42:43], off offset:2560
	v_lshrrev_b32_e32 v39, 1, v38
	v_and_b32_e32 v55, 0x60, v39
	v_ldexp_f32 v0, v45, s2
	v_sub_f32_e32 v0, 1.0, v0
	v_cmp_gt_f32_e32 vcc, s11, v0
	s_and_b64 s[0:1], vcc, exec
	s_cselect_b32 s0, 32, 0
	v_ldexp_f32 v0, v0, s0
	v_log_f32_e32 v0, v0
	s_mov_b32 s0, 0x3f317217
	v_bfe_u32 v54, v38, 4, 2
	s_mov_b32 s11, s89
	s_mul_i32 s2, s10, 3
	s_movk_i32 s39, 0xd80
	s_mov_b32 s69, 0x800000
	s_waitcnt vmcnt(8)
	ds_write_b16 v44, v30
	ds_write_b16_d16_hi v41, v30 offset:272
	ds_write_b16 v44, v31 offset:544
	ds_write_b16_d16_hi v41, v31 offset:816
	ds_write_b16 v44, v32 offset:1088
	ds_write_b16_d16_hi v41, v32 offset:1360
	ds_write_b16 v44, v33 offset:1632
	ds_write_b16_d16_hi v41, v33 offset:1904
	s_waitcnt vmcnt(7)
	ds_write_b16 v44, v26 offset:2176
	ds_write_b16_d16_hi v41, v26 offset:2448
	ds_write_b16 v44, v27 offset:2720
	ds_write_b16_d16_hi v41, v27 offset:2992
	ds_write_b16 v44, v28 offset:3264
	ds_write_b16_d16_hi v41, v28 offset:3536
	ds_write_b16 v44, v29 offset:3808
	ds_write_b16_d16_hi v41, v29 offset:4080
	s_waitcnt vmcnt(6)
	ds_write_b16 v44, v22 offset:4352
	ds_write_b16_d16_hi v41, v22 offset:4624
	ds_write_b16 v44, v23 offset:4896
	ds_write_b16_d16_hi v41, v23 offset:5168
	ds_write_b16 v44, v24 offset:5440
	ds_write_b16_d16_hi v41, v24 offset:5712
	ds_write_b16 v44, v25 offset:5984
	ds_write_b16_d16_hi v41, v25 offset:6256
	s_waitcnt vmcnt(5)
	ds_write_b16 v44, v18 offset:6528
	ds_write_b16_d16_hi v41, v18 offset:6800
	ds_write_b16 v44, v19 offset:7072
	ds_write_b16_d16_hi v41, v19 offset:7344
	ds_write_b16 v44, v20 offset:7616
	ds_write_b16_d16_hi v41, v20 offset:7888
	ds_write_b16 v44, v21 offset:8160
	ds_write_b16_d16_hi v41, v21 offset:8432
	s_waitcnt vmcnt(4)
	ds_write_b16 v44, v14 offset:8704
	ds_write_b16_d16_hi v41, v14 offset:8976
	ds_write_b16 v44, v15 offset:9248
	ds_write_b16_d16_hi v41, v15 offset:9520
	ds_write_b16 v44, v16 offset:9792
	ds_write_b16_d16_hi v41, v16 offset:10064
	ds_write_b16 v44, v17 offset:10336
	ds_write_b16_d16_hi v41, v17 offset:10608
	s_waitcnt vmcnt(3)
	ds_write_b16 v44, v10 offset:10880
	ds_write_b16_d16_hi v41, v10 offset:11152
	ds_write_b16 v44, v11 offset:11424
	ds_write_b16_d16_hi v41, v11 offset:11696
	ds_write_b16 v44, v12 offset:11968
	ds_write_b16_d16_hi v41, v12 offset:12240
	ds_write_b16 v44, v13 offset:12512
	ds_write_b16_d16_hi v41, v13 offset:12784
	s_waitcnt vmcnt(2)
	ds_write_b16 v44, v6 offset:13056
	ds_write_b16_d16_hi v41, v6 offset:13328
	ds_write_b16 v44, v7 offset:13600
	ds_write_b16_d16_hi v41, v7 offset:13872
	global_load_dwordx4 v[10:13], v[42:43], off offset:2576
	ds_write_b16 v44, v8 offset:14144
	ds_write_b16_d16_hi v41, v8 offset:14416
	ds_write_b16 v44, v9 offset:14688
	ds_write_b16_d16_hi v41, v9 offset:14960
	s_waitcnt vmcnt(2)
	ds_write_b16 v44, v2 offset:15232
	ds_write_b16_d16_hi v41, v2 offset:15504
	ds_write_b16 v44, v3 offset:15776
	ds_write_b16_d16_hi v41, v3 offset:16048
	ds_write_b16 v44, v4 offset:16320
	ds_write_b16_d16_hi v41, v4 offset:16592
	global_load_dwordx4 v[6:9], v[42:43], off offset:2592
	v_mul_f32_e32 v2, 0x3f317217, v0
	v_fma_f32 v2, v0, s0, -v2
	v_fmac_f32_e32 v2, 0x3377d1cf, v0
	s_mov_b32 s0, 0x7f800000
	v_fmac_f32_e32 v2, 0x3f317217, v0
	v_cmp_lt_f32_e64 s[0:1], |v0|, s0
	ds_write_b16 v44, v5 offset:16864
	ds_write_b16_d16_hi v41, v5 offset:17136
	v_cndmask_b32_e64 v0, v0, v2, s[0:1]
	v_cndmask_b32_e32 v2, 0, v231, vcc
	s_movk_i32 s0, 0x7f
	v_sub_f32_e32 v0, v0, v2
	v_bitop3_b32 v2, v39, s0, v39 bitop3:0xc
	v_cvt_f32_ubyte0_e32 v2, v2
	v_mul_f32_e32 v2, v0, v2
	v_mul_f32_e32 v0, 0x3fb8aa3b, v2
	s_mov_b32 s0, 0x3fb8aa3b
	v_fma_f32 v3, v2, s0, -v0
	v_rndne_f32_e32 v4, v0
	v_fmac_f32_e32 v3, 0x32a5705f, v2
	v_sub_f32_e32 v0, v0, v4
	v_add_f32_e32 v0, v0, v3
	v_exp_f32_e32 v3, v0
	v_cvt_i32_f32_e32 v4, v4
	s_mov_b32 s0, 0xc2ce8ed0
	v_cmp_ngt_f32_e32 vcc, s0, v2
	s_mov_b32 s0, 0x42b17218
	v_ldexp_f32 v3, v3, v4
	v_cndmask_b32_e32 v3, 0, v3, vcc
	v_cmp_nlt_f32_e32 vcc, s0, v2
	s_waitcnt vmcnt(2)
	v_lshlrev_b32_e32 v15, 16, v34
	v_and_b32_e32 v0, 15, v38
	v_cndmask_b32_e32 v2, v195, v3, vcc
	v_mul_f32_e32 v14, 0x3e000000, v2
	global_load_dwordx4 v[2:5], v[42:43], off offset:2608
	v_mul_f32_e32 v15, v14, v15
	v_cvt_pk_bf16_f32 v15, v15, s0
	s_movk_i32 s0, 0xde00
	v_mad_i32_i24 v16, v40, s0, v44
	ds_write_b16 v16, v15 offset:34816
	v_and_b32_e32 v15, 0xffff0000, v34
	v_mul_f32_e32 v15, v14, v15
	v_cvt_pk_bf16_f32 v15, v15, s0
	v_mad_i32_i24 v17, v40, s0, v41
	ds_write_b16 v17, v15 offset:35088
	v_lshlrev_b32_e32 v15, 16, v35
	v_mul_f32_e32 v15, v14, v15
	v_cvt_pk_bf16_f32 v15, v15, s0
	ds_write_b16 v16, v15 offset:35360
	v_and_b32_e32 v15, 0xffff0000, v35
	v_mul_f32_e32 v15, v14, v15
	v_cvt_pk_bf16_f32 v15, v15, s0
	ds_write_b16 v17, v15 offset:35632
	v_lshlrev_b32_e32 v15, 16, v36
	v_mul_f32_e32 v15, v14, v15
	v_cvt_pk_bf16_f32 v15, v15, s0
	ds_write_b16 v16, v15 offset:35904
	v_and_b32_e32 v15, 0xffff0000, v36
	v_mul_f32_e32 v15, v14, v15
	v_cvt_pk_bf16_f32 v15, v15, s0
	ds_write_b16 v17, v15 offset:36176
	v_lshlrev_b32_e32 v15, 16, v37
	v_mul_f32_e32 v15, v14, v15
	v_cvt_pk_bf16_f32 v15, v15, s0
	ds_write_b16 v16, v15 offset:36448
	v_and_b32_e32 v15, 0xffff0000, v37
	v_mul_f32_e32 v15, v14, v15
	v_cvt_pk_bf16_f32 v15, v15, s0
	ds_write_b16 v17, v15 offset:36720
	s_waitcnt vmcnt(2)
	v_lshlrev_b32_e32 v15, 16, v10
	v_and_b32_e32 v10, 0xffff0000, v10
	v_mul_f32_e32 v10, v14, v10
	v_cvt_pk_bf16_f32 v10, v10, s0
	ds_write_b16 v17, v10 offset:37264
	v_lshlrev_b32_e32 v10, 16, v11
	v_mul_f32_e32 v10, v14, v10
	v_cvt_pk_bf16_f32 v10, v10, s0
	ds_write_b16 v16, v10 offset:37536
	v_and_b32_e32 v10, 0xffff0000, v11
	v_mul_f32_e32 v10, v14, v10
	v_cvt_pk_bf16_f32 v10, v10, s0
	ds_write_b16 v17, v10 offset:37808
	v_lshlrev_b32_e32 v10, 16, v12
	v_mul_f32_e32 v10, v14, v10
	v_cvt_pk_bf16_f32 v10, v10, s0
	ds_write_b16 v16, v10 offset:38080
	v_and_b32_e32 v10, 0xffff0000, v12
	v_mul_f32_e32 v10, v14, v10
	v_cvt_pk_bf16_f32 v10, v10, s0
	ds_write_b16 v17, v10 offset:38352
	v_lshlrev_b32_e32 v10, 16, v13
	v_mul_f32_e32 v10, v14, v10
	v_cvt_pk_bf16_f32 v10, v10, s0
	ds_write_b16 v16, v10 offset:38624
	v_and_b32_e32 v10, 0xffff0000, v13
	v_mul_f32_e32 v10, v14, v10
	v_cvt_pk_bf16_f32 v10, v10, s0
	ds_write_b16 v17, v10 offset:38896
	s_waitcnt vmcnt(1)
	v_lshlrev_b32_e32 v10, 16, v6
	v_and_b32_e32 v6, 0xffff0000, v6
	v_mul_f32_e32 v6, v14, v6
	v_cvt_pk_bf16_f32 v6, v6, s0
	ds_write_b16 v17, v6 offset:39440
	v_lshlrev_b32_e32 v6, 16, v7
	v_mul_f32_e32 v6, v14, v6
	v_cvt_pk_bf16_f32 v6, v6, s0
	ds_write_b16 v16, v6 offset:39712
	v_and_b32_e32 v6, 0xffff0000, v7
	v_mul_f32_e32 v6, v14, v6
	v_cvt_pk_bf16_f32 v6, v6, s0
	ds_write_b16 v17, v6 offset:39984
	v_lshlrev_b32_e32 v6, 16, v8
	v_mul_f32_e32 v6, v14, v6
	v_cvt_pk_bf16_f32 v6, v6, s0
	ds_write_b16 v16, v6 offset:40256
	v_and_b32_e32 v6, 0xffff0000, v8
	v_mul_f32_e32 v6, v14, v6
	v_cvt_pk_bf16_f32 v6, v6, s0
	ds_write_b16 v17, v6 offset:40528
	v_lshlrev_b32_e32 v6, 16, v9
	v_mul_f32_e32 v6, v14, v6
	v_cvt_pk_bf16_f32 v6, v6, s0
	ds_write_b16 v16, v6 offset:40800
	v_and_b32_e32 v6, 0xffff0000, v9
	v_mul_f32_e32 v6, v14, v6
	v_cvt_pk_bf16_f32 v6, v6, s0
	ds_write_b16 v17, v6 offset:41072
	s_waitcnt vmcnt(0)
	v_lshlrev_b32_e32 v6, 16, v2
	v_and_b32_e32 v2, 0xffff0000, v2
	v_mul_f32_e32 v2, v14, v2
	v_cvt_pk_bf16_f32 v2, v2, s0
	ds_write_b16 v17, v2 offset:41616
	v_lshlrev_b32_e32 v2, 16, v3
	v_mul_f32_e32 v2, v14, v2
	v_cvt_pk_bf16_f32 v2, v2, s0
	ds_write_b16 v16, v2 offset:41888
	v_and_b32_e32 v2, 0xffff0000, v3
	v_mul_f32_e32 v2, v14, v2
	v_cvt_pk_bf16_f32 v2, v2, s0
	ds_write_b16 v17, v2 offset:42160
	v_lshlrev_b32_e32 v2, 16, v4
	v_mul_f32_e32 v2, v14, v2
	v_cvt_pk_bf16_f32 v2, v2, s0
	ds_write_b16 v16, v2 offset:42432
	v_and_b32_e32 v2, 0xffff0000, v4
	v_mul_f32_e32 v2, v14, v2
	v_cvt_pk_bf16_f32 v2, v2, s0
	ds_write_b16 v17, v2 offset:42704
	v_lshlrev_b32_e32 v2, 16, v5
	v_mul_f32_e32 v2, v14, v2
	v_cvt_pk_bf16_f32 v2, v2, s0
	ds_write_b16 v16, v2 offset:42976
	v_and_b32_e32 v2, 0xffff0000, v5
	v_mul_f32_e32 v2, v14, v2
	v_mul_f32_e32 v6, v14, v6
	v_cvt_pk_bf16_f32 v2, v2, s0
	v_cvt_pk_bf16_f32 v6, v6, s0
	ds_write_b16 v17, v2 offset:43248
	v_or_b32_e32 v2, v55, v0
	v_mul_f32_e32 v15, v14, v15
	v_mul_f32_e32 v10, v14, v10
	ds_write_b16 v16, v6 offset:41344
	v_lshl_add_u32 v6, v54, 4, s15
	v_mul_u32_u24_e32 v2, 0x88, v2
	v_mul_u32_u24_e32 v7, 0x88, v0
	v_cvt_pk_bf16_f32 v15, v15, s0
	v_cvt_pk_bf16_f32 v10, v10, s0
	v_lshl_add_u32 v56, v2, 1, v6
	v_lshl_add_u32 v57, v7, 1, v6
	ds_write_b16 v16, v15 offset:36992
	ds_write_b16 v16, v10 offset:39168
	s_waitcnt lgkmcnt(0)
	s_barrier
	ds_read_b128 v[2:5], v56
	ds_read_b128 v[38:41], v56 offset:64
	ds_read_b128 v[6:9], v57 offset:34816
	ds_read_b128 v[34:37], v56 offset:4352
	ds_read_b128 v[14:17], v57 offset:39168
	ds_read_b128 v[22:25], v57 offset:43520
	ds_read_b128 v[30:33], v57 offset:47872
	ds_read_b128 v[46:49], v57 offset:43584
	s_waitcnt lgkmcnt(5)
	v_mfma_f32_16x16x32_bf16 v[10:13], v[2:5], v[6:9], 0
	ds_read_b128 v[42:45], v57 offset:39232
	ds_read_b128 v[50:53], v57 offset:47936
	s_lshl_b64 s[0:1], s[10:11], 15
	s_waitcnt lgkmcnt(5)
	v_mfma_f32_16x16x32_bf16 v[18:21], v[2:5], v[14:17], 0
	s_add_u32 s0, s24, s0
	s_addc_u32 s1, s25, s1
	s_add_i32 s9, s2, 0xfffffd80
	s_waitcnt lgkmcnt(4)
	v_mfma_f32_16x16x32_bf16 v[26:29], v[2:5], v[22:25], 0
	s_waitcnt lgkmcnt(3)
	v_mfma_f32_16x16x32_bf16 v[2:5], v[2:5], v[30:33], 0
	v_mfma_f32_16x16x32_bf16 v[6:9], v[34:37], v[6:9], 0
	v_mfma_f32_16x16x32_bf16 v[14:17], v[34:37], v[14:17], 0
	v_mfma_f32_16x16x32_bf16 v[22:25], v[34:37], v[22:25], 0
	v_mfma_f32_16x16x32_bf16 v[30:33], v[34:37], v[30:33], 0
	ds_read_b128 v[34:37], v57 offset:34880
	s_waitcnt lgkmcnt(0)
	v_mfma_f32_16x16x32_bf16 v[10:13], v[38:41], v[34:37], v[10:13]
	v_mfma_f32_16x16x32_bf16 v[18:21], v[38:41], v[42:45], v[18:21]
	v_mfma_f32_16x16x32_bf16 v[26:29], v[38:41], v[46:49], v[26:29]
	v_mfma_f32_16x16x32_bf16 v[2:5], v[38:41], v[50:53], v[2:5]
	ds_read_b128 v[38:41], v56 offset:4416
	s_waitcnt lgkmcnt(0)
	v_mfma_f32_16x16x32_bf16 v[6:9], v[38:41], v[34:37], v[6:9]
	ds_read_b128 v[34:37], v56 offset:128
	v_mfma_f32_16x16x32_bf16 v[14:17], v[38:41], v[42:45], v[14:17]
	ds_read_b128 v[42:45], v57 offset:39296
	v_mfma_f32_16x16x32_bf16 v[22:25], v[38:41], v[46:49], v[22:25]
	ds_read_b128 v[46:49], v57 offset:43648
	v_mfma_f32_16x16x32_bf16 v[30:33], v[38:41], v[50:53], v[30:33]
	ds_read_b128 v[38:41], v57 offset:34944
	ds_read_b128 v[50:53], v57 offset:48000
	s_waitcnt lgkmcnt(1)
	v_mfma_f32_16x16x32_bf16 v[10:13], v[34:37], v[38:41], v[10:13]
	v_mfma_f32_16x16x32_bf16 v[18:21], v[34:37], v[42:45], v[18:21]
	v_mfma_f32_16x16x32_bf16 v[26:29], v[34:37], v[46:49], v[26:29]
	s_waitcnt lgkmcnt(0)
	v_mfma_f32_16x16x32_bf16 v[2:5], v[34:37], v[50:53], v[2:5]
	ds_read_b128 v[34:37], v56 offset:4480
	s_waitcnt lgkmcnt(0)
	v_mfma_f32_16x16x32_bf16 v[6:9], v[34:37], v[38:41], v[6:9]
	ds_read_b128 v[38:41], v56 offset:192
	v_mfma_f32_16x16x32_bf16 v[14:17], v[34:37], v[42:45], v[14:17]
	ds_read_b128 v[42:45], v57 offset:39360
	v_mfma_f32_16x16x32_bf16 v[22:25], v[34:37], v[46:49], v[22:25]
	ds_read_b128 v[46:49], v57 offset:43712
	v_mfma_f32_16x16x32_bf16 v[30:33], v[34:37], v[50:53], v[30:33]
	ds_read_b128 v[34:37], v57 offset:35008
	ds_read_b128 v[50:53], v57 offset:48064
	s_waitcnt lgkmcnt(1)
	v_mfma_f32_16x16x32_bf16 v[10:13], v[38:41], v[34:37], v[10:13]
	v_mfma_f32_16x16x32_bf16 v[18:21], v[38:41], v[42:45], v[18:21]
	v_mfma_f32_16x16x32_bf16 v[26:29], v[38:41], v[46:49], v[26:29]
	s_waitcnt lgkmcnt(0)
	v_mfma_f32_16x16x32_bf16 v[2:5], v[38:41], v[50:53], v[2:5]
	ds_read_b128 v[38:41], v56 offset:4544
	s_waitcnt lgkmcnt(0)
	v_mfma_f32_16x16x32_bf16 v[6:9], v[38:41], v[34:37], v[6:9]
	v_lshlrev_b32_e32 v37, 6, v55
	v_lshl_or_b32 v37, v54, 8, v37
	v_or_b32_e32 v34, 16, v0
	v_mfma_f32_16x16x32_bf16 v[14:17], v[38:41], v[42:45], v[14:17]
	v_or_b32_e32 v35, 32, v0
	v_or_b32_e32 v36, 48, v0
	v_mfma_f32_16x16x32_bf16 v[22:25], v[38:41], v[46:49], v[22:25]
	v_mfma_f32_16x16x32_bf16 v[30:33], v[38:41], v[50:53], v[30:33]
	v_or_b32_e32 v38, v37, v0
	v_lshlrev_b32_e32 v38, 2, v38
	global_store_dword v38, v10, s[0:1]
	global_store_dword v38, v11, s[0:1] offset:256
	global_store_dword v38, v12, s[0:1] offset:512
	global_store_dword v38, v13, s[0:1] offset:768
	global_store_dword v38, v18, s[0:1] offset:64
	v_or_b32_e32 v10, v37, v34
	v_lshlrev_b32_e32 v10, 2, v10
	global_store_dword v10, v19, s[0:1] offset:256
	global_store_dword v10, v20, s[0:1] offset:512
	global_store_dword v10, v21, s[0:1] offset:768
	global_store_dword v38, v26, s[0:1] offset:128
	v_or_b32_e32 v10, v37, v35
	v_lshlrev_b32_e32 v10, 2, v10
	global_store_dword v10, v27, s[0:1] offset:256
	global_store_dword v10, v28, s[0:1] offset:512
	global_store_dword v10, v29, s[0:1] offset:768
	global_store_dword v38, v2, s[0:1] offset:192
	v_or_b32_e32 v2, v37, v36
	v_lshlrev_b32_e32 v2, 2, v2
	global_store_dword v2, v3, s[0:1] offset:256
	global_store_dword v2, v4, s[0:1] offset:512
	global_store_dword v2, v5, s[0:1] offset:768
	v_or_b32_e32 v2, 0x400, v37
	v_or_b32_e32 v3, v2, v0
	v_lshlrev_b32_e32 v3, 2, v3
	global_store_dword v3, v6, s[0:1]
	v_or_b32_e32 v3, 0x440, v37
	v_or_b32_e32 v4, v3, v0
	v_lshlrev_b32_e32 v4, 2, v4
	global_store_dword v4, v7, s[0:1]
	v_or_b32_e32 v4, 0x480, v37
	v_or_b32_e32 v5, v4, v0
	v_lshlrev_b32_e32 v5, 2, v5
	global_store_dword v5, v8, s[0:1]
	v_or_b32_e32 v5, 0x4c0, v37
	v_or_b32_e32 v0, v5, v0
	v_lshlrev_b32_e32 v0, 2, v0
	global_store_dword v0, v9, s[0:1]
	v_or_b32_e32 v0, v2, v34
	v_lshlrev_b32_e32 v0, 2, v0
	global_store_dword v0, v14, s[0:1]
	v_or_b32_e32 v0, v3, v34
	v_lshlrev_b32_e32 v0, 2, v0
	global_store_dword v0, v15, s[0:1]
	v_or_b32_e32 v0, v4, v34
	v_lshlrev_b32_e32 v0, 2, v0
	global_store_dword v0, v16, s[0:1]
	v_or_b32_e32 v0, v5, v34
	v_lshlrev_b32_e32 v0, 2, v0
	global_store_dword v0, v17, s[0:1]
	v_or_b32_e32 v0, v2, v35
	v_lshlrev_b32_e32 v0, 2, v0
	global_store_dword v0, v22, s[0:1]
	v_or_b32_e32 v0, v3, v35
	v_lshlrev_b32_e32 v0, 2, v0
	global_store_dword v0, v23, s[0:1]
	v_or_b32_e32 v0, v4, v35
	v_lshlrev_b32_e32 v0, 2, v0
	global_store_dword v0, v24, s[0:1]
	v_or_b32_e32 v0, v5, v35
	v_lshlrev_b32_e32 v0, 2, v0
	global_store_dword v0, v25, s[0:1]
	v_or_b32_e32 v0, v2, v36
	v_lshlrev_b32_e32 v0, 2, v0
	global_store_dword v0, v30, s[0:1]
	v_or_b32_e32 v0, v3, v36
	v_lshlrev_b32_e32 v0, 2, v0
	global_store_dword v0, v31, s[0:1]
	v_or_b32_e32 v0, v4, v36
	v_lshlrev_b32_e32 v0, 2, v0
	global_store_dword v0, v32, s[0:1]
	v_or_b32_e32 v0, v5, v36
	v_lshlrev_b32_e32 v0, 2, v0
	global_store_dword v0, v33, s[0:1]
	s_lshl_b32 s0, s9, 6
	s_and_b32 s11, s0, 0x3fc0
	v_mov_b32_e32 v0, v194
	s_cmpk_lt_u32 s9, 0x200
	s_barrier
	s_cselect_b64 s[0:1], -1, 0
	s_and_b64 s[4:5], s[0:1], exec
	v_bfe_u32 v12, v0, 2, 6
	v_lshlrev_b32_e32 v0, 4, v0
	s_cselect_b32 s4, s39, 0xe80
	s_lshr_b32 s5, s9, 2
	v_and_b32_e32 v10, 48, v0
	v_or_b32_e32 v0, s11, v12
	s_and_b32 s9, s5, 64
	v_mul_u32_u24_e32 v0, 0xf80, v0
	s_or_b32 s4, s4, s9
	v_lshlrev_b32_e32 v0, 1, v0
	v_lshl_add_u64 v[2:3], s[50:51], 0, v[0:1]
	s_lshl_b32 s4, s4, 1
	s_mov_b32 s5, s89
	v_lshl_add_u64 v[2:3], v[2:3], 0, s[4:5]
	v_lshlrev_b32_e32 v0, 1, v10
	v_lshl_add_u64 v[6:7], v[2:3], 0, v[0:1]
	global_load_dwordx4 v[2:5], v[6:7], off
	s_nop 0
	global_load_dwordx4 v[6:9], v[6:7], off offset:16
	v_mul_u32_u24_e32 v10, 0x48, v10
	v_lshlrev_b32_e32 v10, 1, v10
	v_lshlrev_b32_e32 v11, 1, v12
	v_add3_u32 v13, s15, v10, v11
	v_add3_u32 v10, s15, v11, v10
	s_and_b64 s[0:1], s[0:1], exec
	s_cselect_b32 s1, s53, s55
	s_cselect_b32 s0, s52, s54
	s_waitcnt vmcnt(1)
	ds_write_b16 v13, v2
	ds_write_b16_d16_hi v10, v2 offset:144
	ds_write_b16 v13, v3 offset:288
	ds_write_b16_d16_hi v10, v3 offset:432
	ds_write_b16 v13, v4 offset:576
	ds_write_b16_d16_hi v10, v4 offset:720
	ds_write_b16 v13, v5 offset:864
	ds_write_b16_d16_hi v10, v5 offset:1008
	s_waitcnt vmcnt(0)
	ds_write_b16 v13, v6 offset:1152
	ds_write_b16_d16_hi v10, v6 offset:1296
	ds_write_b16 v13, v7 offset:1440
	ds_write_b16_d16_hi v10, v7 offset:1584
	ds_write_b16 v13, v8 offset:1728
	ds_write_b16_d16_hi v10, v8 offset:1872
	ds_write_b16 v13, v9 offset:2016
	ds_write_b16_d16_hi v10, v9 offset:2160
	v_or_b32_e32 v2, s9, v12
	v_lshlrev_b32_e32 v2, 15, v2
	v_mov_b32_e32 v3, v1
	v_lshl_add_u64 v[10:11], s[0:1], 0, v[2:3]
	v_mul_u32_u24_e32 v2, 0x90, v12
	v_add3_u32 v6, s15, v2, v0
	s_waitcnt lgkmcnt(0)
	s_barrier
	ds_read_b128 v[2:5], v6
	ds_read_b128 v[6:9], v6 offset:16
	s_lshl_b32 s0, s11, 1
	s_mov_b32 s1, s89
	s_add_i32 s9, s2, 0xfffffd81
	v_lshl_add_u64 v[10:11], v[10:11], 0, s[0:1]
	s_lshl_b32 s0, s9, 6
	s_and_b32 s11, s0, 0x3fc0
	v_lshl_add_u64 v[10:11], v[10:11], 0, v[0:1]
	v_mov_b32_e32 v0, v194
	s_cmpk_lt_u32 s9, 0x200
	s_waitcnt lgkmcnt(1)
	global_store_dwordx4 v[10:11], v[2:5], off
	s_waitcnt lgkmcnt(0)
	global_store_dwordx4 v[10:11], v[6:9], off offset:16
	s_barrier
	s_cselect_b64 s[0:1], -1, 0
	s_and_b64 s[4:5], s[0:1], exec
	v_bfe_u32 v12, v0, 2, 6
	v_lshlrev_b32_e32 v0, 4, v0
	s_cselect_b32 s4, s39, 0xe80
	s_lshr_b32 s5, s9, 2
	v_and_b32_e32 v10, 48, v0
	v_or_b32_e32 v0, s11, v12
	s_and_b32 s9, s5, 64
	v_mul_u32_u24_e32 v0, 0xf80, v0
	s_or_b32 s4, s4, s9
	v_lshlrev_b32_e32 v0, 1, v0
	v_lshl_add_u64 v[2:3], s[50:51], 0, v[0:1]
	s_lshl_b32 s4, s4, 1
	s_mov_b32 s5, s89
	v_lshl_add_u64 v[2:3], v[2:3], 0, s[4:5]
	v_lshlrev_b32_e32 v0, 1, v10
	v_lshl_add_u64 v[6:7], v[2:3], 0, v[0:1]
	global_load_dwordx4 v[2:5], v[6:7], off
	s_nop 0
	global_load_dwordx4 v[6:9], v[6:7], off offset:16
	v_mul_u32_u24_e32 v10, 0x48, v10
	v_lshlrev_b32_e32 v10, 1, v10
	v_lshlrev_b32_e32 v11, 1, v12
	v_add3_u32 v13, s15, v10, v11
	v_add3_u32 v10, s15, v11, v10
	s_and_b64 s[0:1], s[0:1], exec
	s_cselect_b32 s1, s53, s55
	s_cselect_b32 s0, s52, s54
	s_addk_i32 s2, 0xfd82
	s_waitcnt vmcnt(1)
	ds_write_b16 v13, v2
	ds_write_b16_d16_hi v10, v2 offset:144
	ds_write_b16 v13, v3 offset:288
	ds_write_b16_d16_hi v10, v3 offset:432
	ds_write_b16 v13, v4 offset:576
	ds_write_b16_d16_hi v10, v4 offset:720
	ds_write_b16 v13, v5 offset:864
	ds_write_b16_d16_hi v10, v5 offset:1008
	s_waitcnt vmcnt(0)
	ds_write_b16 v13, v6 offset:1152
	ds_write_b16_d16_hi v10, v6 offset:1296
	ds_write_b16 v13, v7 offset:1440
	ds_write_b16_d16_hi v10, v7 offset:1584
	ds_write_b16 v13, v8 offset:1728
	ds_write_b16_d16_hi v10, v8 offset:1872
	ds_write_b16 v13, v9 offset:2016
	ds_write_b16_d16_hi v10, v9 offset:2160
	v_or_b32_e32 v2, s9, v12
	v_lshlrev_b32_e32 v2, 15, v2
	v_mov_b32_e32 v3, v1
	v_lshl_add_u64 v[10:11], s[0:1], 0, v[2:3]
	v_mul_u32_u24_e32 v2, 0x90, v12
	v_add3_u32 v6, s15, v2, v0
	s_waitcnt lgkmcnt(0)
	s_barrier
	ds_read_b128 v[2:5], v6
	ds_read_b128 v[6:9], v6 offset:16
	s_lshl_b32 s0, s11, 1
	s_mov_b32 s1, s89
	v_lshl_add_u64 v[10:11], v[10:11], 0, s[0:1]
	s_lshl_b32 s0, s2, 6
	s_and_b32 s9, s0, 0x3fc0
	v_lshl_add_u64 v[10:11], v[10:11], 0, v[0:1]
	v_mov_b32_e32 v0, v194
	s_cmpk_lt_u32 s2, 0x200
	s_waitcnt lgkmcnt(1)
	global_store_dwordx4 v[10:11], v[2:5], off
	s_waitcnt lgkmcnt(0)
	global_store_dwordx4 v[10:11], v[6:9], off offset:16
	s_barrier
	s_cselect_b64 s[0:1], -1, 0
	s_and_b64 s[4:5], s[0:1], exec
	v_bfe_u32 v12, v0, 2, 6
	v_lshlrev_b32_e32 v0, 4, v0
	s_cselect_b32 s4, s39, 0xe80
	s_lshr_b32 s2, s2, 2
	v_and_b32_e32 v10, 48, v0
	v_or_b32_e32 v0, s9, v12
	s_and_b32 s2, s2, 64
	v_mul_u32_u24_e32 v0, 0xf80, v0
	s_or_b32 s4, s4, s2
	v_lshlrev_b32_e32 v0, 1, v0
	v_lshl_add_u64 v[2:3], s[50:51], 0, v[0:1]
	s_lshl_b32 s4, s4, 1
	s_mov_b32 s5, s89
	v_lshl_add_u64 v[2:3], v[2:3], 0, s[4:5]
	v_lshlrev_b32_e32 v0, 1, v10
	v_lshl_add_u64 v[6:7], v[2:3], 0, v[0:1]
	global_load_dwordx4 v[2:5], v[6:7], off
	s_nop 0
	global_load_dwordx4 v[6:9], v[6:7], off offset:16
	v_mul_u32_u24_e32 v10, 0x48, v10
	v_lshlrev_b32_e32 v10, 1, v10
	v_lshlrev_b32_e32 v11, 1, v12
	v_add3_u32 v13, s15, v10, v11
	v_add3_u32 v10, s15, v11, v10
	s_and_b64 s[0:1], s[0:1], exec
	s_cselect_b32 s1, s53, s55
	s_cselect_b32 s0, s52, s54
	s_mov_b64 s[4:5], 0
	s_waitcnt vmcnt(1)
	ds_write_b16 v13, v2
	ds_write_b16_d16_hi v10, v2 offset:144
	ds_write_b16 v13, v3 offset:288
	ds_write_b16_d16_hi v10, v3 offset:432
	ds_write_b16 v13, v4 offset:576
	ds_write_b16_d16_hi v10, v4 offset:720
	ds_write_b16 v13, v5 offset:864
	ds_write_b16_d16_hi v10, v5 offset:1008
	s_waitcnt vmcnt(0)
	ds_write_b16 v13, v6 offset:1152
	ds_write_b16_d16_hi v10, v6 offset:1296
	ds_write_b16 v13, v7 offset:1440
	ds_write_b16_d16_hi v10, v7 offset:1584
	ds_write_b16 v13, v8 offset:1728
	ds_write_b16_d16_hi v10, v8 offset:1872
	ds_write_b16 v13, v9 offset:2016
	ds_write_b16_d16_hi v10, v9 offset:2160
	v_or_b32_e32 v2, s2, v12
	v_lshlrev_b32_e32 v2, 15, v2
	v_mov_b32_e32 v3, v1
	v_lshl_add_u64 v[10:11], s[0:1], 0, v[2:3]
	v_mul_u32_u24_e32 v2, 0x90, v12
	v_add3_u32 v6, s15, v2, v0
	s_waitcnt lgkmcnt(0)
	s_barrier
	ds_read_b128 v[2:5], v6
	ds_read_b128 v[6:9], v6 offset:16
	s_lshl_b32 s0, s9, 1
	s_mov_b32 s1, s89
	v_lshl_add_u64 v[10:11], v[10:11], 0, s[0:1]
	v_lshl_add_u64 v[10:11], v[10:11], 0, v[0:1]
	s_mov_b64 s[0:1], 0
	s_cmpk_lt_u32 s10, 0x180
	s_waitcnt lgkmcnt(1)
	global_store_dwordx4 v[10:11], v[2:5], off
	s_waitcnt lgkmcnt(0)
	global_store_dwordx4 v[10:11], v[6:9], off offset:16
	s_barrier
	s_cbranch_scc0 .LBB0_627
	s_lshl_b32 s2, s10, 6
	v_mov_b32_e32 v0, v194
	s_and_b32 s2, s2, 0x3fc0
	s_xor_b32 s2, s2, 0x2000
	v_bfe_u32 v12, v0, 2, 6
	v_lshlrev_b32_e32 v0, 4, v0
	v_and_b32_e32 v10, 48, v0
	v_or_b32_e32 v0, s2, v12
	v_mul_u32_u24_e32 v0, 0xf80, v0
	v_readlane_b32 s40, v251, 54
	v_lshlrev_b32_e32 v0, 1, v0
	v_readlane_b32 s46, v251, 60
	v_readlane_b32 s47, v251, 61
	s_mov_b64 s[4:5], 0x1d80
	v_lshlrev_b32_e32 v11, 1, v12
	v_lshl_add_u64 v[2:3], s[46:47], 0, v[0:1]
	v_lshlrev_b32_e32 v0, 1, v10
	v_lshl_add_u64 v[2:3], v[2:3], 0, v[0:1]
	v_lshl_add_u64 v[6:7], v[2:3], 0, s[4:5]
	v_add_co_u32_e32 v2, vcc, s68, v2
	v_mul_u32_u24_e32 v10, 0x48, v10
	s_nop 0
	v_addc_co_u32_e32 v3, vcc, 0, v3, vcc
	global_load_dwordx4 v[2:5], v[2:3], off offset:3456
	s_nop 0
	global_load_dwordx4 v[6:9], v[6:7], off offset:16
	v_lshlrev_b32_e32 v10, 1, v10
	v_add3_u32 v13, s15, v10, v11
	v_add3_u32 v10, s15, v11, v10
	v_readlane_b32 s50, v252, 0
	v_readlane_b32 s51, v252, 1
	s_lshl_b32 s4, s2, 1
	s_mov_b32 s5, s89
	v_readlane_b32 s41, v251, 55
	v_readlane_b32 s42, v251, 56
	v_readlane_b32 s43, v251, 57
	v_readlane_b32 s44, v251, 58
	v_readlane_b32 s45, v251, 59
	v_readlane_b32 s48, v251, 62
	v_readlane_b32 s49, v251, 63
	v_readlane_b32 s52, v252, 2
	v_readlane_b32 s53, v252, 3
	v_readlane_b32 s54, v252, 4
	v_readlane_b32 s55, v252, 5
	s_waitcnt vmcnt(1)
	ds_write_b16 v13, v2
	ds_write_b16_d16_hi v10, v2 offset:144
	ds_write_b16 v13, v3 offset:288
	ds_write_b16_d16_hi v10, v3 offset:432
	ds_write_b16 v13, v4 offset:576
	ds_write_b16_d16_hi v10, v4 offset:720
	ds_write_b16 v13, v5 offset:864
	ds_write_b16_d16_hi v10, v5 offset:1008
	s_waitcnt vmcnt(0)
	ds_write_b16 v13, v6 offset:1152
	ds_write_b16_d16_hi v10, v6 offset:1296
	ds_write_b16 v13, v7 offset:1440
	ds_write_b16_d16_hi v10, v7 offset:1584
	ds_write_b16 v13, v8 offset:1728
	ds_write_b16_d16_hi v10, v8 offset:1872
	ds_write_b16 v13, v9 offset:2016
	ds_write_b16_d16_hi v10, v9 offset:2160
	v_lshlrev_b32_e32 v2, 15, v12
	v_mov_b32_e32 v3, v1
	v_lshl_add_u64 v[2:3], s[50:51], 0, v[2:3]
	v_lshl_add_u64 v[2:3], v[2:3], 0, s[4:5]
	v_lshl_add_u64 v[2:3], v[2:3], 0, v[0:1]
	v_mul_u32_u24_e32 v4, 0x90, v12
	s_mov_b64 s[4:5], 0x200000
	v_add3_u32 v0, s15, v4, v0
	v_add_co_u32_e32 v12, vcc, 0x200000, v2
	s_waitcnt lgkmcnt(0)
	s_barrier
	v_lshl_add_u64 v[10:11], v[2:3], 0, s[4:5]
	v_addc_co_u32_e32 v13, vcc, 0, v3, vcc
	ds_read_b128 v[2:5], v0
	ds_read_b128 v[6:9], v0 offset:16
	s_waitcnt lgkmcnt(1)
	global_store_dwordx4 v[12:13], v[2:5], off
	s_waitcnt lgkmcnt(0)
	global_store_dwordx4 v[10:11], v[6:9], off offset:16
	s_barrier
	s_mov_b64 s[4:5], -1
	s_branch .LBB0_627

.LBB0_627:
	s_and_b64 vcc, exec, s[0:1]
	s_cbranch_vccz .LBB0_631
	s_lshl_b32 s0, s10, 5
	s_and_b32 s4, s0, 0x1f80
	v_mov_b32_e32 v50, v194
	s_bitset1_b32 s4, 13
	v_readlane_b32 s40, v251, 54
	v_bfe_u32 v31, v50, 1, 7
	v_or_b32_e32 v0, s4, v31
	v_and_b32_e32 v16, 1, v50
	v_mul_u32_u24_e32 v0, 0x1f00, v0
	v_readlane_b32 s46, v251, 60
	v_readlane_b32 s47, v251, 61
	v_mov_b32_e32 v18, 0
	v_lshrrev_b32_e32 v30, 1, v50
	v_lshl_add_u64 v[10:11], s[46:47], 0, v[0:1]
	v_lshlrev_b32_e32 v0, 9, v16
	v_readlane_b32 s41, v251, 55
	v_readlane_b32 s42, v251, 56
	v_readlane_b32 s43, v251, 57
	v_readlane_b32 s44, v251, 58
	v_readlane_b32 s45, v251, 59
	v_readlane_b32 s48, v251, 62
	v_readlane_b32 s49, v251, 63
	v_readlane_b32 s50, v252, 0
	v_readlane_b32 s51, v252, 1
	v_readlane_b32 s52, v252, 2
	v_readlane_b32 s53, v252, 3
	v_readlane_b32 s54, v252, 4
	v_readlane_b32 s55, v252, 5
	v_lshl_add_u64 v[12:13], v[10:11], 0, v[0:1]
	v_readfirstlane_b32 s64, v194
	s_lshr_b32 s64, s64, 8
	s_lshl_b32 s0, s64, 8
	s_mov_b32 s1, 0
	s_add_i32 s65, s0, 0x100
	v_mov_b32_e32 v19, v18
	v_lshl_add_u64 v[172:173], v[12:13], 0, s[0:1]
	global_load_dwordx4 v[176:179], v[172:173], off offset:1072
	global_load_dwordx4 v[180:183], v[172:173], off offset:1056
	global_load_dwordx4 v[184:187], v[172:173], off offset:1040
	global_load_dwordx4 v[188:191], v[172:173], off offset:1024
	global_load_dwordx4 v[140:143], v[172:173], off offset:1136
	global_load_dwordx4 v[144:147], v[172:173], off offset:1120
	global_load_dwordx4 v[148:151], v[172:173], off offset:1104
	global_load_dwordx4 v[152:155], v[172:173], off offset:1088
.LBB0_629:
	s_add_u32 s0, s0, 0x80
	s_addc_u32 s1, s1, 0
	s_waitcnt vmcnt(4)
	v_mov_b32_e32 v2, v176
	v_mov_b32_e32 v3, v177
	v_mov_b32_e32 v4, v178
	v_mov_b32_e32 v5, v179
	v_mov_b32_e32 v6, v180
	v_mov_b32_e32 v7, v181
	v_mov_b32_e32 v8, v182
	v_mov_b32_e32 v9, v183
	v_mov_b32_e32 v20, v184
	v_mov_b32_e32 v21, v185
	v_mov_b32_e32 v22, v186
	v_mov_b32_e32 v23, v187
	v_mov_b32_e32 v24, v188
	v_mov_b32_e32 v25, v189
	v_mov_b32_e32 v26, v190
	v_mov_b32_e32 v27, v191
	v_lshl_add_u64 v[172:173], v[12:13], 0, s[0:1]
	global_load_dwordx4 v[176:179], v[172:173], off offset:1072
	global_load_dwordx4 v[180:183], v[172:173], off offset:1056
	global_load_dwordx4 v[184:187], v[172:173], off offset:1040
	global_load_dwordx4 v[188:191], v[172:173], off offset:1024
	s_cmp_lg_u32 s0, s65
	v_lshlrev_b32_e32 v0, 16, v24
	v_mul_f32_e32 v17, v0, v0
	v_fmamk_f32 v17, v17, 0xbdd2d3e7, v129
	v_mul_f32_e32 v17, v17, v0
	v_exp_f32_e32 v17, v17
	v_and_b32_e32 v40, 0xffff0000, v27
	v_add_f32_e32 v17, 1.0, v17
	v_rcp_f32_e32 v17, v17
	s_nop 0
	v_mul_f32_e32 v29, v17, v0
	v_and_b32_e32 v0, 0xffff0000, v24
	v_mul_f32_e32 v17, v0, v0
	v_fmamk_f32 v17, v17, 0xbdd2d3e7, v129
	v_mul_f32_e32 v17, v17, v0
	v_exp_f32_e32 v17, v17
	v_mul_f32_e32 v28, v29, v29
	v_add_f32_e32 v17, 1.0, v17
	v_rcp_f32_e32 v17, v17
	s_nop 0
	v_mul_f32_e32 v33, v17, v0
	v_lshlrev_b32_e32 v0, 16, v25
	v_mul_f32_e32 v17, v0, v0
	v_fmamk_f32 v17, v17, 0xbdd2d3e7, v129
	v_mul_f32_e32 v17, v17, v0
	v_exp_f32_e32 v17, v17
	v_mul_f32_e32 v32, v33, v33
	v_add_f32_e32 v17, 1.0, v17
	v_rcp_f32_e32 v17, v17
	s_nop 0
	v_mul_f32_e32 v35, v17, v0
	v_and_b32_e32 v0, 0xffff0000, v25
	v_mul_f32_e32 v17, v0, v0
	v_fmamk_f32 v17, v17, 0xbdd2d3e7, v129
	v_mul_f32_e32 v17, v17, v0
	v_exp_f32_e32 v17, v17
	v_mul_f32_e32 v34, v35, v35
	v_add_f32_e32 v17, 1.0, v17
	v_rcp_f32_e32 v17, v17
	s_nop 0
	v_mul_f32_e32 v25, v17, v0
	v_lshlrev_b32_e32 v0, 16, v26
	v_mul_f32_e32 v17, v0, v0
	v_fmamk_f32 v17, v17, 0xbdd2d3e7, v129
	v_mul_f32_e32 v17, v17, v0
	v_exp_f32_e32 v17, v17
	v_mul_f32_e32 v24, v25, v25
	v_pk_add_f32 v[24:25], v[34:35], v[24:25]
	v_add_f32_e32 v17, 1.0, v17
	v_rcp_f32_e32 v17, v17
	s_nop 0
	v_mul_f32_e32 v37, v17, v0
	v_and_b32_e32 v0, 0xffff0000, v26
	v_mul_f32_e32 v17, v0, v0
	v_fmamk_f32 v17, v17, 0xbdd2d3e7, v129
	v_mul_f32_e32 v17, v17, v0
	v_exp_f32_e32 v17, v17
	v_mul_f32_e32 v26, v40, v40
	v_fmamk_f32 v26, v26, 0xbdd2d3e7, v129
	v_mul_f32_e32 v26, v26, v40
	v_add_f32_e32 v17, 1.0, v17
	v_rcp_f32_e32 v17, v17
	v_exp_f32_e32 v26, v26
	v_mul_f32_e32 v39, v17, v0
	v_lshlrev_b32_e32 v0, 16, v27
	v_mul_f32_e32 v17, v0, v0
	v_fmamk_f32 v17, v17, 0xbdd2d3e7, v129
	v_mul_f32_e32 v17, v17, v0
	v_exp_f32_e32 v17, v17
	v_add_f32_e32 v26, 1.0, v26
	v_rcp_f32_e32 v41, v26
	v_pk_add_f32 v[26:27], v[28:29], v[32:33]
	v_add_f32_e32 v17, 1.0, v17
	v_rcp_f32_e32 v17, v17
	v_mul_f32_e32 v36, v37, v37
	v_mul_f32_e32 v38, v39, v39
	v_pk_add_f32 v[18:19], v[18:19], v[26:27]
	v_mul_f32_e32 v27, v41, v40
	v_pk_add_f32 v[18:19], v[18:19], v[24:25]
	v_pk_add_f32 v[24:25], v[36:37], v[38:39]
	v_mul_f32_e32 v26, v27, v27
	v_pk_add_f32 v[18:19], v[18:19], v[24:25]
	v_mul_f32_e32 v25, v17, v0
	v_lshlrev_b32_e32 v0, 16, v20
	v_mul_f32_e32 v17, v0, v0
	v_fmamk_f32 v17, v17, 0xbdd2d3e7, v129
	v_mul_f32_e32 v17, v17, v0
	v_exp_f32_e32 v17, v17
	v_mul_f32_e32 v24, v25, v25
	v_pk_add_f32 v[24:25], v[24:25], v[26:27]
	v_and_b32_e32 v36, 0xffff0000, v23
	v_add_f32_e32 v17, 1.0, v17
	v_rcp_f32_e32 v17, v17
	v_pk_add_f32 v[18:19], v[18:19], v[24:25]
	v_mul_f32_e32 v25, v17, v0
	v_and_b32_e32 v0, 0xffff0000, v20
	v_mul_f32_e32 v17, v0, v0
	v_fmamk_f32 v17, v17, 0xbdd2d3e7, v129
	v_mul_f32_e32 v17, v17, v0
	v_exp_f32_e32 v17, v17
	v_mul_f32_e32 v24, v25, v25
	v_add_f32_e32 v17, 1.0, v17
	v_rcp_f32_e32 v17, v17
	s_nop 0
	v_mul_f32_e32 v27, v17, v0
	v_lshlrev_b32_e32 v0, 16, v21
	v_mul_f32_e32 v17, v0, v0
	v_fmamk_f32 v17, v17, 0xbdd2d3e7, v129
	v_mul_f32_e32 v17, v17, v0
	v_exp_f32_e32 v17, v17
	v_mul_f32_e32 v26, v27, v27
	v_add_f32_e32 v17, 1.0, v17
	v_rcp_f32_e32 v17, v17
	s_nop 0
	v_mul_f32_e32 v29, v17, v0
	v_and_b32_e32 v0, 0xffff0000, v21
	v_mul_f32_e32 v17, v0, v0
	v_fmamk_f32 v17, v17, 0xbdd2d3e7, v129
	v_mul_f32_e32 v17, v17, v0
	v_exp_f32_e32 v17, v17
	v_mul_f32_e32 v28, v29, v29
	v_add_f32_e32 v17, 1.0, v17
	v_rcp_f32_e32 v17, v17
	s_nop 0
	v_mul_f32_e32 v21, v17, v0
	v_lshlrev_b32_e32 v0, 16, v22
	v_mul_f32_e32 v17, v0, v0
	v_fmamk_f32 v17, v17, 0xbdd2d3e7, v129
	v_mul_f32_e32 v17, v17, v0
	v_exp_f32_e32 v17, v17
	v_mul_f32_e32 v20, v21, v21
	v_pk_add_f32 v[20:21], v[28:29], v[20:21]
	v_add_f32_e32 v17, 1.0, v17
	v_rcp_f32_e32 v17, v17
	s_nop 0
	v_mul_f32_e32 v33, v17, v0
	v_and_b32_e32 v0, 0xffff0000, v22
	v_mul_f32_e32 v17, v0, v0
	v_fmamk_f32 v17, v17, 0xbdd2d3e7, v129
	v_mul_f32_e32 v17, v17, v0
	v_exp_f32_e32 v17, v17
	v_mul_f32_e32 v22, v36, v36
	v_fmamk_f32 v22, v22, 0xbdd2d3e7, v129
	v_mul_f32_e32 v22, v22, v36
	v_add_f32_e32 v17, 1.0, v17
	v_rcp_f32_e32 v17, v17
	v_exp_f32_e32 v22, v22
	v_mul_f32_e32 v35, v17, v0
	v_lshlrev_b32_e32 v0, 16, v23
	v_mul_f32_e32 v17, v0, v0
	v_fmamk_f32 v17, v17, 0xbdd2d3e7, v129
	v_mul_f32_e32 v17, v17, v0
	v_exp_f32_e32 v17, v17
	v_add_f32_e32 v22, 1.0, v22
	v_rcp_f32_e32 v37, v22
	v_pk_add_f32 v[22:23], v[24:25], v[26:27]
	v_add_f32_e32 v17, 1.0, v17
	v_rcp_f32_e32 v17, v17
	v_mul_f32_e32 v32, v33, v33
	v_mul_f32_e32 v34, v35, v35
	v_pk_add_f32 v[18:19], v[18:19], v[22:23]
	v_mul_f32_e32 v23, v37, v36
	v_pk_add_f32 v[18:19], v[18:19], v[20:21]
	v_pk_add_f32 v[20:21], v[32:33], v[34:35]
	v_mul_f32_e32 v22, v23, v23
	v_pk_add_f32 v[18:19], v[18:19], v[20:21]
	v_mul_f32_e32 v21, v17, v0
	v_lshlrev_b32_e32 v0, 16, v6
	v_mul_f32_e32 v17, v0, v0
	v_fmamk_f32 v17, v17, 0xbdd2d3e7, v129
	v_mul_f32_e32 v17, v17, v0
	v_exp_f32_e32 v17, v17
	v_mul_f32_e32 v20, v21, v21
	v_pk_add_f32 v[20:21], v[20:21], v[22:23]
	v_and_b32_e32 v32, 0xffff0000, v9
	v_add_f32_e32 v17, 1.0, v17
	v_rcp_f32_e32 v17, v17
	v_pk_add_f32 v[18:19], v[18:19], v[20:21]
	v_mul_f32_e32 v21, v17, v0
	v_and_b32_e32 v0, 0xffff0000, v6
	v_mul_f32_e32 v6, v0, v0
	v_fmamk_f32 v6, v6, 0xbdd2d3e7, v129
	v_mul_f32_e32 v6, v6, v0
	v_exp_f32_e32 v6, v6
	v_mul_f32_e32 v20, v21, v21
	v_add_f32_e32 v6, 1.0, v6
	v_rcp_f32_e32 v6, v6
	s_nop 0
	v_mul_f32_e32 v23, v6, v0
	v_lshlrev_b32_e32 v0, 16, v7
	v_mul_f32_e32 v6, v0, v0
	v_fmamk_f32 v6, v6, 0xbdd2d3e7, v129
	v_mul_f32_e32 v6, v6, v0
	v_exp_f32_e32 v6, v6
	v_mul_f32_e32 v22, v23, v23
	v_add_f32_e32 v6, 1.0, v6
	v_rcp_f32_e32 v6, v6
	s_nop 0
	v_mul_f32_e32 v25, v6, v0
	v_and_b32_e32 v0, 0xffff0000, v7
	v_mul_f32_e32 v6, v0, v0
	v_fmamk_f32 v6, v6, 0xbdd2d3e7, v129
	v_mul_f32_e32 v6, v6, v0
	v_exp_f32_e32 v6, v6
	v_mul_f32_e32 v24, v25, v25
	v_add_f32_e32 v6, 1.0, v6
	v_rcp_f32_e32 v6, v6
	s_nop 0
	v_mul_f32_e32 v7, v6, v0
	v_lshlrev_b32_e32 v0, 16, v8
	v_mul_f32_e32 v17, v0, v0
	v_fmamk_f32 v17, v17, 0xbdd2d3e7, v129
	v_mul_f32_e32 v17, v17, v0
	v_exp_f32_e32 v17, v17
	v_mul_f32_e32 v6, v7, v7
	v_pk_add_f32 v[6:7], v[24:25], v[6:7]
	v_add_f32_e32 v17, 1.0, v17
	v_rcp_f32_e32 v17, v17
	s_nop 0
	v_mul_f32_e32 v27, v17, v0
	v_and_b32_e32 v0, 0xffff0000, v8
	v_mul_f32_e32 v8, v0, v0
	v_fmamk_f32 v8, v8, 0xbdd2d3e7, v129
	v_mul_f32_e32 v8, v8, v0
	v_exp_f32_e32 v8, v8
	v_mul_f32_e32 v26, v27, v27
	v_add_f32_e32 v8, 1.0, v8
	v_rcp_f32_e32 v8, v8
	s_nop 0
	v_mul_f32_e32 v29, v8, v0
	v_lshlrev_b32_e32 v0, 16, v9
	v_mul_f32_e32 v8, v0, v0
	v_fmamk_f32 v8, v8, 0xbdd2d3e7, v129
	v_mul_f32_e32 v8, v8, v0
	v_exp_f32_e32 v8, v8
	v_mul_f32_e32 v28, v29, v29
	v_add_f32_e32 v8, 1.0, v8
	v_rcp_f32_e32 v17, v8
	v_mul_f32_e32 v8, v32, v32
	v_fmamk_f32 v8, v8, 0xbdd2d3e7, v129
	v_mul_f32_e32 v8, v8, v32
	v_exp_f32_e32 v8, v8
	s_nop 0
	v_add_f32_e32 v8, 1.0, v8
	v_rcp_f32_e32 v33, v8
	v_pk_add_f32 v[8:9], v[20:21], v[22:23]
	s_nop 0
	v_pk_add_f32 v[8:9], v[18:19], v[8:9]
	v_mul_f32_e32 v19, v33, v32
	v_pk_add_f32 v[6:7], v[8:9], v[6:7]
	v_pk_add_f32 v[8:9], v[26:27], v[28:29]
	v_mul_f32_e32 v18, v19, v19
	v_pk_add_f32 v[6:7], v[6:7], v[8:9]
	v_mul_f32_e32 v9, v17, v0
	v_mul_f32_e32 v8, v9, v9
	v_pk_add_f32 v[8:9], v[8:9], v[18:19]
	v_lshlrev_b32_e32 v0, 16, v2
	v_pk_add_f32 v[6:7], v[6:7], v[8:9]
	v_mul_f32_e32 v8, v0, v0
	v_fmamk_f32 v8, v8, 0xbdd2d3e7, v129
	v_mul_f32_e32 v8, v8, v0
	v_exp_f32_e32 v8, v8
	v_and_b32_e32 v26, 0xffff0000, v5
	v_add_f32_e32 v8, 1.0, v8
	v_rcp_f32_e32 v8, v8
	s_nop 0
	v_mul_f32_e32 v9, v8, v0
	v_and_b32_e32 v0, 0xffff0000, v2
	v_mul_f32_e32 v2, v0, v0
	v_fmamk_f32 v2, v2, 0xbdd2d3e7, v129
	v_mul_f32_e32 v2, v2, v0
	v_exp_f32_e32 v2, v2
	v_mul_f32_e32 v8, v9, v9
	v_add_f32_e32 v2, 1.0, v2
	v_rcp_f32_e32 v2, v2
	s_nop 0
	v_mul_f32_e32 v19, v2, v0
	v_lshlrev_b32_e32 v0, 16, v3
	v_mul_f32_e32 v2, v0, v0
	v_fmamk_f32 v2, v2, 0xbdd2d3e7, v129
	v_mul_f32_e32 v2, v2, v0
	v_exp_f32_e32 v2, v2
	v_mul_f32_e32 v18, v19, v19
	v_add_f32_e32 v2, 1.0, v2
	v_rcp_f32_e32 v2, v2
	s_nop 0
	v_mul_f32_e32 v21, v2, v0
	v_and_b32_e32 v0, 0xffff0000, v3
	v_mul_f32_e32 v2, v0, v0
	v_fmamk_f32 v2, v2, 0xbdd2d3e7, v129
	v_mul_f32_e32 v2, v2, v0
	v_exp_f32_e32 v2, v2
	v_mul_f32_e32 v20, v21, v21
	v_add_f32_e32 v2, 1.0, v2
	v_rcp_f32_e32 v2, v2
	s_nop 0
	v_mul_f32_e32 v3, v2, v0
	v_lshlrev_b32_e32 v0, 16, v4
	v_mul_f32_e32 v17, v0, v0
	v_fmamk_f32 v17, v17, 0xbdd2d3e7, v129
	v_mul_f32_e32 v17, v17, v0
	v_exp_f32_e32 v17, v17
	v_mul_f32_e32 v2, v3, v3
	v_pk_add_f32 v[2:3], v[20:21], v[2:3]
	v_add_f32_e32 v17, 1.0, v17
	v_rcp_f32_e32 v17, v17
	s_nop 0
	v_mul_f32_e32 v23, v17, v0
	v_and_b32_e32 v0, 0xffff0000, v4
	v_mul_f32_e32 v4, v0, v0
	v_fmamk_f32 v4, v4, 0xbdd2d3e7, v129
	v_mul_f32_e32 v4, v4, v0
	v_exp_f32_e32 v4, v4
	v_mul_f32_e32 v22, v23, v23
	v_add_f32_e32 v4, 1.0, v4
	v_rcp_f32_e32 v4, v4
	s_nop 0
	v_mul_f32_e32 v25, v4, v0
	v_lshlrev_b32_e32 v0, 16, v5
	v_mul_f32_e32 v4, v0, v0
	v_fmamk_f32 v4, v4, 0xbdd2d3e7, v129
	v_mul_f32_e32 v4, v4, v0
	v_exp_f32_e32 v4, v4
	v_mul_f32_e32 v24, v25, v25
	v_add_f32_e32 v4, 1.0, v4
	v_rcp_f32_e32 v17, v4
	v_mul_f32_e32 v4, v26, v26
	v_fmamk_f32 v4, v4, 0xbdd2d3e7, v129
	v_mul_f32_e32 v4, v4, v26
	v_exp_f32_e32 v4, v4
	s_nop 0
	v_add_f32_e32 v4, 1.0, v4
	v_rcp_f32_e32 v27, v4
	v_pk_add_f32 v[4:5], v[8:9], v[18:19]
	s_nop 0
	v_pk_add_f32 v[4:5], v[6:7], v[4:5]
	v_mul_f32_e32 v7, v27, v26
	v_pk_add_f32 v[2:3], v[4:5], v[2:3]
	v_pk_add_f32 v[4:5], v[22:23], v[24:25]
	v_mul_f32_e32 v6, v7, v7
	v_pk_add_f32 v[2:3], v[2:3], v[4:5]
	v_mul_f32_e32 v5, v17, v0
	v_mul_f32_e32 v4, v5, v5
	v_pk_add_f32 v[4:5], v[4:5], v[6:7]
	s_nop 0
	v_pk_add_f32 v[26:27], v[2:3], v[4:5]
	s_waitcnt vmcnt(4)
	v_mov_b32_e32 v2, v140
	v_mov_b32_e32 v3, v141
	v_mov_b32_e32 v4, v142
	v_mov_b32_e32 v5, v143
	v_mov_b32_e32 v6, v144
	v_mov_b32_e32 v7, v145
	v_mov_b32_e32 v8, v146
	v_mov_b32_e32 v9, v147
	v_mov_b32_e32 v18, v148
	v_mov_b32_e32 v19, v149
	v_mov_b32_e32 v20, v150
	v_mov_b32_e32 v21, v151
	v_mov_b32_e32 v22, v152
	v_mov_b32_e32 v23, v153
	v_mov_b32_e32 v24, v154
	v_mov_b32_e32 v25, v155
	global_load_dwordx4 v[140:143], v[172:173], off offset:1136
	global_load_dwordx4 v[144:147], v[172:173], off offset:1120
	global_load_dwordx4 v[148:151], v[172:173], off offset:1104
	global_load_dwordx4 v[152:155], v[172:173], off offset:1088
	v_lshlrev_b32_e32 v0, 16, v22
	v_mul_f32_e32 v14, v0, v0
	v_fmamk_f32 v14, v14, 0xbdd2d3e7, v129
	v_mul_f32_e32 v14, v14, v0
	v_exp_f32_e32 v14, v14
	s_nop 0
	v_add_f32_e32 v14, 1.0, v14
	v_rcp_f32_e32 v14, v14
	s_nop 0
	v_mul_f32_e32 v15, v14, v0
	v_and_b32_e32 v0, 0xffff0000, v22
	v_mul_f32_e32 v14, v0, v0
	v_fmamk_f32 v14, v14, 0xbdd2d3e7, v129
	v_mul_f32_e32 v14, v14, v0
	v_exp_f32_e32 v14, v14
	s_nop 0
	v_add_f32_e32 v14, 1.0, v14
	v_rcp_f32_e32 v14, v14
	s_nop 0
	v_mul_f32_e32 v29, v14, v0
	v_lshlrev_b32_e32 v0, 16, v23
	v_mul_f32_e32 v17, v0, v0
	v_fmamk_f32 v17, v17, 0xbdd2d3e7, v129
	v_mul_f32_e32 v17, v17, v0
	v_exp_f32_e32 v17, v17
	v_mul_f32_e32 v14, v15, v15
	v_mul_f32_e32 v28, v29, v29
	v_pk_add_f32 v[14:15], v[14:15], v[28:29]
	v_add_f32_e32 v17, 1.0, v17
	v_rcp_f32_e32 v17, v17
	v_pk_add_f32 v[14:15], v[26:27], v[14:15]
	v_mul_f32_e32 v33, v17, v0
	v_and_b32_e32 v0, 0xffff0000, v23
	v_mul_f32_e32 v17, v0, v0
	v_fmamk_f32 v17, v17, 0xbdd2d3e7, v129
	v_mul_f32_e32 v17, v17, v0
	v_exp_f32_e32 v17, v17
	v_mul_f32_e32 v32, v33, v33
	v_add_f32_e32 v17, 1.0, v17
	v_rcp_f32_e32 v17, v17
	s_nop 0
	v_mul_f32_e32 v23, v17, v0
	v_lshlrev_b32_e32 v0, 16, v24
	v_mul_f32_e32 v17, v0, v0
	v_fmamk_f32 v17, v17, 0xbdd2d3e7, v129
	v_mul_f32_e32 v17, v17, v0
	v_exp_f32_e32 v17, v17
	v_mul_f32_e32 v22, v23, v23
	v_pk_add_f32 v[22:23], v[32:33], v[22:23]
	v_add_f32_e32 v17, 1.0, v17
	v_rcp_f32_e32 v17, v17
	v_pk_add_f32 v[14:15], v[14:15], v[22:23]
	v_mul_f32_e32 v35, v17, v0
	v_and_b32_e32 v0, 0xffff0000, v24
	v_mul_f32_e32 v17, v0, v0
	v_fmamk_f32 v17, v17, 0xbdd2d3e7, v129
	v_mul_f32_e32 v17, v17, v0
	v_exp_f32_e32 v17, v17
	v_and_b32_e32 v24, 0xffff0000, v25
	v_mul_f32_e32 v34, v35, v35
	v_add_f32_e32 v17, 1.0, v17
	v_rcp_f32_e32 v17, v17
	s_nop 0
	v_mul_f32_e32 v37, v17, v0
	v_lshlrev_b32_e32 v0, 16, v25
	v_mul_f32_e32 v17, v0, v0
	v_fmamk_f32 v17, v17, 0xbdd2d3e7, v129
	v_mul_f32_e32 v17, v17, v0
	v_exp_f32_e32 v17, v17
	v_mul_f32_e32 v36, v37, v37
	v_mul_f32_e32 v25, v24, v24
	v_fmamk_f32 v25, v25, 0xbdd2d3e7, v129
	v_add_f32_e32 v17, 1.0, v17
	v_rcp_f32_e32 v17, v17
	v_pk_add_f32 v[22:23], v[34:35], v[36:37]
	v_mul_f32_e32 v25, v25, v24
	v_pk_add_f32 v[14:15], v[14:15], v[22:23]
	v_mul_f32_e32 v23, v17, v0
	v_lshlrev_b32_e32 v0, 16, v18
	v_mul_f32_e32 v17, v0, v0
	v_fmamk_f32 v17, v17, 0xbdd2d3e7, v129
	v_exp_f32_e32 v25, v25
	v_mul_f32_e32 v17, v17, v0
	v_exp_f32_e32 v17, v17
	v_add_f32_e32 v25, 1.0, v25
	v_rcp_f32_e32 v25, v25
	v_mul_f32_e32 v22, v23, v23
	v_add_f32_e32 v17, 1.0, v17
	v_rcp_f32_e32 v17, v17
	v_mul_f32_e32 v25, v25, v24
	v_mul_f32_e32 v24, v25, v25
	v_pk_add_f32 v[22:23], v[22:23], v[24:25]
	v_and_b32_e32 v34, 0xffff0000, v21
	v_pk_add_f32 v[14:15], v[14:15], v[22:23]
	v_mul_f32_e32 v23, v17, v0
	v_and_b32_e32 v0, 0xffff0000, v18
	v_mul_f32_e32 v17, v0, v0
	v_fmamk_f32 v17, v17, 0xbdd2d3e7, v129
	v_mul_f32_e32 v17, v17, v0
	v_exp_f32_e32 v17, v17
	v_mul_f32_e32 v22, v23, v23
	v_add_f32_e32 v17, 1.0, v17
	v_rcp_f32_e32 v17, v17
	s_nop 0
	v_mul_f32_e32 v25, v17, v0
	v_lshlrev_b32_e32 v0, 16, v19
	v_mul_f32_e32 v17, v0, v0
	v_fmamk_f32 v17, v17, 0xbdd2d3e7, v129
	v_mul_f32_e32 v17, v17, v0
	v_exp_f32_e32 v17, v17
	v_mul_f32_e32 v24, v25, v25
	v_add_f32_e32 v17, 1.0, v17
	v_rcp_f32_e32 v17, v17
	s_nop 0
	v_mul_f32_e32 v27, v17, v0
	v_and_b32_e32 v0, 0xffff0000, v19
	v_mul_f32_e32 v17, v0, v0
	v_fmamk_f32 v17, v17, 0xbdd2d3e7, v129
	v_mul_f32_e32 v17, v17, v0
	v_exp_f32_e32 v17, v17
	v_mul_f32_e32 v26, v27, v27
	v_add_f32_e32 v17, 1.0, v17
	v_rcp_f32_e32 v17, v17
	s_nop 0
	v_mul_f32_e32 v19, v17, v0
	v_lshlrev_b32_e32 v0, 16, v20
	v_mul_f32_e32 v17, v0, v0
	v_fmamk_f32 v17, v17, 0xbdd2d3e7, v129
	v_mul_f32_e32 v17, v17, v0
	v_exp_f32_e32 v17, v17
	v_mul_f32_e32 v18, v19, v19
	v_pk_add_f32 v[18:19], v[26:27], v[18:19]
	v_add_f32_e32 v17, 1.0, v17
	v_rcp_f32_e32 v17, v17
	s_nop 0
	v_mul_f32_e32 v29, v17, v0
	v_and_b32_e32 v0, 0xffff0000, v20
	v_mul_f32_e32 v17, v0, v0
	v_fmamk_f32 v17, v17, 0xbdd2d3e7, v129
	v_mul_f32_e32 v17, v17, v0
	v_exp_f32_e32 v17, v17
	v_mul_f32_e32 v20, v34, v34
	v_fmamk_f32 v20, v20, 0xbdd2d3e7, v129
	v_mul_f32_e32 v20, v20, v34
	v_add_f32_e32 v17, 1.0, v17
	v_rcp_f32_e32 v17, v17
	v_exp_f32_e32 v20, v20
	v_mul_f32_e32 v33, v17, v0
	v_lshlrev_b32_e32 v0, 16, v21
	v_mul_f32_e32 v17, v0, v0
	v_fmamk_f32 v17, v17, 0xbdd2d3e7, v129
	v_mul_f32_e32 v17, v17, v0
	v_exp_f32_e32 v17, v17
	v_add_f32_e32 v20, 1.0, v20
	v_rcp_f32_e32 v35, v20
	v_pk_add_f32 v[20:21], v[22:23], v[24:25]
	v_add_f32_e32 v17, 1.0, v17
	v_rcp_f32_e32 v17, v17
	v_mul_f32_e32 v28, v29, v29
	v_mul_f32_e32 v32, v33, v33
	v_pk_add_f32 v[14:15], v[14:15], v[20:21]
	v_mul_f32_e32 v21, v35, v34
	v_pk_add_f32 v[14:15], v[14:15], v[18:19]
	v_pk_add_f32 v[18:19], v[28:29], v[32:33]
	v_mul_f32_e32 v20, v21, v21
	v_pk_add_f32 v[14:15], v[14:15], v[18:19]
	v_mul_f32_e32 v19, v17, v0
	v_lshlrev_b32_e32 v0, 16, v6
	v_mul_f32_e32 v17, v0, v0
	v_fmamk_f32 v17, v17, 0xbdd2d3e7, v129
	v_mul_f32_e32 v17, v17, v0
	v_exp_f32_e32 v17, v17
	v_mul_f32_e32 v18, v19, v19
	v_pk_add_f32 v[18:19], v[18:19], v[20:21]
	v_and_b32_e32 v28, 0xffff0000, v9
	v_add_f32_e32 v17, 1.0, v17
	v_rcp_f32_e32 v17, v17
	v_pk_add_f32 v[14:15], v[14:15], v[18:19]
	v_mul_f32_e32 v19, v17, v0
	v_and_b32_e32 v0, 0xffff0000, v6
	v_mul_f32_e32 v6, v0, v0
	v_fmamk_f32 v6, v6, 0xbdd2d3e7, v129
	v_mul_f32_e32 v6, v6, v0
	v_exp_f32_e32 v6, v6
	v_mul_f32_e32 v18, v19, v19
	v_add_f32_e32 v6, 1.0, v6
	v_rcp_f32_e32 v6, v6
	s_nop 0
	v_mul_f32_e32 v21, v6, v0
	v_lshlrev_b32_e32 v0, 16, v7
	v_mul_f32_e32 v6, v0, v0
	v_fmamk_f32 v6, v6, 0xbdd2d3e7, v129
	v_mul_f32_e32 v6, v6, v0
	v_exp_f32_e32 v6, v6
	v_mul_f32_e32 v20, v21, v21
	v_add_f32_e32 v6, 1.0, v6
	v_rcp_f32_e32 v6, v6
	s_nop 0
	v_mul_f32_e32 v23, v6, v0
	v_and_b32_e32 v0, 0xffff0000, v7
	v_mul_f32_e32 v6, v0, v0
	v_fmamk_f32 v6, v6, 0xbdd2d3e7, v129
	v_mul_f32_e32 v6, v6, v0
	v_exp_f32_e32 v6, v6
	v_mul_f32_e32 v22, v23, v23
	v_add_f32_e32 v6, 1.0, v6
	v_rcp_f32_e32 v6, v6
	s_nop 0
	v_mul_f32_e32 v7, v6, v0
	v_lshlrev_b32_e32 v0, 16, v8
	v_mul_f32_e32 v17, v0, v0
	v_fmamk_f32 v17, v17, 0xbdd2d3e7, v129
	v_mul_f32_e32 v17, v17, v0
	v_exp_f32_e32 v17, v17
	v_mul_f32_e32 v6, v7, v7
	v_pk_add_f32 v[6:7], v[22:23], v[6:7]
	v_add_f32_e32 v17, 1.0, v17
	v_rcp_f32_e32 v17, v17
	s_nop 0
	v_mul_f32_e32 v25, v17, v0
	v_and_b32_e32 v0, 0xffff0000, v8
	v_mul_f32_e32 v8, v0, v0
	v_fmamk_f32 v8, v8, 0xbdd2d3e7, v129
	v_mul_f32_e32 v8, v8, v0
	v_exp_f32_e32 v8, v8
	v_mul_f32_e32 v24, v25, v25
	v_add_f32_e32 v8, 1.0, v8
	v_rcp_f32_e32 v8, v8
	s_nop 0
	v_mul_f32_e32 v27, v8, v0
	v_lshlrev_b32_e32 v0, 16, v9
	v_mul_f32_e32 v8, v0, v0
	v_fmamk_f32 v8, v8, 0xbdd2d3e7, v129
	v_mul_f32_e32 v8, v8, v0
	v_exp_f32_e32 v8, v8
	v_mul_f32_e32 v26, v27, v27
	v_add_f32_e32 v8, 1.0, v8
	v_rcp_f32_e32 v17, v8
	v_mul_f32_e32 v8, v28, v28
	v_fmamk_f32 v8, v8, 0xbdd2d3e7, v129
	v_mul_f32_e32 v8, v8, v28
	v_exp_f32_e32 v8, v8
	s_nop 0
	v_add_f32_e32 v8, 1.0, v8
	v_rcp_f32_e32 v29, v8
	v_pk_add_f32 v[8:9], v[18:19], v[20:21]
	s_nop 0
	v_pk_add_f32 v[8:9], v[14:15], v[8:9]
	v_mul_f32_e32 v15, v29, v28
	v_pk_add_f32 v[6:7], v[8:9], v[6:7]
	v_pk_add_f32 v[8:9], v[24:25], v[26:27]
	v_mul_f32_e32 v14, v15, v15
	v_pk_add_f32 v[6:7], v[6:7], v[8:9]
	v_mul_f32_e32 v9, v17, v0
	v_mul_f32_e32 v8, v9, v9
	v_pk_add_f32 v[8:9], v[8:9], v[14:15]
	v_lshlrev_b32_e32 v0, 16, v2
	v_pk_add_f32 v[6:7], v[6:7], v[8:9]
	v_mul_f32_e32 v8, v0, v0
	v_fmamk_f32 v8, v8, 0xbdd2d3e7, v129
	v_mul_f32_e32 v8, v8, v0
	v_exp_f32_e32 v8, v8
	v_and_b32_e32 v24, 0xffff0000, v5
	v_add_f32_e32 v8, 1.0, v8
	v_rcp_f32_e32 v8, v8
	s_nop 0
	v_mul_f32_e32 v9, v8, v0
	v_and_b32_e32 v0, 0xffff0000, v2
	v_mul_f32_e32 v2, v0, v0
	v_fmamk_f32 v2, v2, 0xbdd2d3e7, v129
	v_mul_f32_e32 v2, v2, v0
	v_exp_f32_e32 v2, v2
	v_mul_f32_e32 v8, v9, v9
	v_add_f32_e32 v2, 1.0, v2
	v_rcp_f32_e32 v2, v2
	s_nop 0
	v_mul_f32_e32 v15, v2, v0
	v_lshlrev_b32_e32 v0, 16, v3
	v_mul_f32_e32 v2, v0, v0
	v_fmamk_f32 v2, v2, 0xbdd2d3e7, v129
	v_mul_f32_e32 v2, v2, v0
	v_exp_f32_e32 v2, v2
	v_mul_f32_e32 v14, v15, v15
	v_add_f32_e32 v2, 1.0, v2
	v_rcp_f32_e32 v2, v2
	s_nop 0
	v_mul_f32_e32 v19, v2, v0
	v_and_b32_e32 v0, 0xffff0000, v3
	v_mul_f32_e32 v2, v0, v0
	v_fmamk_f32 v2, v2, 0xbdd2d3e7, v129
	v_mul_f32_e32 v2, v2, v0
	v_exp_f32_e32 v2, v2
	v_mul_f32_e32 v18, v19, v19
	v_add_f32_e32 v2, 1.0, v2
	v_rcp_f32_e32 v2, v2
	s_nop 0
	v_mul_f32_e32 v3, v2, v0
	v_lshlrev_b32_e32 v0, 16, v4
	v_mul_f32_e32 v17, v0, v0
	v_fmamk_f32 v17, v17, 0xbdd2d3e7, v129
	v_mul_f32_e32 v17, v17, v0
	v_exp_f32_e32 v17, v17
	v_mul_f32_e32 v2, v3, v3
	v_pk_add_f32 v[2:3], v[18:19], v[2:3]
	v_add_f32_e32 v17, 1.0, v17
	v_rcp_f32_e32 v17, v17
	s_nop 0
	v_mul_f32_e32 v21, v17, v0
	v_and_b32_e32 v0, 0xffff0000, v4
	v_mul_f32_e32 v4, v0, v0
	v_fmamk_f32 v4, v4, 0xbdd2d3e7, v129
	v_mul_f32_e32 v4, v4, v0
	v_exp_f32_e32 v4, v4
	v_mul_f32_e32 v20, v21, v21
	v_add_f32_e32 v4, 1.0, v4
	v_rcp_f32_e32 v4, v4
	s_nop 0
	v_mul_f32_e32 v23, v4, v0
	v_lshlrev_b32_e32 v0, 16, v5
	v_mul_f32_e32 v4, v0, v0
	v_fmamk_f32 v4, v4, 0xbdd2d3e7, v129
	v_mul_f32_e32 v4, v4, v0
	v_exp_f32_e32 v4, v4
	v_mul_f32_e32 v22, v23, v23
	v_add_f32_e32 v4, 1.0, v4
	v_rcp_f32_e32 v17, v4
	v_mul_f32_e32 v4, v24, v24
	v_fmamk_f32 v4, v4, 0xbdd2d3e7, v129
	v_mul_f32_e32 v4, v4, v24
	v_exp_f32_e32 v4, v4
	s_nop 0
	v_add_f32_e32 v4, 1.0, v4
	v_rcp_f32_e32 v25, v4
	v_pk_add_f32 v[4:5], v[8:9], v[14:15]
	s_nop 0
	v_pk_add_f32 v[4:5], v[6:7], v[4:5]
	v_mul_f32_e32 v7, v25, v24
	v_pk_add_f32 v[2:3], v[4:5], v[2:3]
	v_pk_add_f32 v[4:5], v[20:21], v[22:23]
	v_mul_f32_e32 v6, v7, v7
	v_pk_add_f32 v[2:3], v[2:3], v[4:5]
	v_mul_f32_e32 v5, v17, v0
	v_mul_f32_e32 v4, v5, v5
	v_pk_add_f32 v[4:5], v[4:5], v[6:7]
	s_nop 0
	v_pk_add_f32 v[18:19], v[2:3], v[4:5]
	s_cbranch_scc1 .LBB0_629
	v_and_b32_e32 v171, 0xff, v194
	v_lshlrev_b32_e32 v171, 3, v171
	s_mul_i32 s66, s64, 0x12000
	s_add_i32 s66, s66, 0x11000
	s_xor_b32 s67, s64, 1
	s_mul_i32 s67, s67, 0x12000
	s_add_i32 s67, s67, 0x11000
	v_add_u32_e32 v172, s66, v171
	v_add_u32_e32 v173, s67, v171
	ds_write_b64 v172, v[18:19]
	s_waitcnt lgkmcnt(0)
	s_barrier
	ds_read_b64 v[174:175], v173
	s_waitcnt lgkmcnt(0)
	v_add_f32_e32 v18, v18, v174
	v_add_f32_e32 v19, v19, v175
	s_mov_b32 s9, s89
	v_lshl_add_u64 v[2:3], v[10:11], 0, s[8:9]
	v_lshlrev_b32_e32 v0, 7, v16
	v_lshl_add_u64 v[22:23], v[2:3], 0, v[0:1]
	global_load_dwordx4 v[10:13], v[22:23], off offset:1024
	v_lshlrev_b32_e32 v20, 8, v16
	global_load_dwordx2 v[28:29], v20, s[16:17]
	global_load_dwordx2 v[36:37], v20, s[20:21]
	global_load_dwordx2 v[40:41], v20, s[16:17] offset:16
	global_load_dwordx2 v[42:43], v20, s[16:17] offset:32
	global_load_dwordx2 v[24:25], v20, s[16:17] offset:48
	global_load_dwordx2 v[44:45], v20, s[20:21] offset:16
	global_load_dwordx2 v[46:47], v20, s[20:21] offset:32
	global_load_dwordx2 v[26:27], v20, s[20:21] offset:48
	v_lshlrev_b32_e32 v34, 6, v16
	v_mul_u32_u24_e32 v4, 0x4400, v16
	global_load_dwordx4 v[14:17], v[22:23], off offset:1040
	ds_bpermute_b32 v3, v80, v19
	ds_bpermute_b32 v2, v80, v18
	s_mov_b32 s0, 0x3b000000
	v_lshlrev_b32_e32 v33, 1, v31
	v_add3_u32 v38, s15, v4, v33
	v_or_b32_e32 v4, 1, v34
	s_waitcnt lgkmcnt(0)
	v_pk_add_f32 v[2:3], v[18:19], v[2:3]
	v_mul_u32_u24_e32 v39, 0x110, v4
	v_pk_mul_f32 v[18:19], v[2:3], s[0:1] op_sel_hi:[1,0]
	v_or_b32_e32 v78, 7, v34
	v_fma_f32 v2, -v19, v19, v18
	v_max_f32_e32 v2, 0, v2
	v_add_f32_e32 v2, 0x358637bd, v2
	v_mul_f32_e32 v3, 0x4b800000, v2
	v_cmp_gt_f32_e32 vcc, s69, v2
	v_add3_u32 v18, s15, v39, v33
	v_or_b32_e32 v80, 10, v34
	v_cndmask_b32_e32 v2, v2, v3, vcc
	v_rsq_f32_e32 v48, v2
	global_load_dwordx4 v[2:5], v[22:23], off offset:1072
	global_load_dwordx4 v[6:9], v[22:23], off offset:1056
	v_or_b32_e32 v79, 11, v34
	v_readlane_b32 s40, v251, 22
	v_mul_f32_e32 v39, 0x45800000, v48
	v_cndmask_b32_e32 v39, v48, v39, vcc
	v_readlane_b32 s41, v251, 23
	v_mov_b32_e32 v21, v1
	v_mul_u32_u24_e32 v83, 0x110, v31
	v_add3_u32 v0, s15, v83, v0
	v_or_b32_e32 v100, 31, v34
	v_cmp_gt_u32_e32 vcc, v31, v34
	v_or_b32_e32 v35, 4, v34
	v_and_b32_e32 v32, 15, v50
	v_readlane_b32 s42, v251, 24
	v_readlane_b32 s43, v251, 25
	v_readlane_b32 s44, v251, 26
	v_readlane_b32 s45, v251, 27
	v_readlane_b32 s46, v251, 28
	v_readlane_b32 s47, v251, 29
	v_readlane_b32 s48, v251, 30
	v_readlane_b32 s49, v251, 31
	v_readlane_b32 s50, v251, 32
	v_readlane_b32 s51, v251, 33
	v_readlane_b32 s52, v251, 34
	v_readlane_b32 s53, v251, 35
	v_readlane_b32 s54, v251, 36
	v_readlane_b32 s55, v251, 37
	s_mov_b32 s2, 0x1f000
	s_waitcnt vmcnt(11)
	v_lshlrev_b32_e32 v48, 16, v10
	v_and_b32_e32 v10, 0xffff0000, v10
	v_lshlrev_b32_e32 v49, 16, v11
	v_and_b32_e32 v11, 0xffff0000, v11
	v_mul_f32_e32 v52, v48, v48
	v_mul_f32_e32 v53, v10, v10
	v_mul_f32_e32 v55, v11, v11
	v_fmamk_f32 v52, v52, 0xbdd2d3e7, v129
	v_fmamk_f32 v53, v53, 0xbdd2d3e7, v129
	v_fmamk_f32 v55, v55, 0xbdd2d3e7, v129
	v_mul_f32_e32 v52, v52, v48
	v_mul_f32_e32 v53, v53, v10
	v_mul_f32_e32 v55, v55, v11
	v_exp_f32_e32 v52, v52
	v_exp_f32_e32 v53, v53
	v_exp_f32_e32 v55, v55
	v_lshlrev_b32_e32 v51, 16, v12
	v_add_f32_e32 v52, 1.0, v52
	v_add_f32_e32 v53, 1.0, v53
	v_add_f32_e32 v55, 1.0, v55
	v_rcp_f32_e32 v52, v52
	v_mul_f32_e32 v56, v51, v51
	v_rcp_f32_e32 v53, v53
	v_rcp_f32_e32 v55, v55
	v_fmamk_f32 v56, v56, 0xbdd2d3e7, v129
	v_mul_f32_e32 v56, v56, v51
	v_fma_f32 v48, v52, v48, -v19
	v_and_b32_e32 v12, 0xffff0000, v12
	v_fma_f32 v10, v53, v10, -v19
	v_fma_f32 v11, v55, v11, -v19
	v_mul_f32_e32 v48, v39, v48
	v_mul_f32_e32 v57, 0x3d372713, v12
	v_exp_f32_e32 v56, v56
	v_mul_f32_e32 v10, v39, v10
	v_mul_f32_e32 v59, v39, v11
	s_waitcnt vmcnt(9)
	v_fma_f32 v11, v28, v48, v36
	v_mul_f32_e32 v57, v57, v12
	v_fmac_f32_e32 v37, v29, v10
	v_cvt_pk_bf16_f32 v10, v11, s0
	v_cvt_pk_bf16_f32 v11, v37, s0
	ds_write_b16 v38, v10 offset:34816
	ds_write_b16 v18, v11 offset:34816
	v_fma_f32 v10, v57, v12, v12
	v_mul_f32_e32 v10, 0xbfcc422a, v10
	v_lshlrev_b32_e32 v28, 16, v13
	v_add_f32_e32 v56, 1.0, v56
	v_mul_f32_e32 v10, 0x3fb8aa3b, v10
	v_mul_f32_e32 v29, v28, v28
	v_rcp_f32_e32 v56, v56
	v_exp_f32_e32 v10, v10
	v_fmamk_f32 v29, v29, 0xbdd2d3e7, v129
	v_mul_f32_e32 v29, v29, v28
	v_fma_f32 v51, v56, v51, -v19
	v_add_f32_e32 v10, 1.0, v10
	v_exp_f32_e32 v29, v29
	v_mul_f32_e32 v11, v39, v51
	v_rcp_f32_e32 v10, v10
	s_waitcnt vmcnt(5)
	v_fma_f32 v11, v40, v11, v44
	v_cvt_pk_bf16_f32 v11, v11, s0
	ds_write_b16 v18, v11 offset:35632
	v_add_f32_e32 v11, 1.0, v29
	v_fma_f32 v10, v10, v12, -v19
	v_rcp_f32_e32 v11, v11
	v_mul_f32_e32 v10, v39, v10
	v_fmac_f32_e32 v45, v10, v41
	v_cvt_pk_bf16_f32 v10, v45, s0
	ds_write_b16 v18, v10 offset:35904
	v_fma_f32 v10, v11, v28, -v19
	v_and_b32_e32 v11, 0xffff0000, v13
	v_mul_f32_e32 v12, v11, v11
	v_fmamk_f32 v12, v12, 0xbdd2d3e7, v129
	v_mul_f32_e32 v12, v12, v11
	v_exp_f32_e32 v12, v12
	s_waitcnt vmcnt(2)
	v_lshlrev_b32_e32 v13, 16, v14
	v_mul_f32_e32 v28, v13, v13
	v_fmamk_f32 v28, v28, 0xbdd2d3e7, v129
	v_add_f32_e32 v12, 1.0, v12
	v_rcp_f32_e32 v12, v12
	v_mul_f32_e32 v28, v28, v13
	v_fma_f32 v11, v12, v11, -v19
	v_exp_f32_e32 v28, v28
	v_mul_f32_e32 v44, v39, v11
	v_and_b32_e32 v11, 0xffff0000, v14
	v_mul_f32_e32 v12, v11, v11
	v_fmamk_f32 v12, v12, 0xbdd2d3e7, v129
	v_mul_f32_e32 v12, v12, v11
	v_mul_f32_e32 v45, v39, v10
	v_add_f32_e32 v10, 1.0, v28
	v_rcp_f32_e32 v10, v10
	v_exp_f32_e32 v12, v12
	v_lshlrev_b32_e32 v29, 16, v16
	v_fma_f32 v10, v10, v13, -v19
	v_lshlrev_b32_e32 v13, 16, v15
	v_add_f32_e32 v12, 1.0, v12
	v_mul_f32_e32 v14, v13, v13
	v_rcp_f32_e32 v12, v12
	v_fmamk_f32 v14, v14, 0xbdd2d3e7, v129
	v_mul_f32_e32 v10, v39, v10
	v_mul_f32_e32 v14, v14, v13
	v_fma_f32 v10, v42, v10, v46
	v_cvt_pk_bf16_f32 v10, v10, s0
	v_exp_f32_e32 v14, v14
	ds_write_b16 v18, v10 offset:36720
	v_fma_f32 v10, v12, v11, -v19
	v_mul_f32_e32 v10, v39, v10
	v_fmac_f32_e32 v47, v43, v10
	v_cvt_pk_bf16_f32 v10, v47, s0
	v_and_b32_e32 v15, 0xffff0000, v15
	v_add_f32_e32 v11, 1.0, v14
	ds_write_b16 v18, v10 offset:36992
	v_mul_f32_e32 v10, v15, v15
	v_rcp_f32_e32 v11, v11
	v_fmamk_f32 v10, v10, 0xbdd2d3e7, v129
	v_mul_f32_e32 v10, v10, v15
	v_fma_f32 v14, v11, v13, -v19
	v_exp_f32_e32 v28, v10
	global_load_dwordx2 v[10:11], v20, s[16:17] offset:64
	global_load_dwordx2 v[12:13], v20, s[20:21] offset:64
	v_mul_f32_e32 v37, v29, v29
	v_fmamk_f32 v37, v37, 0xbdd2d3e7, v129
	v_add_f32_e32 v28, 1.0, v28
	v_mul_f32_e32 v37, v37, v29
	v_rcp_f32_e32 v28, v28
	v_exp_f32_e32 v37, v37
	v_fma_f32 v15, v28, v15, -v19
	v_mul_f32_e32 v46, v39, v15
	v_and_b32_e32 v15, 0xffff0000, v16
	v_mul_f32_e32 v16, v15, v15
	v_mul_f32_e32 v47, v39, v14
	v_add_f32_e32 v14, 1.0, v37
	v_fmamk_f32 v16, v16, 0xbdd2d3e7, v129
	v_rcp_f32_e32 v14, v14
	v_mul_f32_e32 v16, v16, v15
	v_exp_f32_e32 v16, v16
	v_fma_f32 v14, v14, v29, -v19
	v_mul_f32_e32 v14, v39, v14
	v_fma_f32 v14, v24, v14, v26
	v_lshlrev_b32_e32 v24, 16, v17
	v_add_f32_e32 v16, 1.0, v16
	v_mul_f32_e32 v26, v24, v24
	v_rcp_f32_e32 v16, v16
	v_fmamk_f32 v26, v26, 0xbdd2d3e7, v129
	v_mul_f32_e32 v26, v26, v24
	v_cvt_pk_bf16_f32 v14, v14, s0
	v_exp_f32_e32 v26, v26
	ds_write_b16 v18, v14 offset:37808
	v_fma_f32 v14, v16, v15, -v19
	v_mul_f32_e32 v14, v39, v14
	v_fmac_f32_e32 v27, v14, v25
	v_cvt_pk_bf16_f32 v14, v27, s0
	v_and_b32_e32 v25, 0xffff0000, v17
	v_add_f32_e32 v15, 1.0, v26
	ds_write_b16 v18, v14 offset:38080
	v_mul_f32_e32 v14, v25, v25
	v_rcp_f32_e32 v15, v15
	v_fmamk_f32 v14, v14, 0xbdd2d3e7, v129
	v_mul_f32_e32 v14, v14, v25
	v_fma_f32 v24, v15, v24, -v19
	v_exp_f32_e32 v26, v14
	global_load_dwordx2 v[14:15], v20, s[16:17] offset:80
	global_load_dwordx2 v[16:17], v20, s[20:21] offset:80
	s_waitcnt vmcnt(4)
	v_lshlrev_b32_e32 v27, 16, v6
	v_mul_f32_e32 v28, v27, v27
	v_fmamk_f32 v28, v28, 0xbdd2d3e7, v129
	v_mul_f32_e32 v28, v28, v27
	v_exp_f32_e32 v28, v28
	v_mul_f32_e32 v55, v39, v24
	v_mul_f32_e32 v54, v49, v49
	v_fmamk_f32 v54, v54, 0xbdd2d3e7, v129
	v_add_f32_e32 v24, 1.0, v28
	v_rcp_f32_e32 v24, v24
	v_and_b32_e32 v6, 0xffff0000, v6
	v_mul_f32_e32 v54, v54, v49
	v_fma_f32 v24, v24, v27, -v19
	v_mul_f32_e32 v40, v39, v24
	v_mul_f32_e32 v24, v6, v6
	v_fmamk_f32 v24, v24, 0xbdd2d3e7, v129
	v_mul_f32_e32 v24, v24, v6
	v_exp_f32_e32 v54, v54
	v_exp_f32_e32 v41, v24
	v_add_f32_e32 v54, 1.0, v54
	v_add_f32_e32 v26, 1.0, v26
	v_rcp_f32_e32 v54, v54
	v_rcp_f32_e32 v26, v26
	s_waitcnt vmcnt(2)
	v_fma_f32 v10, v10, v40, v12
	v_lshlrev_b32_e32 v40, 16, v7
	v_add_f32_e32 v12, 1.0, v41
	v_mul_f32_e32 v41, v40, v40
	v_fmamk_f32 v41, v41, 0xbdd2d3e7, v129
	v_mul_f32_e32 v41, v41, v40
	v_fma_f32 v49, v54, v49, -v19
	v_fma_f32 v25, v26, v25, -v19
	v_mul_f32_e32 v65, v39, v49
	v_mul_f32_e32 v54, v39, v25
	global_load_dwordx2 v[24:25], v20, s[16:17] offset:96
	global_load_dwordx2 v[28:29], v20, s[16:17] offset:112
	global_load_dwordx2 v[26:27], v20, s[20:21] offset:96
	global_load_dwordx2 v[48:49], v20, s[20:21] offset:112
	v_exp_f32_e32 v41, v41
	v_rcp_f32_e32 v12, v12
	v_cvt_pk_bf16_f32 v10, v10, s0
	ds_write_b16 v18, v10 offset:38896
	v_add_f32_e32 v10, 1.0, v41
	v_fma_f32 v6, v12, v6, -v19
	v_rcp_f32_e32 v10, v10
	v_mul_f32_e32 v6, v39, v6
	v_fmac_f32_e32 v13, v11, v6
	v_cvt_pk_bf16_f32 v6, v13, s0
	v_and_b32_e32 v7, 0xffff0000, v7
	ds_write_b16 v18, v6 offset:39168
	v_fma_f32 v6, v10, v40, -v19
	v_mul_f32_e32 v10, v7, v7
	v_fmamk_f32 v10, v10, 0xbdd2d3e7, v129
	v_mul_f32_e32 v10, v10, v7
	v_exp_f32_e32 v10, v10
	v_lshlrev_b32_e32 v11, 16, v8
	v_mul_f32_e32 v12, v11, v11
	v_fmamk_f32 v12, v12, 0xbdd2d3e7, v129
	v_mul_f32_e32 v12, v12, v11
	v_add_f32_e32 v10, 1.0, v10
	v_rcp_f32_e32 v10, v10
	v_exp_f32_e32 v12, v12
	v_mul_f32_e32 v53, v39, v6
	v_fma_f32 v7, v10, v7, -v19
	v_mul_f32_e32 v52, v39, v7
	v_and_b32_e32 v7, 0xffff0000, v8
	v_add_f32_e32 v6, 1.0, v12
	v_mul_f32_e32 v8, v7, v7
	v_rcp_f32_e32 v6, v6
	v_fmamk_f32 v8, v8, 0xbdd2d3e7, v129
	v_mul_f32_e32 v8, v8, v7
	v_lshlrev_b32_e32 v10, 16, v9
	v_fma_f32 v6, v6, v11, -v19
	v_exp_f32_e32 v8, v8
	v_mul_f32_e32 v11, v10, v10
	v_fmamk_f32 v11, v11, 0xbdd2d3e7, v129
	v_mul_f32_e32 v11, v11, v10
	v_add_f32_e32 v8, 1.0, v8
	v_rcp_f32_e32 v8, v8
	v_exp_f32_e32 v11, v11
	v_mul_f32_e32 v6, v39, v6
	s_waitcnt vmcnt(4)
	v_fma_f32 v6, v14, v6, v16
	v_cvt_pk_bf16_f32 v6, v6, s0
	ds_write_b16 v18, v6 offset:39984
	v_fma_f32 v6, v8, v7, -v19
	v_add_f32_e32 v7, 1.0, v11
	v_rcp_f32_e32 v7, v7
	v_mul_f32_e32 v6, v39, v6
	v_fmac_f32_e32 v17, v6, v15
	v_cvt_pk_bf16_f32 v6, v17, s0
	ds_write_b16 v18, v6 offset:40256
	v_fma_f32 v6, v7, v10, -v19
	v_and_b32_e32 v7, 0xffff0000, v9
	v_lshlrev_b32_e32 v9, 16, v2
	v_mul_f32_e32 v10, v9, v9
	v_fmamk_f32 v10, v10, 0xbdd2d3e7, v129
	v_mul_f32_e32 v8, v7, v7
	v_mul_f32_e32 v10, v10, v9
	v_fmamk_f32 v8, v8, 0xbdd2d3e7, v129
	v_mul_f32_e32 v8, v8, v7
	v_exp_f32_e32 v10, v10
	v_exp_f32_e32 v8, v8
	v_mul_f32_e32 v58, v39, v6
	v_add_f32_e32 v6, 1.0, v10
	global_load_dwordx4 v[10:13], v[22:23], off offset:1104
	global_load_dwordx4 v[14:17], v[22:23], off offset:1088
	v_add_f32_e32 v8, 1.0, v8
	v_rcp_f32_e32 v8, v8
	v_and_b32_e32 v2, 0xffff0000, v2
	v_rcp_f32_e32 v6, v6
	v_or_b32_e32 v36, 8, v34
	v_fma_f32 v7, v8, v7, -v19
	v_mul_f32_e32 v56, v39, v7
	v_mul_f32_e32 v7, v2, v2
	v_fmamk_f32 v7, v7, 0xbdd2d3e7, v129
	v_mul_f32_e32 v7, v7, v2
	v_exp_f32_e32 v7, v7
	v_lshlrev_b32_e32 v8, 16, v3
	v_fma_f32 v6, v6, v9, -v19
	v_mul_f32_e32 v9, v8, v8
	v_add_f32_e32 v7, 1.0, v7
	v_rcp_f32_e32 v7, v7
	v_fmamk_f32 v9, v9, 0xbdd2d3e7, v129
	v_mul_f32_e32 v9, v9, v8
	v_fma_f32 v2, v7, v2, -v19
	v_mul_f32_e32 v6, v39, v6
	v_mul_f32_e32 v2, v39, v2
	s_waitcnt vmcnt(3)
	v_fma_f32 v6, v24, v6, v26
	v_exp_f32_e32 v9, v9
	v_fmac_f32_e32 v27, v25, v2
	v_cvt_pk_bf16_f32 v6, v6, s0
	v_cvt_pk_bf16_f32 v2, v27, s0
	ds_write_b16 v18, v6 offset:41072
	ds_write_b16 v18, v2 offset:41344
	global_load_dwordx2 v[24:25], v20, s[16:17] offset:128
	global_load_dwordx2 v[26:27], v20, s[20:21] offset:128
	v_add_f32_e32 v6, 1.0, v9
	v_rcp_f32_e32 v6, v6
	v_and_b32_e32 v3, 0xffff0000, v3
	v_lshlrev_b32_e32 v7, 16, v4
	v_or_b32_e32 v37, 12, v34
	v_fma_f32 v2, v6, v8, -v19
	v_mul_f32_e32 v6, v3, v3
	v_fmamk_f32 v6, v6, 0xbdd2d3e7, v129
	v_mul_f32_e32 v6, v6, v3
	v_exp_f32_e32 v6, v6
	v_mul_f32_e32 v8, v7, v7
	v_fmamk_f32 v8, v8, 0xbdd2d3e7, v129
	v_mul_f32_e32 v8, v8, v7
	v_add_f32_e32 v6, 1.0, v6
	v_rcp_f32_e32 v6, v6
	v_exp_f32_e32 v8, v8
	v_mul_f32_e32 v64, v39, v2
	v_fma_f32 v3, v6, v3, -v19
	v_mul_f32_e32 v63, v39, v3
	v_and_b32_e32 v3, 0xffff0000, v4
	v_add_f32_e32 v2, 1.0, v8
	v_mul_f32_e32 v4, v3, v3
	v_rcp_f32_e32 v2, v2
	v_fmamk_f32 v4, v4, 0xbdd2d3e7, v129
	v_mul_f32_e32 v4, v4, v3
	v_fma_f32 v2, v2, v7, -v19
	v_exp_f32_e32 v4, v4
	v_mul_f32_e32 v2, v39, v2
	s_waitcnt vmcnt(4)
	v_fma_f32 v2, v28, v2, v48
	v_cvt_pk_bf16_f32 v2, v2, s0
	ds_write_b16 v18, v2 offset:42160
	v_add_f32_e32 v2, 1.0, v4
	v_lshlrev_b32_e32 v4, 16, v5
	v_mul_f32_e32 v6, v4, v4
	v_fmamk_f32 v6, v6, 0xbdd2d3e7, v129
	v_rcp_f32_e32 v2, v2
	v_mul_f32_e32 v6, v6, v4
	v_exp_f32_e32 v6, v6
	v_fma_f32 v2, v2, v3, -v19
	v_mul_f32_e32 v2, v39, v2
	v_fmac_f32_e32 v49, v2, v29
	v_add_f32_e32 v2, 1.0, v6
	v_cvt_pk_bf16_f32 v6, v49, s0
	ds_write_b16 v18, v6 offset:42432
	global_load_dwordx2 v[60:61], v20, s[16:17] offset:144
	global_load_dwordx2 v[66:67], v20, s[20:21] offset:144
	v_and_b32_e32 v3, 0xffff0000, v5
	v_mul_f32_e32 v5, v3, v3
	v_fmamk_f32 v5, v5, 0xbdd2d3e7, v129
	v_mul_f32_e32 v5, v5, v3
	v_rcp_f32_e32 v2, v2
	v_exp_f32_e32 v5, v5
	s_waitcnt vmcnt(4)
	v_lshlrev_b32_e32 v28, 16, v14
	v_and_b32_e32 v14, 0xffff0000, v14
	v_fma_f32 v2, v2, v4, -v19
	v_add_f32_e32 v4, 1.0, v5
	v_mul_f32_e32 v5, v28, v28
	v_fmamk_f32 v5, v5, 0xbdd2d3e7, v129
	v_mul_f32_e32 v5, v5, v28
	v_rcp_f32_e32 v4, v4
	v_exp_f32_e32 v5, v5
	v_mul_f32_e32 v69, v39, v2
	v_fma_f32 v2, v4, v3, -v19
	v_mul_f32_e32 v68, v39, v2
	v_add_f32_e32 v2, 1.0, v5
	v_rcp_f32_e32 v29, v2
	global_load_dwordx4 v[2:5], v[22:23], off offset:1136
	global_load_dwordx4 v[6:9], v[22:23], off offset:1120
	v_or_b32_e32 v38, 16, v34
	v_or_b32_e32 v40, 20, v34
	v_fma_f32 v22, v29, v28, -v19
	v_mul_f32_e32 v48, v39, v22
	v_mul_f32_e32 v22, v14, v14
	v_fmamk_f32 v22, v22, 0xbdd2d3e7, v129
	v_mul_f32_e32 v22, v22, v14
	v_exp_f32_e32 v49, v22
	global_load_dwordx2 v[74:75], v20, s[16:17] offset:160
	global_load_dwordx2 v[22:23], v20, s[16:17] offset:176
	global_load_dwordx2 v[76:77], v20, s[20:21] offset:160
	global_load_dwordx2 v[28:29], v20, s[20:21] offset:176
	s_waitcnt vmcnt(8)
	v_fma_f32 v24, v24, v48, v26
	v_lshlrev_b32_e32 v48, 16, v15
	v_add_f32_e32 v26, 1.0, v49
	v_mul_f32_e32 v49, v48, v48
	v_fmamk_f32 v49, v49, 0xbdd2d3e7, v129
	v_mul_f32_e32 v49, v49, v48
	v_exp_f32_e32 v49, v49
	v_rcp_f32_e32 v26, v26
	v_cvt_pk_bf16_f32 v24, v24, s0
	ds_write_b16 v18, v24 offset:43248
	v_add_f32_e32 v24, 1.0, v49
	v_fma_f32 v14, v26, v14, -v19
	v_rcp_f32_e32 v24, v24
	v_mul_f32_e32 v14, v39, v14
	v_fmac_f32_e32 v27, v25, v14
	v_cvt_pk_bf16_f32 v14, v27, s0
	v_and_b32_e32 v15, 0xffff0000, v15
	ds_write_b16 v18, v14 offset:43520
	v_fma_f32 v14, v24, v48, -v19
	v_mul_f32_e32 v24, v15, v15
	v_fmamk_f32 v24, v24, 0xbdd2d3e7, v129
	v_mul_f32_e32 v24, v24, v15
	v_exp_f32_e32 v24, v24
	v_lshlrev_b32_e32 v25, 16, v16
	v_mul_f32_e32 v26, v25, v25
	v_fmamk_f32 v26, v26, 0xbdd2d3e7, v129
	v_mul_f32_e32 v26, v26, v25
	v_add_f32_e32 v24, 1.0, v24
	v_rcp_f32_e32 v24, v24
	v_exp_f32_e32 v26, v26
	v_mul_f32_e32 v73, v39, v14
	v_fma_f32 v15, v24, v15, -v19
	v_mul_f32_e32 v72, v39, v15
	v_and_b32_e32 v15, 0xffff0000, v16
	v_add_f32_e32 v14, 1.0, v26
	v_mul_f32_e32 v16, v15, v15
	v_rcp_f32_e32 v14, v14
	v_fmamk_f32 v16, v16, 0xbdd2d3e7, v129
	v_mul_f32_e32 v16, v16, v15
	v_lshlrev_b32_e32 v24, 16, v17
	v_fma_f32 v14, v14, v25, -v19
	v_exp_f32_e32 v16, v16
	v_mul_f32_e32 v25, v24, v24
	v_fmamk_f32 v25, v25, 0xbdd2d3e7, v129
	v_mul_f32_e32 v25, v25, v24
	v_add_f32_e32 v16, 1.0, v16
	v_rcp_f32_e32 v16, v16
	v_exp_f32_e32 v25, v25
	v_mul_f32_e32 v14, v39, v14
	s_waitcnt vmcnt(6)
	v_fma_f32 v14, v60, v14, v66
	v_cvt_pk_bf16_f32 v14, v14, s0
	ds_write_b16 v18, v14 offset:44336
	v_fma_f32 v14, v16, v15, -v19
	v_add_f32_e32 v15, 1.0, v25
	v_rcp_f32_e32 v15, v15
	v_mul_f32_e32 v14, v39, v14
	v_fmac_f32_e32 v67, v14, v61
	v_cvt_pk_bf16_f32 v14, v67, s0
	ds_write_b16 v18, v14 offset:44608
	v_fma_f32 v14, v15, v24, -v19
	v_and_b32_e32 v15, 0xffff0000, v17
	v_mul_f32_e32 v16, v15, v15
	v_fmamk_f32 v16, v16, 0xbdd2d3e7, v129
	v_mul_f32_e32 v16, v16, v15
	v_exp_f32_e32 v16, v16
	v_lshlrev_b32_e32 v17, 16, v10
	v_mul_f32_e32 v24, v17, v17
	v_fmamk_f32 v24, v24, 0xbdd2d3e7, v129
	v_mul_f32_e32 v24, v24, v17
	v_add_f32_e32 v16, 1.0, v16
	v_rcp_f32_e32 v16, v16
	v_exp_f32_e32 v24, v24
	v_and_b32_e32 v10, 0xffff0000, v10
	v_mul_f32_e32 v71, v39, v14
	v_fma_f32 v15, v16, v15, -v19
	v_add_f32_e32 v14, 1.0, v24
	v_mul_f32_e32 v70, v39, v15
	v_mul_f32_e32 v15, v10, v10
	v_rcp_f32_e32 v14, v14
	v_fmamk_f32 v15, v15, 0xbdd2d3e7, v129
	v_mul_f32_e32 v15, v15, v10
	v_fma_f32 v14, v14, v17, -v19
	v_exp_f32_e32 v15, v15
	v_mul_f32_e32 v14, v39, v14
	s_waitcnt vmcnt(1)
	v_fma_f32 v14, v74, v14, v76
	v_cvt_pk_bf16_f32 v14, v14, s0
	ds_write_b16 v18, v14 offset:45424
	v_add_f32_e32 v14, 1.0, v15
	v_lshlrev_b32_e32 v15, 16, v11
	v_rcp_f32_e32 v14, v14
	v_mul_f32_e32 v16, v15, v15
	v_fmamk_f32 v16, v16, 0xbdd2d3e7, v129
	v_mul_f32_e32 v16, v16, v15
	v_and_b32_e32 v11, 0xffff0000, v11
	v_fma_f32 v10, v14, v10, -v19
	v_mul_f32_e32 v14, v11, v11
	v_exp_f32_e32 v16, v16
	v_fmamk_f32 v14, v14, 0xbdd2d3e7, v129
	v_mul_f32_e32 v14, v14, v11
	v_mul_f32_e32 v10, v39, v10
	v_fmac_f32_e32 v77, v75, v10
	v_add_f32_e32 v10, 1.0, v16
	v_exp_f32_e32 v14, v14
	v_rcp_f32_e32 v10, v10
	v_cvt_pk_bf16_f32 v16, v77, s0
	ds_write_b16 v18, v16 offset:45696
	v_add_f32_e32 v14, 1.0, v14
	v_fma_f32 v10, v10, v15, -v19
	v_rcp_f32_e32 v14, v14
	v_lshlrev_b32_e32 v15, 16, v12
	v_mul_f32_e32 v16, v15, v15
	v_fmamk_f32 v16, v16, 0xbdd2d3e7, v129
	v_mul_f32_e32 v16, v16, v15
	v_mul_f32_e32 v67, v39, v10
	v_fma_f32 v10, v14, v11, -v19
	v_and_b32_e32 v11, 0xffff0000, v12
	v_mul_f32_e32 v12, v11, v11
	v_exp_f32_e32 v16, v16
	v_fmamk_f32 v12, v12, 0xbdd2d3e7, v129
	v_mul_f32_e32 v12, v12, v11
	v_mul_f32_e32 v66, v39, v10
	v_add_f32_e32 v10, 1.0, v16
	v_exp_f32_e32 v12, v12
	v_rcp_f32_e32 v10, v10
	v_or_b32_e32 v76, 2, v34
	v_or_b32_e32 v77, 3, v34
	v_add_f32_e32 v12, 1.0, v12
	v_fma_f32 v10, v10, v15, -v19
	v_rcp_f32_e32 v12, v12
	v_mul_f32_e32 v10, v39, v10
	s_waitcnt vmcnt(0)
	v_fma_f32 v10, v22, v10, v28
	v_cvt_pk_bf16_f32 v10, v10, s0
	ds_write_b16 v18, v10 offset:46512
	v_fma_f32 v10, v12, v11, -v19
	v_lshlrev_b32_e32 v11, 16, v13
	v_mul_f32_e32 v12, v11, v11
	v_fmamk_f32 v12, v12, 0xbdd2d3e7, v129
	v_mul_f32_e32 v12, v12, v11
	v_exp_f32_e32 v12, v12
	v_mul_f32_e32 v10, v39, v10
	v_fmac_f32_e32 v29, v10, v23
	v_lshlrev_b32_e32 v14, 2, v76
	v_add_f32_e32 v12, 1.0, v12
	v_rcp_f32_e32 v12, v12
	v_cvt_pk_bf16_f32 v10, v29, s0
	v_lshlrev_b32_e32 v16, 2, v77
	global_load_dword v15, v14, s[16:17]
	s_nop 0
	global_load_dword v14, v14, s[20:21]
	s_nop 0
	global_load_dword v17, v16, s[16:17]
	s_nop 0
	global_load_dword v16, v16, s[20:21]
	ds_write_b16 v18, v10 offset:46784
	v_fma_f32 v10, v12, v11, -v19
	v_and_b32_e32 v11, 0xffff0000, v13
	v_lshlrev_b32_e32 v13, 16, v6
	v_mul_f32_e32 v22, v13, v13
	v_fmamk_f32 v22, v22, 0xbdd2d3e7, v129
	v_mul_f32_e32 v22, v22, v13
	v_mul_f32_e32 v12, v11, v11
	v_fmamk_f32 v12, v12, 0xbdd2d3e7, v129
	v_exp_f32_e32 v22, v22
	v_mul_f32_e32 v12, v12, v11
	v_exp_f32_e32 v12, v12
	v_mul_f32_e32 v75, v39, v10
	v_add_f32_e32 v10, 1.0, v22
	v_rcp_f32_e32 v10, v10
	v_add_f32_e32 v12, 1.0, v12
	v_and_b32_e32 v6, 0xffff0000, v6
	v_rcp_f32_e32 v12, v12
	v_fma_f32 v22, v10, v13, -v19
	v_mul_f32_e32 v10, v6, v6
	v_fmamk_f32 v10, v10, 0xbdd2d3e7, v129
	v_mul_f32_e32 v10, v10, v6
	v_fma_f32 v11, v12, v11, -v19
	v_mul_f32_e32 v74, v39, v11
	v_exp_f32_e32 v23, v10
	global_load_dwordx2 v[10:11], v20, s[16:17] offset:192
	global_load_dwordx2 v[12:13], v20, s[20:21] offset:192
	v_mul_f32_e32 v81, v39, v22
	v_lshlrev_b32_e32 v90, 16, v8
	v_add_f32_e32 v22, 1.0, v23
	v_lshlrev_b32_e32 v23, 16, v7
	v_mul_f32_e32 v24, v23, v23
	v_and_b32_e32 v7, 0xffff0000, v7
	v_fmamk_f32 v24, v24, 0xbdd2d3e7, v129
	v_mul_f32_e32 v25, v7, v7
	v_mul_f32_e32 v24, v24, v23
	v_fmamk_f32 v25, v25, 0xbdd2d3e7, v129
	v_mul_f32_e32 v25, v25, v7
	v_rcp_f32_e32 v22, v22
	v_exp_f32_e32 v24, v24
	v_exp_f32_e32 v25, v25
	v_fma_f32 v6, v22, v6, -v19
	v_add_f32_e32 v22, 1.0, v24
	v_rcp_f32_e32 v22, v22
	v_add_f32_e32 v24, 1.0, v25
	v_rcp_f32_e32 v24, v24
	v_mul_f32_e32 v82, v39, v6
	v_fma_f32 v6, v22, v23, -v19
	v_mul_f32_e32 v62, v39, v6
	v_fma_f32 v6, v24, v7, -v19
	v_mul_f32_e32 v61, v39, v6
	v_or_b32_e32 v6, s88, v31
	v_lshlrev_b32_e32 v6, 7, v6
	v_mov_b32_e32 v7, v1
	v_lshl_add_u64 v[6:7], v[6:7], 2, s[40:41]
	v_lshl_add_u64 v[6:7], v[6:7], 0, v[20:21]
	v_and_b32_e32 v8, 0xffff0000, v8
	v_mul_f32_e32 v97, v8, v8
	v_fmamk_f32 v97, v97, 0xbdd2d3e7, v129
	v_mul_f32_e32 v97, v97, v8
	v_exp_f32_e32 v97, v97
	v_and_b32_e32 v98, 0xffff0000, v9
	v_and_b32_e32 v104, 0xffff0000, v5
	v_or_b32_e32 v41, 24, v34
	v_or_b32_e32 v42, 28, v34
	v_or_b32_e32 v43, 32, v34
	v_or_b32_e32 v48, 36, v34
	s_waitcnt vmcnt(4)
	v_fmac_f32_e32 v14, v15, v65
	v_mul_u32_u24_e32 v15, 0x110, v76
	v_cvt_pk_bf16_f32 v14, v14, s0
	v_add3_u32 v15, s15, v15, v33
	v_or_b32_e32 v65, 6, v34
	ds_write_b16 v15, v14 offset:34816
	v_lshlrev_b32_e32 v14, 2, v65
	global_load_dword v84, v14, s[16:17]
	global_load_dword v85, v14, s[20:21]
	s_waitcnt vmcnt(4)
	v_fmac_f32_e32 v16, v17, v59
	v_lshlrev_b32_e32 v14, 2, v78
	v_mul_u32_u24_e32 v15, 0x110, v77
	global_load_dword v86, v14, s[16:17]
	global_load_dword v87, v14, s[20:21]
	v_cvt_pk_bf16_f32 v14, v16, s0
	v_add3_u32 v15, s15, v15, v33
	ds_write_b16 v15, v14 offset:34816
	v_lshlrev_b32_e32 v14, 2, v80
	global_load_dwordx2 v[22:23], v20, s[16:17] offset:208
	global_load_dwordx2 v[24:25], v20, s[20:21] offset:208
	global_load_dword v88, v14, s[16:17]
	global_load_dword v89, v14, s[20:21]
	v_lshlrev_b32_e32 v14, 2, v79
	global_load_dword v91, v14, s[16:17]
	global_load_dword v92, v14, s[20:21]
	v_mul_f32_e32 v14, v90, v90
	v_fmamk_f32 v14, v14, 0xbdd2d3e7, v129
	v_mul_f32_e32 v14, v14, v90
	v_or_b32_e32 v59, 14, v34
	v_lshlrev_b32_e32 v15, 2, v59
	global_load_dword v93, v15, s[16:17]
	global_load_dword v94, v15, s[20:21]
	v_exp_f32_e32 v95, v14
	global_load_dwordx2 v[14:15], v20, s[16:17] offset:224
	global_load_dwordx2 v[16:17], v20, s[16:17] offset:240
	global_load_dwordx2 v[26:27], v20, s[20:21] offset:224
	s_nop 0
	global_load_dwordx2 v[20:21], v20, s[20:21] offset:240
	v_or_b32_e32 v49, 40, v34
	v_or_b32_e32 v51, 44, v34
	v_or_b32_e32 v57, 48, v34
	s_waitcnt vmcnt(16)
	v_fma_f32 v10, v10, v81, v12
	v_cvt_pk_bf16_f32 v12, v10, s0
	v_or_b32_e32 v10, 15, v34
	v_add_f32_e32 v81, 1.0, v95
	v_lshlrev_b32_e32 v95, 2, v10
	global_load_dword v96, v95, s[16:17]
	s_nop 0
	global_load_dword v95, v95, s[20:21]
	v_rcp_f32_e32 v81, v81
	ds_write_b16 v18, v12 offset:47600
	v_fmac_f32_e32 v13, v11, v82
	v_cvt_pk_bf16_f32 v11, v13, s0
	v_fma_f32 v12, v81, v90, -v19
	v_lshlrev_b32_e32 v90, 16, v9
	v_add_f32_e32 v81, 1.0, v97
	v_mul_f32_e32 v97, v90, v90
	v_fmamk_f32 v97, v97, 0xbdd2d3e7, v129
	v_mul_f32_e32 v97, v97, v90
	v_rcp_f32_e32 v81, v81
	v_exp_f32_e32 v97, v97
	v_mul_f32_e32 v12, v39, v12
	v_mul_u32_u24_e32 v13, 0x110, v80
	v_fma_f32 v8, v81, v8, -v19
	v_add_f32_e32 v81, 1.0, v97
	v_rcp_f32_e32 v81, v81
	v_mul_f32_e32 v99, v39, v8
	v_add3_u32 v13, s15, v13, v33
	v_mul_f32_e32 v9, v98, v98
	v_fma_f32 v8, v81, v90, -v19
	v_mul_u32_u24_e32 v81, 0x110, v65
	v_add3_u32 v81, s15, v81, v33
	v_fmamk_f32 v9, v9, 0xbdd2d3e7, v129
	v_mul_f32_e32 v9, v9, v98
	v_exp_f32_e32 v9, v9
	v_or_b32_e32 v90, 26, v34
	v_or_b32_e32 v60, 52, v34
	v_or_b32_e32 v29, 56, v34
	v_add_f32_e32 v9, 1.0, v9
	v_rcp_f32_e32 v97, v9
	v_mul_f32_e32 v9, v39, v8
	v_or_b32_e32 v28, 60, v34
	v_readlane_b32 s40, v251, 54
	v_fma_f32 v8, v97, v98, -v19
	v_or_b32_e32 v97, 30, v34
	v_mul_f32_e32 v8, v39, v8
	v_readlane_b32 s46, v251, 60
	v_readlane_b32 s47, v251, 61
	v_readlane_b32 s48, v251, 62
	v_readlane_b32 s49, v251, 63
	v_readlane_b32 s41, v251, 55
	v_readlane_b32 s42, v251, 56
	v_readlane_b32 s43, v251, 57
	s_waitcnt vmcnt(16)
	v_fmac_f32_e32 v85, v45, v84
	v_cvt_pk_bf16_f32 v45, v85, s0
	ds_write_b16 v81, v45 offset:34816
	v_mul_u32_u24_e32 v45, 0x110, v78
	s_waitcnt vmcnt(14)
	v_fmac_f32_e32 v87, v44, v86
	v_cvt_pk_bf16_f32 v44, v87, s0
	v_add3_u32 v45, s15, v45, v33
	ds_write_b16 v45, v44 offset:34816
	ds_write_b16 v18, v11 offset:47872
	s_waitcnt vmcnt(12)
	v_fma_f32 v11, v22, v12, v24
	s_waitcnt vmcnt(10)
	v_fmac_f32_e32 v89, v88, v47
	v_cvt_pk_bf16_f32 v12, v89, s0
	ds_write_b16 v13, v12 offset:34816
	s_waitcnt vmcnt(8)
	v_fmac_f32_e32 v92, v91, v46
	v_mul_u32_u24_e32 v13, 0x110, v79
	v_cvt_pk_bf16_f32 v12, v92, s0
	v_add3_u32 v13, s15, v13, v33
	v_cvt_pk_bf16_f32 v11, v11, s0
	ds_write_b16 v13, v12 offset:34816
	ds_write_b16 v18, v11 offset:48688
	v_lshlrev_b32_e32 v13, 16, v2
	v_mul_f32_e32 v22, v13, v13
	v_fmamk_f32 v22, v22, 0xbdd2d3e7, v129
	v_mul_f32_e32 v22, v22, v13
	v_exp_f32_e32 v22, v22
	v_fmac_f32_e32 v25, v99, v23
	v_cvt_pk_bf16_f32 v11, v25, s0
	s_waitcnt vmcnt(6)
	v_fmac_f32_e32 v94, v55, v93
	v_mul_u32_u24_e32 v12, 0x110, v59
	ds_write_b16 v18, v11 offset:48960
	v_cvt_pk_bf16_f32 v11, v94, s0
	v_add3_u32 v12, s15, v12, v33
	ds_write_b16 v12, v11 offset:34816
	v_add_f32_e32 v12, 1.0, v22
	v_rcp_f32_e32 v12, v12
	s_waitcnt vmcnt(0)
	v_fmac_f32_e32 v95, v54, v96
	v_mul_u32_u24_e32 v22, 0x110, v10
	v_cvt_pk_bf16_f32 v11, v95, s0
	v_add3_u32 v22, s15, v22, v33
	v_and_b32_e32 v2, 0xffff0000, v2
	ds_write_b16 v22, v11 offset:34816
	v_fma_f32 v11, v12, v13, -v19
	v_mul_f32_e32 v12, v2, v2
	v_lshlrev_b32_e32 v13, 16, v3
	v_fmamk_f32 v12, v12, 0xbdd2d3e7, v129
	v_mul_f32_e32 v22, v13, v13
	v_mul_f32_e32 v12, v12, v2
	v_fmamk_f32 v22, v22, 0xbdd2d3e7, v129
	v_mul_f32_e32 v22, v22, v13
	v_exp_f32_e32 v12, v12
	v_exp_f32_e32 v22, v22
	v_mul_f32_e32 v11, v39, v11
	v_add_f32_e32 v12, 1.0, v12
	v_fma_f32 v11, v14, v11, v26
	v_rcp_f32_e32 v12, v12
	v_add_f32_e32 v14, 1.0, v22
	v_rcp_f32_e32 v14, v14
	v_and_b32_e32 v3, 0xffff0000, v3
	v_fma_f32 v2, v12, v2, -v19
	v_mul_f32_e32 v12, v39, v2
	v_fma_f32 v2, v14, v13, -v19
	v_mul_f32_e32 v13, v3, v3
	v_fmamk_f32 v13, v13, 0xbdd2d3e7, v129
	v_mul_f32_e32 v13, v13, v3
	v_or_b32_e32 v81, 18, v34
	v_or_b32_e32 v86, 19, v34
	v_lshlrev_b32_e32 v14, 2, v81
	v_lshlrev_b32_e32 v22, 2, v86
	global_load_dword v26, v14, s[16:17]
	s_nop 0
	global_load_dword v14, v14, s[20:21]
	s_nop 0
	global_load_dword v54, v22, s[16:17]
	global_load_dword v55, v22, s[20:21]
	v_lshlrev_b32_e32 v22, 16, v4
	v_exp_f32_e32 v13, v13
	v_mul_f32_e32 v23, v22, v22
	v_fmamk_f32 v23, v23, 0xbdd2d3e7, v129
	v_mul_f32_e32 v23, v23, v22
	v_add_f32_e32 v13, 1.0, v13
	v_rcp_f32_e32 v13, v13
	v_exp_f32_e32 v23, v23
	v_or_b32_e32 v87, 22, v34
	v_lshlrev_b32_e32 v24, 2, v87
	v_fma_f32 v3, v13, v3, -v19
	v_add_f32_e32 v13, 1.0, v23
	global_load_dword v82, v24, s[16:17]
	global_load_dword v83, v24, s[20:21]
	v_or_b32_e32 v88, 23, v34
	v_rcp_f32_e32 v13, v13
	v_and_b32_e32 v4, 0xffff0000, v4
	v_lshlrev_b32_e32 v24, 2, v88
	v_mul_f32_e32 v23, v4, v4
	global_load_dword v84, v24, s[16:17]
	global_load_dword v85, v24, s[20:21]
	v_fmamk_f32 v23, v23, 0xbdd2d3e7, v129
	v_mul_f32_e32 v23, v23, v4
	v_fma_f32 v13, v13, v22, -v19
	v_lshlrev_b32_e32 v22, 2, v90
	global_load_dword v91, v22, s[16:17]
	global_load_dword v92, v22, s[20:21]
	v_or_b32_e32 v93, 27, v34
	v_exp_f32_e32 v23, v23
	v_lshlrev_b32_e32 v22, 2, v93
	global_load_dword v94, v22, s[16:17]
	global_load_dword v95, v22, s[20:21]
	v_lshlrev_b32_e32 v96, 16, v5
	v_lshlrev_b32_e32 v22, 2, v97
	global_load_dword v98, v22, s[16:17]
	global_load_dword v99, v22, s[20:21]
	v_mul_f32_e32 v22, 0x3d372713, v96
	v_mul_f32_e32 v89, v39, v13
	v_add_f32_e32 v13, 1.0, v23
	v_lshlrev_b32_e32 v23, 2, v100
	v_mul_f32_e32 v22, v22, v96
	global_load_dword v101, v23, s[16:17]
	global_load_dword v102, v23, s[20:21]
	v_fma_f32 v22, v22, v96, v96
	v_mul_f32_e32 v22, 0xbfcc422a, v22
	v_mul_f32_e32 v103, 0x3fb8aa3b, v22
	global_load_dwordx4 v[22:25], v[6:7], off offset:16
	global_load_dwordx4 v[44:47], v[6:7], off
	v_rcp_f32_e32 v13, v13
	v_exp_f32_e32 v103, v103
	v_mul_f32_e32 v5, v104, v104
	v_fmamk_f32 v5, v5, 0xbdd2d3e7, v129
	v_mul_f32_e32 v5, v5, v104
	v_fma_f32 v4, v13, v4, -v19
	v_add_f32_e32 v13, 1.0, v103
	v_rcp_f32_e32 v13, v13
	v_exp_f32_e32 v5, v5
	v_mul_f32_e32 v105, v39, v4
	v_cvt_pk_bf16_f32 v11, v11, s0
	v_fma_f32 v4, v13, v96, -v19
	v_add_f32_e32 v5, 1.0, v5
	v_rcp_f32_e32 v103, v5
	v_fmac_f32_e32 v27, v15, v12
	v_mul_f32_e32 v5, v39, v4
	v_fma_f32 v16, v16, v89, v20
	v_fma_f32 v4, v103, v104, -v19
	v_mul_u32_u24_e32 v19, 0x110, v87
	v_add3_u32 v19, s15, v19, v33
	v_cvt_pk_bf16_f32 v16, v16, s0
	v_fmac_f32_e32 v21, v105, v17
	v_mul_f32_e32 v2, v39, v2
	v_mul_f32_e32 v3, v39, v3
	v_mul_f32_e32 v4, v39, v4
	v_mul_u32_u24_e32 v17, 0x110, v90
	v_add3_u32 v17, s15, v17, v33
	v_readlane_b32 s44, v251, 58
	v_readlane_b32 s45, v251, 59
	v_readlane_b32 s50, v252, 0
	v_readlane_b32 s51, v252, 1
	s_waitcnt vmcnt(16)
	v_fmac_f32_e32 v14, v26, v53
	v_cvt_pk_bf16_f32 v13, v14, s0
	v_mul_u32_u24_e32 v14, 0x110, v81
	v_add3_u32 v14, s15, v14, v33
	ds_write_b16 v14, v13 offset:34816
	s_waitcnt vmcnt(14)
	v_fmac_f32_e32 v55, v54, v52
	v_mul_u32_u24_e32 v14, 0x110, v86
	v_cvt_pk_bf16_f32 v13, v55, s0
	v_add3_u32 v14, s15, v14, v33
	ds_write_b16 v14, v13 offset:34816
	ds_write_b16 v18, v11 offset:49776
	v_cvt_pk_bf16_f32 v11, v27, s0
	ds_write_b16 v18, v11 offset:50048
	global_load_dwordx4 v[12:15], v[6:7], off offset:48
	global_load_dwordx4 v[52:55], v[6:7], off offset:32
	v_readlane_b32 s52, v252, 2
	v_readlane_b32 s53, v252, 3
	v_readlane_b32 s54, v252, 4
	s_waitcnt vmcnt(14)
	v_fmac_f32_e32 v83, v58, v82
	v_cvt_pk_bf16_f32 v11, v83, s0
	ds_write_b16 v19, v11 offset:34816
	v_mul_u32_u24_e32 v19, 0x110, v88
	v_add3_u32 v19, s15, v19, v33
	v_or_b32_e32 v58, 35, v34
	s_waitcnt vmcnt(12)
	v_fmac_f32_e32 v85, v56, v84
	v_cvt_pk_bf16_f32 v11, v85, s0
	v_or_b32_e32 v56, 34, v34
	ds_write_b16 v19, v11 offset:34816
	v_lshlrev_b32_e32 v11, 2, v56
	v_lshlrev_b32_e32 v19, 2, v58
	global_load_dword v39, v11, s[16:17]
	s_nop 0
	global_load_dword v11, v11, s[20:21]
	s_nop 0
	global_load_dword v89, v19, s[16:17]
	global_load_dword v96, v19, s[20:21]
	ds_write_b16 v18, v16 offset:50864
	v_cvt_pk_bf16_f32 v16, v21, s0
	s_waitcnt vmcnt(14)
	v_fmac_f32_e32 v92, v91, v64
	ds_write_b16 v18, v16 offset:51136
	v_cvt_pk_bf16_f32 v16, v92, s0
	ds_write_b16 v17, v16 offset:34816
	s_waitcnt vmcnt(12)
	v_fmac_f32_e32 v95, v94, v63
	v_mul_u32_u24_e32 v17, 0x110, v93
	v_cvt_pk_bf16_f32 v16, v95, s0
	v_add3_u32 v17, s15, v17, v33
	ds_write_b16 v17, v16 offset:34816
	s_waitcnt vmcnt(10)
	v_fmac_f32_e32 v99, v69, v98
	v_mul_u32_u24_e32 v17, 0x110, v97
	v_cvt_pk_bf16_f32 v16, v99, s0
	v_add3_u32 v17, s15, v17, v33
	ds_write_b16 v17, v16 offset:34816
	s_waitcnt vmcnt(8)
	v_fmac_f32_e32 v102, v68, v101
	v_mul_u32_u24_e32 v17, 0x110, v100
	v_cvt_pk_bf16_f32 v16, v102, s0
	v_add3_u32 v17, s15, v17, v33
	ds_write_b16 v17, v16 offset:34816
	s_waitcnt vmcnt(6)
	v_cndmask_b32_e32 v16, 0, v45, vcc
	v_cmp_le_u32_e32 vcc, v34, v31
	v_or_b32_e32 v63, 38, v34
	v_or_b32_e32 v69, 39, v34
	v_cndmask_b32_e32 v17, 0, v44, vcc
	v_cvt_pk_bf16_f32 v16, v17, v16
	v_lshlrev_b32_e32 v17, 2, v63
	global_load_dword v64, v17, s[16:17]
	global_load_dword v68, v17, s[20:21]
	v_lshlrev_b32_e32 v18, 2, v69
	global_load_dword v91, v18, s[16:17]
	global_load_dword v92, v18, s[20:21]
	v_cvt_pk_bf16_f32 v17, v46, v47
	v_cmp_le_u32_e32 vcc, v76, v31
	global_load_dwordx4 v[44:47], v[6:7], off offset:80
	global_load_dwordx4 v[82:85], v[6:7], off offset:64
	v_cndmask_b32_e32 v18, 0, v17, vcc
	v_lshrrev_b32_e32 v17, 16, v17
	v_cmp_le_u32_e32 vcc, v77, v31
	v_or_b32_e32 v76, 47, v34
	v_readlane_b32 s55, v252, 5
	v_cndmask_b32_e32 v17, 0, v17, vcc
	v_cmp_gt_u32_e32 vcc, v31, v35
	v_perm_b32 v17, v17, v18, s19
	s_waitcnt vmcnt(8)
	v_fmac_f32_e32 v11, v39, v73
	v_cndmask_b32_e32 v18, 0, v23, vcc
	v_cmp_le_u32_e32 vcc, v35, v31
	v_cvt_pk_bf16_f32 v11, v11, s0
	v_or_b32_e32 v35, 42, v34
	v_cndmask_b32_e32 v19, 0, v22, vcc
	v_cvt_pk_bf16_f32 v18, v19, v18
	v_cvt_pk_bf16_f32 v19, v24, v25
	v_cmp_le_u32_e32 vcc, v65, v31
	s_waitcnt vmcnt(6)
	v_fmac_f32_e32 v96, v89, v72
	s_waitcnt vmcnt(4)
	v_fmac_f32_e32 v68, v71, v64
	v_cndmask_b32_e32 v20, 0, v19, vcc
	v_lshrrev_b32_e32 v19, 16, v19
	v_cmp_le_u32_e32 vcc, v78, v31
	s_waitcnt vmcnt(2)
	v_fmac_f32_e32 v92, v70, v91
	v_cndmask_b32_e32 v19, 0, v19, vcc
	v_perm_b32 v19, v19, v20, s19
	ds_write_b128 v0, v[16:19]
	global_load_dwordx4 v[20:23], v[6:7], off offset:112
	global_load_dwordx4 v[24:27], v[6:7], off offset:96
	v_cmp_gt_u32_e32 vcc, v31, v36
	s_nop 1
	v_cndmask_b32_e32 v16, 0, v53, vcc
	v_cmp_le_u32_e32 vcc, v36, v31
	s_nop 1
	v_cndmask_b32_e32 v17, 0, v52, vcc
	v_cvt_pk_bf16_f32 v16, v17, v16
	v_cvt_pk_bf16_f32 v17, v54, v55
	v_cmp_le_u32_e32 vcc, v80, v31
	v_or_b32_e32 v54, 43, v34
	v_lshlrev_b32_e32 v19, 2, v54
	v_cndmask_b32_e32 v18, 0, v17, vcc
	v_lshrrev_b32_e32 v17, 16, v17
	v_cmp_le_u32_e32 vcc, v79, v31
	s_nop 1
	v_cndmask_b32_e32 v17, 0, v17, vcc
	v_perm_b32 v17, v17, v18, s19
	v_mul_u32_u24_e32 v18, 0x110, v56
	v_add3_u32 v18, s15, v18, v33
	ds_write_b16 v18, v11 offset:34816
	v_lshlrev_b32_e32 v18, 2, v35
	global_load_dword v52, v18, s[16:17]
	global_load_dword v53, v18, s[20:21]
	v_mul_u32_u24_e32 v18, 0x110, v58
	v_cvt_pk_bf16_f32 v11, v96, s0
	v_add3_u32 v18, s15, v18, v33
	v_cmp_gt_u32_e32 vcc, v31, v37
	global_load_dword v55, v19, s[16:17]
	global_load_dword v65, v19, s[20:21]
	ds_write_b16 v18, v11 offset:34816
	v_cndmask_b32_e32 v11, 0, v13, vcc
	v_cmp_le_u32_e32 vcc, v37, v31
	s_waitcnt vmcnt(2)
	v_fmac_f32_e32 v53, v52, v67
	v_cndmask_b32_e32 v12, 0, v12, vcc
	v_cvt_pk_bf16_f32 v18, v12, v11
	v_cvt_pk_bf16_f32 v11, v14, v15
	v_cmp_le_u32_e32 vcc, v59, v31
	v_or_b32_e32 v59, 46, v34
	s_waitcnt vmcnt(0)
	v_fmac_f32_e32 v65, v55, v66
	v_cndmask_b32_e32 v12, 0, v11, vcc
	v_lshrrev_b32_e32 v11, 16, v11
	v_cmp_le_u32_e32 vcc, v10, v31
	v_or_b32_e32 v52, 54, v34
	s_nop 0
	v_cndmask_b32_e32 v10, 0, v11, vcc
	v_perm_b32 v19, v10, v12, s19
	v_lshlrev_b32_e32 v10, 2, v59
	global_load_dword v72, v10, s[16:17]
	global_load_dword v73, v10, s[20:21]
	ds_write_b128 v0, v[16:19] offset:16
	v_lshlrev_b32_e32 v10, 2, v76
	v_mul_u32_u24_e32 v11, 0x110, v63
	global_load_dword v77, v10, s[16:17]
	global_load_dword v78, v10, s[20:21]
	v_cvt_pk_bf16_f32 v10, v68, s0
	v_add3_u32 v11, s15, v11, v33
	ds_write_b16 v11, v10 offset:34816
	global_load_dwordx4 v[10:13], v[6:7], off offset:144
	global_load_dwordx4 v[14:17], v[6:7], off offset:128
	v_mul_u32_u24_e32 v19, 0x110, v69
	v_cvt_pk_bf16_f32 v18, v92, s0
	v_add3_u32 v19, s15, v19, v33
	v_cmp_gt_u32_e32 vcc, v31, v38
	ds_write_b16 v19, v18 offset:34816
	s_waitcnt vmcnt(4)
	v_fmac_f32_e32 v73, v75, v72
	v_cndmask_b32_e32 v18, 0, v83, vcc
	v_cmp_le_u32_e32 vcc, v38, v31
	s_waitcnt vmcnt(2)
	v_fmac_f32_e32 v78, v74, v77
	v_cndmask_b32_e32 v19, 0, v82, vcc
	v_cvt_pk_bf16_f32 v36, v19, v18
	v_cvt_pk_bf16_f32 v18, v84, v85
	v_cmp_le_u32_e32 vcc, v81, v31
	s_nop 1
	v_cndmask_b32_e32 v19, 0, v18, vcc
	v_lshrrev_b32_e32 v18, 16, v18
	v_cmp_le_u32_e32 vcc, v86, v31
	s_nop 1
	v_cndmask_b32_e32 v18, 0, v18, vcc
	v_cmp_gt_u32_e32 vcc, v31, v40
	v_perm_b32 v37, v18, v19, s19
	s_nop 0
	v_cndmask_b32_e32 v18, 0, v45, vcc
	v_cmp_le_u32_e32 vcc, v40, v31
	s_nop 1
	v_cndmask_b32_e32 v19, 0, v44, vcc
	v_cvt_pk_bf16_f32 v38, v19, v18
	v_cvt_pk_bf16_f32 v18, v46, v47
	v_cmp_le_u32_e32 vcc, v87, v31
	s_nop 1
	v_cndmask_b32_e32 v19, 0, v18, vcc
	v_lshrrev_b32_e32 v18, 16, v18
	v_cmp_le_u32_e32 vcc, v88, v31
	s_nop 1
	v_cndmask_b32_e32 v18, 0, v18, vcc
	v_cmp_gt_u32_e32 vcc, v31, v41
	v_perm_b32 v39, v18, v19, s19
	ds_write_b128 v0, v[36:39] offset:32
	v_cndmask_b32_e32 v18, 0, v25, vcc
	v_cmp_le_u32_e32 vcc, v41, v31
	v_mul_u32_u24_e32 v41, 0x110, v35
	v_add3_u32 v41, s15, v41, v33
	v_cndmask_b32_e32 v19, 0, v24, vcc
	v_cvt_pk_bf16_f32 v18, v19, v18
	v_cvt_pk_bf16_f32 v19, v26, v27
	global_load_dwordx4 v[24:27], v[6:7], off offset:176
	global_load_dwordx4 v[36:39], v[6:7], off offset:160
	v_cmp_le_u32_e32 vcc, v90, v31
	s_nop 1
	v_cndmask_b32_e32 v40, 0, v19, vcc
	v_lshrrev_b32_e32 v19, 16, v19
	v_cmp_le_u32_e32 vcc, v93, v31
	s_nop 1
	v_cndmask_b32_e32 v19, 0, v19, vcc
	v_cmp_gt_u32_e32 vcc, v31, v42
	v_perm_b32 v19, v19, v40, s19
	v_cvt_pk_bf16_f32 v40, v53, s0
	v_cndmask_b32_e32 v21, 0, v21, vcc
	v_cmp_le_u32_e32 vcc, v42, v31
	ds_write_b16 v41, v40 offset:34816
	v_mul_u32_u24_e32 v41, 0x110, v54
	v_cndmask_b32_e32 v20, 0, v20, vcc
	v_cvt_pk_bf16_f32 v20, v20, v21
	v_cvt_pk_bf16_f32 v21, v22, v23
	v_cmp_le_u32_e32 vcc, v97, v31
	v_cvt_pk_bf16_f32 v40, v65, s0
	v_add3_u32 v41, s15, v41, v33
	v_cndmask_b32_e32 v22, 0, v21, vcc
	v_lshrrev_b32_e32 v21, 16, v21
	v_cmp_le_u32_e32 vcc, v100, v31
	ds_write_b16 v41, v40 offset:34816
	v_mul_u32_u24_e32 v23, 0x110, v76
	v_cndmask_b32_e32 v21, 0, v21, vcc
	v_perm_b32 v21, v21, v22, s19
	ds_write_b128 v0, v[18:21] offset:48
	v_mul_u32_u24_e32 v19, 0x110, v59
	v_cvt_pk_bf16_f32 v18, v73, s0
	v_add3_u32 v19, s15, v19, v33
	v_cmp_gt_u32_e32 vcc, v31, v43
	ds_write_b16 v19, v18 offset:34816
	v_cvt_pk_bf16_f32 v22, v78, s0
	v_add3_u32 v23, s15, v23, v33
	s_waitcnt vmcnt(2)
	v_cndmask_b32_e32 v15, 0, v15, vcc
	v_cmp_le_u32_e32 vcc, v43, v31
	global_load_dwordx4 v[18:21], v[6:7], off offset:208
	global_load_dwordx4 v[44:47], v[6:7], off offset:192
	ds_write_b16 v23, v22 offset:34816
	v_cndmask_b32_e32 v14, 0, v14, vcc
	v_or_b32_e32 v23, 50, v34
	v_cvt_pk_bf16_f32 v14, v14, v15
	v_cvt_pk_bf16_f32 v15, v16, v17
	v_or_b32_e32 v22, 51, v34
	v_lshlrev_b32_e32 v17, 2, v23
	v_cmp_le_u32_e32 vcc, v56, v31
	global_load_dword v40, v17, s[16:17]
	global_load_dword v41, v17, s[20:21]
	v_lshlrev_b32_e32 v17, 2, v22
	v_cndmask_b32_e32 v16, 0, v15, vcc
	v_lshrrev_b32_e32 v15, 16, v15
	global_load_dword v42, v17, s[16:17]
	global_load_dword v43, v17, s[20:21]
	v_cmp_le_u32_e32 vcc, v58, v31
	s_waitcnt vmcnt(2)
	v_fmac_f32_e32 v41, v40, v62
	v_cndmask_b32_e32 v15, 0, v15, vcc
	v_cmp_gt_u32_e32 vcc, v31, v48
	v_perm_b32 v15, v15, v16, s19
	s_waitcnt vmcnt(0)
	v_fmac_f32_e32 v43, v42, v61
	v_cndmask_b32_e32 v11, 0, v11, vcc
	v_cmp_le_u32_e32 vcc, v48, v31
	v_or_b32_e32 v48, 55, v34
	s_nop 0
	v_cndmask_b32_e32 v10, 0, v10, vcc
	v_cvt_pk_bf16_f32 v16, v10, v11
	v_cvt_pk_bf16_f32 v10, v12, v13
	v_cmp_le_u32_e32 vcc, v63, v31
	s_nop 1
	v_cndmask_b32_e32 v11, 0, v10, vcc
	v_lshrrev_b32_e32 v10, 16, v10
	v_cmp_le_u32_e32 vcc, v69, v31
	s_nop 1
	v_cndmask_b32_e32 v10, 0, v10, vcc
	v_perm_b32 v17, v10, v11, s19
	v_lshlrev_b32_e32 v10, 2, v52
	global_load_dword v53, v10, s[16:17]
	global_load_dword v55, v10, s[20:21]
	v_lshlrev_b32_e32 v10, 2, v48
	global_load_dword v56, v10, s[16:17]
	global_load_dword v58, v10, s[20:21]
	v_cmp_gt_u32_e32 vcc, v31, v49
	ds_write_b128 v0, v[14:17] offset:64
	s_waitcnt vmcnt(2)
	v_fmac_f32_e32 v55, v9, v53
	v_cndmask_b32_e32 v10, 0, v37, vcc
	v_cmp_le_u32_e32 vcc, v49, v31
	v_or_b32_e32 v49, 58, v34
	v_cvt_pk_bf16_f32 v9, v55, s0
	v_cndmask_b32_e32 v11, 0, v36, vcc
	v_cvt_pk_bf16_f32 v10, v11, v10
	v_cvt_pk_bf16_f32 v11, v38, v39
	v_cmp_le_u32_e32 vcc, v35, v31
	global_load_dwordx4 v[14:17], v[6:7], off offset:240
	global_load_dwordx4 v[36:39], v[6:7], off offset:224
	v_cndmask_b32_e32 v12, 0, v11, vcc
	v_lshrrev_b32_e32 v11, 16, v11
	v_cmp_le_u32_e32 vcc, v54, v31
	v_or_b32_e32 v35, 59, v34
	s_waitcnt vmcnt(2)
	v_fmac_f32_e32 v58, v8, v56
	v_cndmask_b32_e32 v6, 0, v11, vcc
	v_perm_b32 v11, v6, v12, s19
	v_lshlrev_b32_e32 v6, 2, v49
	global_load_dword v54, v6, s[16:17]
	global_load_dword v63, v6, s[20:21]
	v_lshlrev_b32_e32 v6, 2, v35
	v_cmp_gt_u32_e32 vcc, v31, v51
	global_load_dword v64, v6, s[16:17]
	global_load_dword v65, v6, s[20:21]
	v_cndmask_b32_e32 v6, 0, v25, vcc
	v_cmp_le_u32_e32 vcc, v51, v31
	s_waitcnt vmcnt(2)
	v_fmac_f32_e32 v63, v54, v2
	v_cndmask_b32_e32 v7, 0, v24, vcc
	v_cvt_pk_bf16_f32 v12, v7, v6
	v_cvt_pk_bf16_f32 v6, v26, v27
	v_cmp_le_u32_e32 vcc, v59, v31
	v_mul_u32_u24_e32 v26, 0x110, v22
	v_cvt_pk_bf16_f32 v27, v41, s0
	v_cndmask_b32_e32 v7, 0, v6, vcc
	v_lshrrev_b32_e32 v6, 16, v6
	v_cmp_le_u32_e32 vcc, v76, v31
	v_add3_u32 v26, s15, v26, v33
	v_cvt_pk_bf16_f32 v2, v63, s0
	v_cndmask_b32_e32 v6, 0, v6, vcc
	v_perm_b32 v13, v6, v7, s19
	ds_write_b128 v0, v[10:13] offset:80
	v_or_b32_e32 v11, 62, v34
	v_or_b32_e32 v10, 63, v34
	v_lshlrev_b32_e32 v7, 2, v11
	global_load_dword v12, v7, s[16:17]
	global_load_dword v13, v7, s[20:21]
	v_lshlrev_b32_e32 v7, 2, v10
	global_load_dword v24, v7, s[16:17]
	global_load_dword v25, v7, s[20:21]
	v_cmp_gt_u32_e32 vcc, v31, v57
	s_waitcnt vmcnt(4)
	v_fmac_f32_e32 v65, v64, v3
	v_and_or_b32 v76, v30, 64, v32
	v_cndmask_b32_e32 v6, 0, v45, vcc
	v_cmp_le_u32_e32 vcc, v57, v31
	s_waitcnt vmcnt(2)
	v_fmac_f32_e32 v13, v5, v12
	v_cndmask_b32_e32 v7, 0, v44, vcc
	v_cvt_pk_bf16_f32 v6, v7, v6
	v_mul_u32_u24_e32 v7, 0x110, v23
	v_add3_u32 v7, s15, v7, v33
	ds_write_b16 v7, v27 offset:34816
	v_cvt_pk_bf16_f32 v7, v43, s0
	ds_write_b16 v26, v7 offset:34816
	v_cvt_pk_bf16_f32 v7, v46, v47
	v_cmp_le_u32_e32 vcc, v23, v31
	v_cvt_pk_bf16_f32 v5, v13, s0
	s_waitcnt vmcnt(0)
	v_fmac_f32_e32 v25, v4, v24
	v_cndmask_b32_e32 v23, 0, v7, vcc
	v_lshrrev_b32_e32 v7, 16, v7
	v_cmp_le_u32_e32 vcc, v22, v31
	s_nop 1
	v_cndmask_b32_e32 v7, 0, v7, vcc
	v_perm_b32 v7, v7, v23, s19
	v_cmp_gt_u32_e32 vcc, v31, v60
	ds_write_b64 v0, v[6:7] offset:96
	s_nop 0
	v_cndmask_b32_e32 v6, 0, v19, vcc
	v_cmp_le_u32_e32 vcc, v60, v31
	s_nop 1
	v_cndmask_b32_e32 v7, 0, v18, vcc
	v_cvt_pk_bf16_f32 v6, v7, v6
	v_mul_u32_u24_e32 v7, 0x110, v52
	v_add3_u32 v7, s15, v7, v33
	v_mul_u32_u24_e32 v18, 0x110, v48
	v_add3_u32 v18, s15, v18, v33
	ds_write_b16 v7, v9 offset:34816
	v_cvt_pk_bf16_f32 v7, v58, s0
	ds_write_b16 v18, v7 offset:34816
	v_cvt_pk_bf16_f32 v7, v20, v21
	v_cmp_le_u32_e32 vcc, v52, v31
	s_nop 1
	v_cndmask_b32_e32 v8, 0, v7, vcc
	v_lshrrev_b32_e32 v7, 16, v7
	v_cmp_le_u32_e32 vcc, v48, v31
	s_nop 1
	v_cndmask_b32_e32 v7, 0, v7, vcc
	v_perm_b32 v7, v7, v8, s19
	v_cmp_gt_u32_e32 vcc, v31, v29
	ds_write_b64 v0, v[6:7] offset:104
	v_mul_u32_u24_e32 v8, 0x110, v35
	v_cndmask_b32_e32 v6, 0, v37, vcc
	v_cmp_le_u32_e32 vcc, v29, v31
	v_add3_u32 v8, s15, v8, v33
	s_nop 0
	v_cndmask_b32_e32 v7, 0, v36, vcc
	v_cvt_pk_bf16_f32 v6, v7, v6
	v_mul_u32_u24_e32 v7, 0x110, v49
	v_add3_u32 v7, s15, v7, v33
	ds_write_b16 v7, v2 offset:34816
	v_cvt_pk_bf16_f32 v2, v65, s0
	ds_write_b16 v8, v2 offset:34816
	v_cvt_pk_bf16_f32 v2, v38, v39
	v_cmp_le_u32_e32 vcc, v49, v31
	s_nop 1
	v_cndmask_b32_e32 v3, 0, v2, vcc
	v_lshrrev_b32_e32 v2, 16, v2
	v_cmp_le_u32_e32 vcc, v35, v31
	s_nop 1
	v_cndmask_b32_e32 v2, 0, v2, vcc
	v_cmp_gt_u32_e32 vcc, v31, v28
	v_perm_b32 v7, v2, v3, s19
	ds_write_b64 v0, v[6:7] offset:112
	v_cndmask_b32_e32 v2, 0, v15, vcc
	v_cmp_le_u32_e32 vcc, v28, v31
	v_mul_u32_u24_e32 v6, 0x110, v10
	v_add3_u32 v6, s15, v6, v33
	v_cndmask_b32_e32 v3, 0, v14, vcc
	v_cvt_pk_bf16_f32 v2, v3, v2
	v_mul_u32_u24_e32 v3, 0x110, v11
	v_add3_u32 v3, s15, v3, v33
	ds_write_b16 v3, v5 offset:34816
	v_cvt_pk_bf16_f32 v3, v25, s0
	ds_write_b16 v6, v3 offset:34816
	v_cvt_pk_bf16_f32 v3, v16, v17
	v_cmp_le_u32_e32 vcc, v11, v31
	v_mul_u32_u24_e32 v7, 0x88, v76
	s_mov_b64 s[0:1], 0x1f000
	v_cndmask_b32_e32 v4, 0, v3, vcc
	v_lshrrev_b32_e32 v3, 16, v3
	v_cmp_le_u32_e32 vcc, v10, v31
	s_nop 1
	v_cndmask_b32_e32 v3, 0, v3, vcc
	v_perm_b32 v3, v3, v4, s19
	ds_write_b64 v0, v[2:3] offset:120
	v_bfe_u32 v0, v50, 4, 2
	v_and_b32_e32 v2, 0x4f, v50
	v_lshl_add_u32 v6, v0, 4, s15
	v_mul_u32_u24_e32 v2, 0x88, v2
	v_lshl_add_u32 v51, v2, 1, v6
	s_waitcnt lgkmcnt(0)
	s_barrier
	ds_read_b128 v[2:5], v51 offset:34816
	ds_read_b128 v[72:75], v51 offset:34880
	ds_read_b128 v[14:17], v51 offset:39168
	ds_read_b128 v[78:81], v51 offset:39232
	ds_read_b128 v[22:25], v51 offset:43520
	ds_read_b128 v[82:85], v51 offset:43584
	ds_read_b128 v[30:33], v51 offset:47872
	ds_read_b128 v[86:89], v51 offset:47936
	v_lshl_add_u32 v77, v7, 1, v6
	ds_read_b128 v[6:9], v77
	ds_read_b128 v[34:37], v77 offset:4352
	ds_read_b128 v[52:55], v77 offset:8704
	ds_read_b128 v[68:71], v77 offset:13056
	s_waitcnt lgkmcnt(3)
	v_mfma_f32_16x16x32_bf16 v[10:13], v[2:5], v[6:9], 0
	ds_read_b128 v[98:101], v51 offset:48000
	v_mfma_f32_16x16x32_bf16 v[18:21], v[14:17], v[6:9], 0
	v_mfma_f32_16x16x32_bf16 v[26:29], v[22:25], v[6:9], 0
	v_mfma_f32_16x16x32_bf16 v[6:9], v[30:33], v[6:9], 0
	s_waitcnt lgkmcnt(3)
	v_mfma_f32_16x16x32_bf16 v[38:41], v[2:5], v[34:37], 0
	v_mfma_f32_16x16x32_bf16 v[42:45], v[14:17], v[34:37], 0
	v_mfma_f32_16x16x32_bf16 v[46:49], v[22:25], v[34:37], 0
	v_mfma_f32_16x16x32_bf16 v[34:37], v[30:33], v[34:37], 0
	s_waitcnt lgkmcnt(2)
	v_mfma_f32_16x16x32_bf16 v[56:59], v[2:5], v[52:55], 0
	v_mfma_f32_16x16x32_bf16 v[60:63], v[14:17], v[52:55], 0
	v_mfma_f32_16x16x32_bf16 v[64:67], v[22:25], v[52:55], 0
	v_mfma_f32_16x16x32_bf16 v[52:55], v[30:33], v[52:55], 0
	s_waitcnt lgkmcnt(1)
	v_mfma_f32_16x16x32_bf16 v[2:5], v[2:5], v[68:71], 0
	v_mfma_f32_16x16x32_bf16 v[14:17], v[14:17], v[68:71], 0
	v_mfma_f32_16x16x32_bf16 v[22:25], v[22:25], v[68:71], 0
	v_mfma_f32_16x16x32_bf16 v[30:33], v[30:33], v[68:71], 0
	ds_read_b128 v[68:71], v77 offset:64
	s_waitcnt lgkmcnt(0)
	v_mfma_f32_16x16x32_bf16 v[10:13], v[72:75], v[68:71], v[10:13]
	v_mfma_f32_16x16x32_bf16 v[18:21], v[78:81], v[68:71], v[18:21]
	v_mfma_f32_16x16x32_bf16 v[26:29], v[82:85], v[68:71], v[26:29]
	v_mfma_f32_16x16x32_bf16 v[6:9], v[86:89], v[68:71], v[6:9]
	ds_read_b128 v[68:71], v77 offset:4416
	s_waitcnt lgkmcnt(0)
	v_mfma_f32_16x16x32_bf16 v[38:41], v[72:75], v[68:71], v[38:41]
	v_mfma_f32_16x16x32_bf16 v[42:45], v[78:81], v[68:71], v[42:45]
	v_mfma_f32_16x16x32_bf16 v[46:49], v[82:85], v[68:71], v[46:49]
	v_mfma_f32_16x16x32_bf16 v[34:37], v[86:89], v[68:71], v[34:37]
	ds_read_b128 v[68:71], v77 offset:8768
	s_waitcnt lgkmcnt(0)
	v_mfma_f32_16x16x32_bf16 v[90:93], v[78:81], v[68:71], v[60:63]
	s_nop 2
	ds_read_b128 v[60:63], v77 offset:13120
	v_mfma_f32_16x16x32_bf16 v[56:59], v[72:75], v[68:71], v[56:59]
	v_mfma_f32_16x16x32_bf16 v[94:97], v[82:85], v[68:71], v[64:67]
	v_mfma_f32_16x16x32_bf16 v[52:55], v[86:89], v[68:71], v[52:55]
	s_nop 1
	ds_read_b128 v[66:69], v51 offset:34944
	s_waitcnt lgkmcnt(1)
	v_mfma_f32_16x16x32_bf16 v[2:5], v[72:75], v[60:63], v[2:5]
	v_mfma_f32_16x16x32_bf16 v[70:73], v[86:89], v[60:63], v[30:33]
	s_nop 2
	ds_read_b128 v[30:33], v77 offset:128
	v_mfma_f32_16x16x32_bf16 v[14:17], v[78:81], v[60:63], v[14:17]
	s_waitcnt lgkmcnt(0)
	v_mfma_f32_16x16x32_bf16 v[78:81], v[66:69], v[30:33], v[10:13]
	s_nop 2
	ds_read_b128 v[10:13], v51 offset:39296
	v_mfma_f32_16x16x32_bf16 v[22:25], v[82:85], v[60:63], v[22:25]
	v_mfma_f32_16x16x32_bf16 v[102:105], v[98:101], v[30:33], v[6:9]
	s_nop 2
	ds_read_b128 v[6:9], v77 offset:4480
	s_waitcnt lgkmcnt(1)
	v_mfma_f32_16x16x32_bf16 v[82:85], v[10:13], v[30:33], v[18:21]
	s_nop 2
	ds_read_b128 v[18:21], v51 offset:43648
	s_waitcnt lgkmcnt(1)
	v_mfma_f32_16x16x32_bf16 v[106:109], v[66:69], v[6:9], v[38:41]
	v_mfma_f32_16x16x32_bf16 v[110:113], v[10:13], v[6:9], v[42:45]
	s_waitcnt lgkmcnt(0)
	v_mfma_f32_16x16x32_bf16 v[114:117], v[18:21], v[6:9], v[46:49]
	v_mfma_f32_16x16x32_bf16 v[62:65], v[98:101], v[6:9], v[34:37]
	ds_read_b128 v[6:9], v77 offset:8832
	s_waitcnt lgkmcnt(0)
	v_mfma_f32_16x16x32_bf16 v[42:45], v[98:101], v[6:9], v[52:55]
	s_nop 2
	ds_read_b128 v[52:55], v77 offset:13184
	v_mfma_f32_16x16x32_bf16 v[86:89], v[18:21], v[30:33], v[26:29]
	ds_read_b128 v[30:33], v51 offset:35008
	s_waitcnt lgkmcnt(1)
	v_mfma_f32_16x16x32_bf16 v[26:29], v[66:69], v[52:55], v[2:5]
	v_mfma_f32_16x16x32_bf16 v[2:5], v[18:21], v[52:55], v[22:25]
	s_nop 2
	v_and_b32_e32 v22, 64, v50
	v_mfma_f32_16x16x32_bf16 v[38:41], v[66:69], v[6:9], v[56:59]
	v_lshlrev_b32_e32 v66, 3, v0
	v_lshlrev_b32_e32 v0, 1, v22
	v_or_b32_e32 v24, s4, v76
	v_lshl_add_u64 v[22:23], s[6:7], 0, v[0:1]
	v_mov_b32_e32 v67, v1
	v_mfma_f32_16x16x32_bf16 v[34:37], v[10:13], v[6:9], v[90:93]
	v_lshl_add_u64 v[22:23], v[22:23], 0, v[66:67]
	v_lshlrev_b32_e32 v76, 2, v76
	s_mov_b32 s4, 0x3e000
	v_mfma_f32_16x16x32_bf16 v[46:49], v[18:21], v[6:9], v[94:97]
	v_mfma_f32_16x16x32_bf16 v[6:9], v[10:13], v[52:55], v[14:17]
	v_mfma_f32_16x16x32_bf16 v[10:13], v[98:101], v[52:55], v[70:73]
	ds_read_b128 v[52:55], v77 offset:192
	s_nop 0
	ds_read_b128 v[14:17], v51 offset:39360
	ds_read_b128 v[18:21], v51 offset:43712
	v_mul_u32_u24_e32 v72, 0x1f00, v24
	v_mov_b32_e32 v73, v1
	v_lshl_add_u64 v[68:69], v[22:23], 0, v[72:73]
	global_load_dwordx2 v[98:99], v[68:69], off
	global_load_dwordx2 v[100:101], v[68:69], off offset:32
	ds_read_b128 v[94:97], v77 offset:4544
	s_waitcnt lgkmcnt(0)
	v_mfma_f32_16x16x32_bf16 v[58:61], v[30:33], v[94:97], v[106:109]
	s_nop 2
	global_load_dword v106, v76, s[12:13]
	ds_read_b128 v[22:25], v51 offset:48064
	v_lshl_add_u64 v[72:73], s[46:47], 0, v[72:73]
	s_waitcnt lgkmcnt(0)
	v_mfma_f32_16x16x32_bf16 v[90:93], v[22:25], v[52:55], v[102:105]
	s_nop 2
	global_load_dwordx2 v[102:103], v[68:69], off offset:64
	global_load_dwordx2 v[104:105], v[68:69], off offset:96
	v_lshl_add_u64 v[72:73], v[72:73], 0, s[8:9]
	v_lshl_add_u64 v[72:73], v[72:73], 0, v[0:1]
	v_mfma_f32_16x16x32_bf16 v[78:81], v[30:33], v[52:55], v[78:81]
	v_lshl_add_u64 v[66:67], v[72:73], 0, v[66:67]
	v_add_co_u32_e32 v70, vcc, s2, v68
	v_mfma_f32_16x16x32_bf16 v[82:85], v[14:17], v[52:55], v[82:85]
	s_nop 0
	v_addc_co_u32_e32 v71, vcc, 0, v69, vcc
	s_waitcnt vmcnt(4)
	v_lshlrev_b32_e32 v107, 16, v98
	v_and_b32_e32 v98, 0xffff0000, v98
	v_mul_f32_e32 v75, v98, v98
	v_mul_f32_e32 v74, v107, v107
	v_fmamk_f32 v75, v75, 0xbdd2d3e7, v129
	v_fmamk_f32 v74, v74, 0xbdd2d3e7, v129
	v_mul_f32_e32 v75, v75, v98
	v_mul_f32_e32 v74, v74, v107
	v_exp_f32_e32 v108, v75
	v_exp_f32_e32 v74, v74
	s_waitcnt vmcnt(2)
	v_add_f32_e32 v79, v79, v106
	v_add_f32_e32 v78, v78, v106
	v_add_f32_e32 v108, 1.0, v108
	v_add_f32_e32 v74, 1.0, v74
	v_rcp_f32_e32 v108, v108
	v_rcp_f32_e32 v109, v74
	v_add_f32_e32 v80, v80, v106
	v_add_f32_e32 v81, v81, v106
	v_mul_f32_e32 v98, v108, v98
	v_mul_f32_e32 v107, v109, v107
	v_mul_f32_e32 v79, v98, v79
	v_lshlrev_b32_e32 v98, 16, v99
	v_and_b32_e32 v99, 0xffff0000, v99
	v_mul_f32_e32 v78, v107, v78
	v_mul_f32_e32 v107, v98, v98
	v_mul_f32_e32 v108, v99, v99
	v_fmamk_f32 v107, v107, 0xbdd2d3e7, v129
	v_fmamk_f32 v108, v108, 0xbdd2d3e7, v129
	v_mul_f32_e32 v107, v107, v98
	v_mul_f32_e32 v108, v108, v99
	v_exp_f32_e32 v107, v107
	v_exp_f32_e32 v108, v108
	v_cvt_pk_bf16_f32 v78, v78, v79
	v_lshlrev_b32_e32 v0, 16, v100
	v_add_f32_e32 v107, 1.0, v107
	v_add_f32_e32 v79, 1.0, v108
	v_rcp_f32_e32 v107, v107
	v_rcp_f32_e32 v79, v79
	v_mul_f32_e32 v72, v0, v0
	v_and_b32_e32 v73, 0xffff0000, v100
	v_mul_f32_e32 v98, v107, v98
	v_mul_f32_e32 v79, v79, v99
	v_mul_f32_e32 v80, v98, v80
	v_mul_f32_e32 v79, v79, v81
	v_cvt_pk_bf16_f32 v79, v80, v79
	v_fmamk_f32 v72, v72, 0xbdd2d3e7, v129
	v_mul_f32_e32 v80, v73, v73
	v_mul_f32_e32 v72, v72, v0
	v_fmamk_f32 v80, v80, 0xbdd2d3e7, v129
	v_mul_f32_e32 v80, v80, v73
	v_exp_f32_e32 v72, v72
	v_exp_f32_e32 v80, v80
	global_store_dwordx2 v[66:67], v[78:79], off
	v_add_f32_e32 v72, 1.0, v72
	v_rcp_f32_e32 v72, v72
	v_add_f32_e32 v78, 1.0, v80
	v_rcp_f32_e32 v78, v78
	v_and_b32_e32 v79, 0xffff0000, v101
	v_mul_f32_e32 v0, v72, v0
	v_add_f32_e32 v72, v82, v106
	v_mul_f32_e32 v0, v0, v72
	v_mul_f32_e32 v72, v78, v73
	v_add_f32_e32 v73, v83, v106
	v_mul_f32_e32 v72, v72, v73
	v_lshlrev_b32_e32 v73, 16, v101
	v_mul_f32_e32 v78, v73, v73
	v_fmamk_f32 v78, v78, 0xbdd2d3e7, v129
	v_mul_f32_e32 v80, v79, v79
	v_mul_f32_e32 v78, v78, v73
	v_fmamk_f32 v80, v80, 0xbdd2d3e7, v129
	v_mul_f32_e32 v80, v80, v79
	v_exp_f32_e32 v78, v78
	v_exp_f32_e32 v80, v80
	v_cvt_pk_bf16_f32 v72, v0, v72
	v_add_f32_e32 v78, 1.0, v78
	v_rcp_f32_e32 v78, v78
	v_add_f32_e32 v0, 1.0, v80
	v_rcp_f32_e32 v0, v0
	v_mfma_f32_16x16x32_bf16 v[86:89], v[18:21], v[52:55], v[86:89]
	v_mul_f32_e32 v73, v78, v73
	v_add_f32_e32 v78, v84, v106
	v_mul_f32_e32 v73, v73, v78
	v_mul_f32_e32 v0, v0, v79
	v_add_f32_e32 v78, v85, v106
	v_mul_f32_e32 v0, v0, v78
	v_cvt_pk_bf16_f32 v73, v73, v0
	s_waitcnt vmcnt(2)
	v_lshlrev_b32_e32 v0, 16, v102
	v_mul_f32_e32 v78, v0, v0
	v_and_b32_e32 v79, 0xffff0000, v102
	v_fmamk_f32 v78, v78, 0xbdd2d3e7, v129
	v_mul_f32_e32 v80, v79, v79
	v_mul_f32_e32 v78, v78, v0
	v_fmamk_f32 v80, v80, 0xbdd2d3e7, v129
	v_mul_f32_e32 v80, v80, v79
	v_exp_f32_e32 v78, v78
	v_exp_f32_e32 v80, v80
	global_store_dwordx2 v[66:67], v[72:73], off offset:32
	v_add_f32_e32 v78, 1.0, v78
	v_rcp_f32_e32 v78, v78
	v_add_f32_e32 v72, 1.0, v80
	v_rcp_f32_e32 v72, v72
	v_add_f32_e32 v73, v86, v106
	v_mul_f32_e32 v0, v78, v0
	v_mul_f32_e32 v0, v0, v73
	v_mul_f32_e32 v72, v72, v79
	v_add_f32_e32 v73, v87, v106
	v_mul_f32_e32 v72, v72, v73
	v_lshlrev_b32_e32 v73, 16, v103
	v_mul_f32_e32 v78, v73, v73
	v_and_b32_e32 v79, 0xffff0000, v103
	v_fmamk_f32 v78, v78, 0xbdd2d3e7, v129
	v_mul_f32_e32 v80, v79, v79
	v_mul_f32_e32 v78, v78, v73
	v_fmamk_f32 v80, v80, 0xbdd2d3e7, v129
	v_mul_f32_e32 v80, v80, v79
	v_exp_f32_e32 v78, v78
	v_exp_f32_e32 v80, v80
	v_cvt_pk_bf16_f32 v72, v0, v72
	v_add_f32_e32 v78, 1.0, v78
	v_rcp_f32_e32 v78, v78
	v_add_f32_e32 v0, 1.0, v80
	v_rcp_f32_e32 v0, v0
	global_load_dwordx2 v[74:75], v[70:71], off
	global_load_dwordx2 v[82:83], v[70:71], off offset:32
	v_mul_f32_e32 v73, v78, v73
	v_add_f32_e32 v78, v88, v106
	v_mul_f32_e32 v73, v73, v78
	v_mul_f32_e32 v0, v0, v79
	v_add_f32_e32 v78, v89, v106
	v_mul_f32_e32 v0, v0, v78
	v_cvt_pk_bf16_f32 v73, v73, v0
	s_waitcnt vmcnt(4)
	v_lshlrev_b32_e32 v0, 16, v104
	v_mul_f32_e32 v78, v0, v0
	v_and_b32_e32 v79, 0xffff0000, v104
	v_fmamk_f32 v78, v78, 0xbdd2d3e7, v129
	v_mul_f32_e32 v80, v79, v79
	v_mul_f32_e32 v78, v78, v0
	v_fmamk_f32 v80, v80, 0xbdd2d3e7, v129
	v_mul_f32_e32 v80, v80, v79
	v_exp_f32_e32 v78, v78
	v_exp_f32_e32 v80, v80
	global_store_dwordx2 v[66:67], v[72:73], off offset:64
	v_add_f32_e32 v78, 1.0, v78
	v_rcp_f32_e32 v78, v78
	v_add_f32_e32 v72, 1.0, v80
	v_rcp_f32_e32 v72, v72
	v_add_f32_e32 v73, v90, v106
	v_mul_f32_e32 v0, v78, v0
	v_mul_f32_e32 v0, v0, v73
	v_mul_f32_e32 v72, v72, v79
	v_add_f32_e32 v73, v91, v106
	v_mul_f32_e32 v72, v72, v73
	v_lshlrev_b32_e32 v73, 16, v105
	v_mul_f32_e32 v78, v73, v73
	v_and_b32_e32 v79, 0xffff0000, v105
	v_fmamk_f32 v78, v78, 0xbdd2d3e7, v129
	v_mul_f32_e32 v80, v79, v79
	v_mul_f32_e32 v78, v78, v73
	v_fmamk_f32 v80, v80, 0xbdd2d3e7, v129
	v_mul_f32_e32 v80, v80, v79
	v_exp_f32_e32 v78, v78
	v_exp_f32_e32 v80, v80
	v_cvt_pk_bf16_f32 v72, v0, v72
	v_add_f32_e32 v78, 1.0, v78
	v_rcp_f32_e32 v78, v78
	v_add_f32_e32 v0, 1.0, v80
	v_rcp_f32_e32 v0, v0
	v_mfma_f32_16x16x32_bf16 v[54:57], v[14:17], v[94:97], v[110:113]
	v_mul_f32_e32 v73, v78, v73
	v_add_f32_e32 v78, v92, v106
	v_mul_f32_e32 v73, v78, v73
	v_mul_f32_e32 v0, v0, v79
	v_add_f32_e32 v78, v93, v106
	v_mul_f32_e32 v0, v78, v0
	v_cvt_pk_bf16_f32 v73, v73, v0
	global_store_dwordx2 v[66:67], v[72:73], off offset:96
	global_load_dword v0, v76, s[12:13] offset:64
	ds_read_b128 v[78:81], v77 offset:8896
	global_load_dwordx2 v[84:85], v[70:71], off offset:64
	global_load_dwordx2 v[86:87], v[70:71], off offset:96
	v_add_co_u32_e32 v72, vcc, s4, v68
	v_mfma_f32_16x16x32_bf16 v[50:53], v[18:21], v[94:97], v[114:117]
	s_nop 0
	v_addc_co_u32_e32 v73, vcc, 0, v69, vcc
	s_waitcnt vmcnt(6)
	v_lshlrev_b32_e32 v88, 16, v74
	v_and_b32_e32 v74, 0xffff0000, v74
	v_mul_f32_e32 v71, v74, v74
	v_mul_f32_e32 v70, v88, v88
	v_fmamk_f32 v71, v71, 0xbdd2d3e7, v129
	v_fmamk_f32 v70, v70, 0xbdd2d3e7, v129
	v_mul_f32_e32 v71, v71, v74
	v_mul_f32_e32 v70, v70, v88
	v_exp_f32_e32 v89, v71
	v_exp_f32_e32 v70, v70
	v_mfma_f32_16x16x32_bf16 v[62:65], v[22:25], v[94:97], v[62:65]
	v_add_f32_e32 v89, 1.0, v89
	v_add_f32_e32 v70, 1.0, v70
	v_rcp_f32_e32 v89, v89
	v_rcp_f32_e32 v90, v70
	global_load_dwordx2 v[70:71], v[72:73], off
	s_waitcnt lgkmcnt(0)
	v_mfma_f32_16x16x32_bf16 v[38:41], v[30:33], v[78:81], v[38:41]
	v_mul_f32_e32 v74, v89, v74
	v_mul_f32_e32 v88, v90, v88
	s_waitcnt vmcnt(3)
	v_add_f32_e32 v59, v59, v0
	v_add_f32_e32 v58, v58, v0
	v_mul_f32_e32 v59, v74, v59
	v_lshlrev_b32_e32 v74, 16, v75
	v_mul_f32_e32 v58, v88, v58
	v_mul_f32_e32 v88, v74, v74
	v_fmamk_f32 v88, v88, 0xbdd2d3e7, v129
	v_mul_f32_e32 v88, v88, v74
	v_exp_f32_e32 v88, v88
	v_and_b32_e32 v75, 0xffff0000, v75
	v_mul_f32_e32 v89, v75, v75
	v_fmamk_f32 v89, v89, 0xbdd2d3e7, v129
	v_mul_f32_e32 v89, v89, v75
	v_add_f32_e32 v88, 1.0, v88
	v_rcp_f32_e32 v88, v88
	v_exp_f32_e32 v89, v89
	v_cvt_pk_bf16_f32 v58, v58, v59
	v_mul_f32_e32 v74, v88, v74
	v_lshlrev_b32_e32 v88, 16, v82
	v_and_b32_e32 v82, 0xffff0000, v82
	v_mul_f32_e32 v90, v82, v82
	v_add_f32_e32 v59, 1.0, v89
	v_mul_f32_e32 v89, v88, v88
	v_fmamk_f32 v90, v90, 0xbdd2d3e7, v129
	v_rcp_f32_e32 v59, v59
	v_fmamk_f32 v89, v89, 0xbdd2d3e7, v129
	v_mul_f32_e32 v90, v90, v82
	v_mul_f32_e32 v89, v89, v88
	v_exp_f32_e32 v90, v90
	v_add_f32_e32 v60, v60, v0
	v_mul_f32_e32 v59, v59, v75
	v_add_f32_e32 v61, v61, v0
	v_exp_f32_e32 v89, v89
	v_mul_f32_e32 v60, v74, v60
	v_mul_f32_e32 v59, v59, v61
	v_add_co_u32_e32 v74, vcc, s2, v66
	v_cvt_pk_bf16_f32 v59, v60, v59
	s_nop 0
	v_addc_co_u32_e32 v75, vcc, 0, v67, vcc
	global_store_dwordx2 v[74:75], v[58:59], off
	v_add_f32_e32 v58, 1.0, v90
	v_add_f32_e32 v89, 1.0, v89
	v_rcp_f32_e32 v58, v58
	v_rcp_f32_e32 v89, v89
	v_add_f32_e32 v55, v55, v0
	v_add_f32_e32 v54, v54, v0
	v_mul_f32_e32 v58, v58, v82
	v_mul_f32_e32 v59, v89, v88
	v_mul_f32_e32 v55, v58, v55
	v_lshlrev_b32_e32 v58, 16, v83
	v_and_b32_e32 v74, 0xffff0000, v83
	v_mul_f32_e32 v54, v59, v54
	v_mul_f32_e32 v59, v58, v58
	v_mul_f32_e32 v75, v74, v74
	v_fmamk_f32 v59, v59, 0xbdd2d3e7, v129
	v_fmamk_f32 v75, v75, 0xbdd2d3e7, v129
	v_mul_f32_e32 v59, v59, v58
	v_mul_f32_e32 v75, v75, v74
	v_exp_f32_e32 v59, v59
	v_exp_f32_e32 v75, v75
	v_cvt_pk_bf16_f32 v54, v54, v55
	v_add_f32_e32 v56, v56, v0
	v_add_f32_e32 v59, 1.0, v59
	v_add_f32_e32 v55, 1.0, v75
	v_rcp_f32_e32 v59, v59
	v_rcp_f32_e32 v55, v55
	v_add_f32_e32 v57, v57, v0
	v_lshl_add_u64 v[60:61], v[66:67], 0, s[0:1]
	v_mul_f32_e32 v58, v59, v58
	v_mul_f32_e32 v55, v55, v74
	v_mul_f32_e32 v56, v58, v56
	v_mul_f32_e32 v55, v55, v57
	s_waitcnt vmcnt(3)
	v_and_b32_e32 v58, 0xffff0000, v84
	v_cvt_pk_bf16_f32 v55, v56, v55
	v_lshlrev_b32_e32 v56, 16, v84
	v_mul_f32_e32 v59, v58, v58
	v_mul_f32_e32 v57, v56, v56
	v_fmamk_f32 v59, v59, 0xbdd2d3e7, v129
	v_fmamk_f32 v57, v57, 0xbdd2d3e7, v129
	v_mul_f32_e32 v59, v59, v58
	v_mul_f32_e32 v57, v57, v56
	v_exp_f32_e32 v59, v59
	v_exp_f32_e32 v57, v57
	global_store_dwordx2 v[60:61], v[54:55], off offset:32
	v_add_f32_e32 v51, v51, v0
	v_add_f32_e32 v54, 1.0, v59
	v_add_f32_e32 v57, 1.0, v57
	v_rcp_f32_e32 v54, v54
	v_rcp_f32_e32 v57, v57
	v_add_f32_e32 v50, v50, v0
	v_add_f32_e32 v52, v52, v0
	v_mul_f32_e32 v54, v54, v58
	v_mul_f32_e32 v55, v57, v56
	v_mul_f32_e32 v51, v54, v51
	v_lshlrev_b32_e32 v54, 16, v85
	v_and_b32_e32 v56, 0xffff0000, v85
	v_mul_f32_e32 v50, v55, v50
	v_mul_f32_e32 v55, v54, v54
	v_mul_f32_e32 v57, v56, v56
	v_fmamk_f32 v55, v55, 0xbdd2d3e7, v129
	v_fmamk_f32 v57, v57, 0xbdd2d3e7, v129
	v_mul_f32_e32 v55, v55, v54
	v_mul_f32_e32 v57, v57, v56
	v_exp_f32_e32 v55, v55
	v_exp_f32_e32 v57, v57
	v_cvt_pk_bf16_f32 v50, v50, v51
	v_add_f32_e32 v53, v53, v0
	v_add_f32_e32 v55, 1.0, v55
	v_add_f32_e32 v51, 1.0, v57
	v_rcp_f32_e32 v55, v55
	v_rcp_f32_e32 v51, v51
	s_mov_b32 s2, 0x5d000
	v_mfma_f32_16x16x32_bf16 v[34:37], v[14:17], v[78:81], v[34:37]
	v_mul_f32_e32 v54, v55, v54
	v_mul_f32_e32 v51, v51, v56
	v_mul_f32_e32 v52, v54, v52
	v_mul_f32_e32 v51, v51, v53
	v_cvt_pk_bf16_f32 v51, v52, v51
	s_waitcnt vmcnt(3)
	v_lshlrev_b32_e32 v52, 16, v86
	v_mul_f32_e32 v53, v52, v52
	v_and_b32_e32 v54, 0xffff0000, v86
	v_fmamk_f32 v53, v53, 0xbdd2d3e7, v129
	v_mul_f32_e32 v55, v54, v54
	v_mul_f32_e32 v53, v53, v52
	v_fmamk_f32 v55, v55, 0xbdd2d3e7, v129
	v_mul_f32_e32 v55, v55, v54
	v_exp_f32_e32 v53, v53
	v_exp_f32_e32 v55, v55
	global_store_dwordx2 v[60:61], v[50:51], off offset:64
	v_add_f32_e32 v53, 1.0, v53
	v_rcp_f32_e32 v53, v53
	v_add_f32_e32 v50, 1.0, v55
	v_rcp_f32_e32 v50, v50
	s_mov_b64 s[0:1], 0x3e000
	v_mul_f32_e32 v51, v53, v52
	v_add_f32_e32 v52, v62, v0
	v_mul_f32_e32 v51, v51, v52
	v_mul_f32_e32 v50, v50, v54
	v_add_f32_e32 v52, v63, v0
	v_mul_f32_e32 v50, v50, v52
	v_lshlrev_b32_e32 v52, 16, v87
	v_and_b32_e32 v54, 0xffff0000, v87
	v_mul_f32_e32 v53, v52, v52
	v_mul_f32_e32 v55, v54, v54
	v_fmamk_f32 v53, v53, 0xbdd2d3e7, v129
	v_fmamk_f32 v55, v55, 0xbdd2d3e7, v129
	v_mul_f32_e32 v53, v53, v52
	v_mul_f32_e32 v55, v55, v54
	v_exp_f32_e32 v53, v53
	v_exp_f32_e32 v55, v55
	v_cvt_pk_bf16_f32 v50, v51, v50
	v_mfma_f32_16x16x32_bf16 v[46:49], v[18:21], v[78:81], v[46:49]
	v_add_f32_e32 v53, 1.0, v53
	v_add_f32_e32 v51, 1.0, v55
	v_rcp_f32_e32 v53, v53
	v_rcp_f32_e32 v51, v51
	v_mfma_f32_16x16x32_bf16 v[42:45], v[22:25], v[78:81], v[42:45]
	v_mul_f32_e32 v52, v53, v52
	v_add_f32_e32 v53, v64, v0
	v_mul_f32_e32 v51, v51, v54
	v_add_f32_e32 v0, v65, v0
	v_mul_f32_e32 v52, v52, v53
	v_mul_f32_e32 v0, v51, v0
	v_cvt_pk_bf16_f32 v51, v52, v0
	global_store_dwordx2 v[60:61], v[50:51], off offset:96
	global_load_dword v0, v76, s[12:13] offset:128
	global_load_dwordx2 v[54:55], v[72:73], off offset:32
	ds_read_b128 v[50:53], v77 offset:13248
	global_load_dwordx2 v[56:57], v[72:73], off offset:64
	global_load_dwordx2 v[58:59], v[72:73], off offset:96
	s_waitcnt vmcnt(8)
	v_lshlrev_b32_e32 v60, 16, v70
	s_waitcnt lgkmcnt(0)
	v_mfma_f32_16x16x32_bf16 v[26:29], v[30:33], v[50:53], v[26:29]
	v_mul_f32_e32 v30, v60, v60
	v_and_b32_e32 v61, 0xffff0000, v70
	v_fmamk_f32 v30, v30, 0xbdd2d3e7, v129
	v_mul_f32_e32 v31, v61, v61
	v_mul_f32_e32 v30, v30, v60
	v_fmamk_f32 v31, v31, 0xbdd2d3e7, v129
	v_mul_f32_e32 v31, v31, v61
	v_exp_f32_e32 v30, v30
	v_exp_f32_e32 v62, v31
	v_add_co_u32_e32 v32, vcc, s2, v68
	v_add_f32_e32 v30, 1.0, v30
	v_rcp_f32_e32 v63, v30
	v_add_f32_e32 v62, 1.0, v62
	v_rcp_f32_e32 v62, v62
	v_addc_co_u32_e32 v33, vcc, 0, v69, vcc
	v_mul_f32_e32 v60, v63, v60
	global_load_dwordx2 v[30:31], v[32:33], off
	v_mfma_f32_16x16x32_bf16 v[6:9], v[14:17], v[50:53], v[6:9]
	global_load_dwordx2 v[14:15], v[32:33], off offset:32
	s_waitcnt vmcnt(5)
	v_add_f32_e32 v38, v38, v0
	v_mul_f32_e32 v38, v60, v38
	v_mul_f32_e32 v60, v62, v61
	v_and_b32_e32 v62, 0xffff0000, v71
	v_mul_f32_e32 v63, v62, v62
	v_fmamk_f32 v63, v63, 0xbdd2d3e7, v129
	v_mul_f32_e32 v63, v63, v62
	v_add_f32_e32 v39, v39, v0
	v_exp_f32_e32 v63, v63
	v_mul_f32_e32 v39, v60, v39
	v_lshlrev_b32_e32 v60, 16, v71
	v_mul_f32_e32 v61, v60, v60
	v_fmamk_f32 v61, v61, 0xbdd2d3e7, v129
	v_mul_f32_e32 v61, v61, v60
	v_cvt_pk_bf16_f32 v38, v38, v39
	v_add_f32_e32 v39, 1.0, v63
	v_rcp_f32_e32 v39, v39
	v_exp_f32_e32 v61, v61
	v_add_f32_e32 v40, v40, v0
	v_mul_f32_e32 v39, v39, v62
	s_waitcnt vmcnt(4)
	v_lshlrev_b32_e32 v62, 16, v54
	v_and_b32_e32 v54, 0xffff0000, v54
	v_mul_f32_e32 v64, v54, v54
	v_add_f32_e32 v61, 1.0, v61
	v_mul_f32_e32 v63, v62, v62
	v_fmamk_f32 v64, v64, 0xbdd2d3e7, v129
	v_rcp_f32_e32 v61, v61
	v_fmamk_f32 v63, v63, 0xbdd2d3e7, v129
	v_mul_f32_e32 v64, v64, v54
	v_mul_f32_e32 v63, v63, v62
	v_exp_f32_e32 v64, v64
	v_mul_f32_e32 v60, v61, v60
	v_add_f32_e32 v41, v41, v0
	v_exp_f32_e32 v63, v63
	v_mul_f32_e32 v40, v60, v40
	v_mul_f32_e32 v39, v39, v41
	v_add_co_u32_e32 v60, vcc, s4, v66
	v_cvt_pk_bf16_f32 v39, v40, v39
	s_nop 0
	v_addc_co_u32_e32 v61, vcc, 0, v67, vcc
	global_store_dwordx2 v[60:61], v[38:39], off
	v_add_f32_e32 v38, 1.0, v64
	v_add_f32_e32 v63, 1.0, v63
	v_rcp_f32_e32 v38, v38
	v_rcp_f32_e32 v63, v63
	v_add_f32_e32 v35, v35, v0
	v_add_f32_e32 v34, v34, v0
	v_mul_f32_e32 v38, v38, v54
	v_mul_f32_e32 v39, v63, v62
	v_mul_f32_e32 v35, v38, v35
	v_lshlrev_b32_e32 v38, 16, v55
	v_and_b32_e32 v54, 0xffff0000, v55
	v_mul_f32_e32 v34, v39, v34
	v_mul_f32_e32 v39, v38, v38
	v_mul_f32_e32 v55, v54, v54
	v_fmamk_f32 v39, v39, 0xbdd2d3e7, v129
	v_fmamk_f32 v55, v55, 0xbdd2d3e7, v129
	v_mul_f32_e32 v39, v39, v38
	v_mul_f32_e32 v55, v55, v54
	v_exp_f32_e32 v39, v39
	v_exp_f32_e32 v55, v55
	v_cvt_pk_bf16_f32 v34, v34, v35
	v_add_f32_e32 v36, v36, v0
	v_add_f32_e32 v39, 1.0, v39
	v_add_f32_e32 v35, 1.0, v55
	v_rcp_f32_e32 v39, v39
	v_rcp_f32_e32 v35, v35
	v_add_f32_e32 v37, v37, v0
	v_lshl_add_u64 v[40:41], v[66:67], 0, s[0:1]
	v_mul_f32_e32 v38, v39, v38
	v_mul_f32_e32 v35, v35, v54
	v_mul_f32_e32 v36, v38, v36
	v_mul_f32_e32 v35, v35, v37
	v_cvt_pk_bf16_f32 v35, v36, v35
	s_waitcnt vmcnt(4)
	v_lshlrev_b32_e32 v36, 16, v56
	v_mul_f32_e32 v37, v36, v36
	v_and_b32_e32 v38, 0xffff0000, v56
	v_fmamk_f32 v37, v37, 0xbdd2d3e7, v129
	v_mul_f32_e32 v39, v38, v38
	v_mul_f32_e32 v37, v37, v36
	v_fmamk_f32 v39, v39, 0xbdd2d3e7, v129
	v_mul_f32_e32 v39, v39, v38
	v_exp_f32_e32 v37, v37
	v_exp_f32_e32 v39, v39
	global_store_dwordx2 v[40:41], v[34:35], off offset:32
	v_add_f32_e32 v37, 1.0, v37
	v_rcp_f32_e32 v37, v37
	v_add_f32_e32 v34, 1.0, v39
	v_rcp_f32_e32 v34, v34
	v_mfma_f32_16x16x32_bf16 v[2:5], v[18:21], v[50:53], v[2:5]
	v_mul_f32_e32 v35, v37, v36
	v_add_f32_e32 v36, v46, v0
	v_mul_f32_e32 v35, v35, v36
	v_mul_f32_e32 v34, v34, v38
	v_add_f32_e32 v36, v47, v0
	v_mul_f32_e32 v34, v34, v36
	v_lshlrev_b32_e32 v36, 16, v57
	v_mul_f32_e32 v37, v36, v36
	v_and_b32_e32 v38, 0xffff0000, v57
	v_fmamk_f32 v37, v37, 0xbdd2d3e7, v129
	v_mul_f32_e32 v39, v38, v38
	v_mul_f32_e32 v37, v37, v36
	v_fmamk_f32 v39, v39, 0xbdd2d3e7, v129
	v_mul_f32_e32 v39, v39, v38
	v_exp_f32_e32 v37, v37
	v_exp_f32_e32 v39, v39
	v_cvt_pk_bf16_f32 v34, v35, v34
	v_add_f32_e32 v37, 1.0, v37
	v_rcp_f32_e32 v37, v37
	v_add_f32_e32 v35, 1.0, v39
	v_rcp_f32_e32 v35, v35
	s_waitcnt vmcnt(3)
	v_lshlrev_b32_e32 v20, 16, v30
	v_mul_f32_e32 v36, v37, v36
	v_add_f32_e32 v37, v48, v0
	v_mul_f32_e32 v36, v36, v37
	v_mul_f32_e32 v35, v35, v38
	v_add_f32_e32 v37, v49, v0
	v_mul_f32_e32 v35, v35, v37
	v_cvt_pk_bf16_f32 v35, v36, v35
	v_lshlrev_b32_e32 v36, 16, v58
	v_mul_f32_e32 v37, v36, v36
	v_and_b32_e32 v38, 0xffff0000, v58
	v_fmamk_f32 v37, v37, 0xbdd2d3e7, v129
	v_mul_f32_e32 v39, v38, v38
	v_mul_f32_e32 v37, v37, v36
	v_fmamk_f32 v39, v39, 0xbdd2d3e7, v129
	v_mul_f32_e32 v39, v39, v38
	v_exp_f32_e32 v37, v37
	v_exp_f32_e32 v39, v39
	global_store_dwordx2 v[40:41], v[34:35], off offset:64
	v_add_f32_e32 v37, 1.0, v37
	v_rcp_f32_e32 v37, v37
	v_add_f32_e32 v34, 1.0, v39
	v_rcp_f32_e32 v34, v34
	v_mul_f32_e32 v21, v20, v20
	v_mul_f32_e32 v35, v37, v36
	v_add_f32_e32 v36, v42, v0
	v_mul_f32_e32 v35, v35, v36
	v_mul_f32_e32 v34, v34, v38
	v_add_f32_e32 v36, v43, v0
	v_mul_f32_e32 v34, v34, v36
	v_lshlrev_b32_e32 v36, 16, v59
	v_and_b32_e32 v38, 0xffff0000, v59
	v_mul_f32_e32 v37, v36, v36
	v_mul_f32_e32 v39, v38, v38
	v_fmamk_f32 v37, v37, 0xbdd2d3e7, v129
	v_fmamk_f32 v39, v39, 0xbdd2d3e7, v129
	v_mul_f32_e32 v37, v37, v36
	v_mul_f32_e32 v39, v39, v38
	v_exp_f32_e32 v37, v37
	v_exp_f32_e32 v39, v39
	v_cvt_pk_bf16_f32 v34, v35, v34
	v_and_b32_e32 v30, 0xffff0000, v30
	v_add_f32_e32 v37, 1.0, v37
	v_add_f32_e32 v35, 1.0, v39
	v_rcp_f32_e32 v37, v37
	v_rcp_f32_e32 v35, v35
	v_fmamk_f32 v21, v21, 0xbdd2d3e7, v129
	v_mul_f32_e32 v21, v21, v20
	v_mul_f32_e32 v36, v37, v36
	v_add_f32_e32 v37, v44, v0
	v_mul_f32_e32 v35, v35, v38
	v_add_f32_e32 v0, v45, v0
	v_mul_f32_e32 v36, v36, v37
	v_mul_f32_e32 v0, v35, v0
	v_cvt_pk_bf16_f32 v35, v36, v0
	global_store_dwordx2 v[40:41], v[34:35], off offset:96
	global_load_dword v0, v76, s[12:13] offset:192
	global_load_dwordx2 v[16:17], v[32:33], off offset:64
	global_load_dwordx2 v[18:19], v[32:33], off offset:96
	v_mul_f32_e32 v32, v30, v30
	v_fmamk_f32 v32, v32, 0xbdd2d3e7, v129
	v_mul_f32_e32 v32, v32, v30
	v_exp_f32_e32 v21, v21
	v_exp_f32_e32 v32, v32
	v_mfma_f32_16x16x32_bf16 v[10:13], v[22:25], v[50:53], v[10:13]
	v_add_f32_e32 v21, 1.0, v21
	v_rcp_f32_e32 v21, v21
	v_add_f32_e32 v22, 1.0, v32
	v_rcp_f32_e32 v22, v22
	v_and_b32_e32 v24, 0xffff0000, v31
	v_mul_f32_e32 v20, v21, v20
	v_mul_f32_e32 v25, v24, v24
	v_fmamk_f32 v25, v25, 0xbdd2d3e7, v129
	v_mul_f32_e32 v25, v25, v24
	v_exp_f32_e32 v25, v25
	s_mov_b64 s[0:1], 0x5d000
	s_waitcnt vmcnt(2)
	v_add_f32_e32 v21, v26, v0
	v_mul_f32_e32 v20, v20, v21
	v_mul_f32_e32 v21, v22, v30
	v_add_f32_e32 v22, v27, v0
	v_mul_f32_e32 v21, v21, v22
	v_lshlrev_b32_e32 v22, 16, v31
	v_mul_f32_e32 v23, v22, v22
	v_fmamk_f32 v23, v23, 0xbdd2d3e7, v129
	v_mul_f32_e32 v23, v23, v22
	v_exp_f32_e32 v23, v23
	v_lshlrev_b32_e32 v26, 16, v14
	v_and_b32_e32 v14, 0xffff0000, v14
	v_cvt_pk_bf16_f32 v20, v20, v21
	v_add_f32_e32 v23, 1.0, v23
	v_rcp_f32_e32 v23, v23
	v_add_f32_e32 v21, 1.0, v25
	v_mul_f32_e32 v27, v26, v26
	v_rcp_f32_e32 v21, v21
	v_mul_f32_e32 v22, v23, v22
	v_add_f32_e32 v23, v28, v0
	v_mul_f32_e32 v28, v14, v14
	v_fmamk_f32 v28, v28, 0xbdd2d3e7, v129
	v_fmamk_f32 v27, v27, 0xbdd2d3e7, v129
	v_mul_f32_e32 v28, v28, v14
	v_mul_f32_e32 v27, v27, v26
	v_exp_f32_e32 v28, v28
	v_mul_f32_e32 v22, v22, v23
	v_mul_f32_e32 v21, v21, v24
	v_add_f32_e32 v23, v29, v0
	v_exp_f32_e32 v27, v27
	v_mul_f32_e32 v21, v21, v23
	v_add_co_u32_e32 v24, vcc, s2, v66
	v_cvt_pk_bf16_f32 v21, v22, v21
	s_nop 0
	v_addc_co_u32_e32 v25, vcc, 0, v67, vcc
	global_store_dwordx2 v[24:25], v[20:21], off
	v_add_f32_e32 v20, 1.0, v28
	v_add_f32_e32 v27, 1.0, v27
	v_rcp_f32_e32 v20, v20
	v_rcp_f32_e32 v27, v27
	v_add_f32_e32 v7, v7, v0
	v_add_f32_e32 v6, v6, v0
	v_mul_f32_e32 v14, v20, v14
	v_mul_f32_e32 v21, v27, v26
	v_mul_f32_e32 v7, v14, v7
	v_lshlrev_b32_e32 v14, 16, v15
	v_and_b32_e32 v15, 0xffff0000, v15
	v_mul_f32_e32 v6, v21, v6
	v_mul_f32_e32 v20, v14, v14
	v_mul_f32_e32 v21, v15, v15
	v_fmamk_f32 v20, v20, 0xbdd2d3e7, v129
	v_fmamk_f32 v21, v21, 0xbdd2d3e7, v129
	v_mul_f32_e32 v20, v20, v14
	v_mul_f32_e32 v21, v21, v15
	v_exp_f32_e32 v20, v20
	v_exp_f32_e32 v21, v21
	v_cvt_pk_bf16_f32 v6, v6, v7
	v_add_f32_e32 v8, v8, v0
	v_add_f32_e32 v20, 1.0, v20
	v_add_f32_e32 v7, 1.0, v21
	v_rcp_f32_e32 v20, v20
	v_rcp_f32_e32 v7, v7
	v_add_f32_e32 v9, v9, v0
	v_lshl_add_u64 v[22:23], v[66:67], 0, s[0:1]
	v_mul_f32_e32 v14, v20, v14
	v_mul_f32_e32 v7, v7, v15
	v_mul_f32_e32 v8, v14, v8
	v_mul_f32_e32 v7, v7, v9
	s_waitcnt vmcnt(2)
	v_and_b32_e32 v14, 0xffff0000, v16
	v_cvt_pk_bf16_f32 v7, v8, v7
	v_lshlrev_b32_e32 v8, 16, v16
	v_mul_f32_e32 v15, v14, v14
	v_mul_f32_e32 v9, v8, v8
	v_fmamk_f32 v15, v15, 0xbdd2d3e7, v129
	v_fmamk_f32 v9, v9, 0xbdd2d3e7, v129
	v_mul_f32_e32 v15, v15, v14
	v_mul_f32_e32 v9, v9, v8
	v_exp_f32_e32 v15, v15
	v_exp_f32_e32 v9, v9
	global_store_dwordx2 v[22:23], v[6:7], off offset:32
	v_add_f32_e32 v3, v3, v0
	v_add_f32_e32 v6, 1.0, v15
	v_add_f32_e32 v9, 1.0, v9
	v_rcp_f32_e32 v6, v6
	v_rcp_f32_e32 v9, v9
	v_add_f32_e32 v2, v2, v0
	v_add_f32_e32 v4, v4, v0
	v_mul_f32_e32 v6, v6, v14
	v_mul_f32_e32 v7, v9, v8
	v_mul_f32_e32 v3, v6, v3
	v_lshlrev_b32_e32 v6, 16, v17
	v_and_b32_e32 v8, 0xffff0000, v17
	v_mul_f32_e32 v2, v7, v2
	v_mul_f32_e32 v7, v6, v6
	v_mul_f32_e32 v9, v8, v8
	v_fmamk_f32 v7, v7, 0xbdd2d3e7, v129
	v_fmamk_f32 v9, v9, 0xbdd2d3e7, v129
	v_mul_f32_e32 v7, v7, v6
	v_mul_f32_e32 v9, v9, v8
	v_exp_f32_e32 v7, v7
	v_exp_f32_e32 v9, v9
	v_cvt_pk_bf16_f32 v2, v2, v3
	v_add_f32_e32 v5, v5, v0
	v_add_f32_e32 v7, 1.0, v7
	v_add_f32_e32 v3, 1.0, v9
	v_rcp_f32_e32 v7, v7
	v_rcp_f32_e32 v3, v3
	s_lshl_b32 s0, s38, 6
	s_and_b32 s2, s0, 0x3fc0
	v_mul_f32_e32 v6, v7, v6
	v_mul_f32_e32 v3, v3, v8
	v_mul_f32_e32 v4, v6, v4
	v_mul_f32_e32 v3, v3, v5
	v_cvt_pk_bf16_f32 v3, v4, v3
	s_waitcnt vmcnt(2)
	v_lshlrev_b32_e32 v4, 16, v18
	v_mul_f32_e32 v5, v4, v4
	v_and_b32_e32 v6, 0xffff0000, v18
	v_fmamk_f32 v5, v5, 0xbdd2d3e7, v129
	v_mul_f32_e32 v7, v6, v6
	v_mul_f32_e32 v5, v5, v4
	v_fmamk_f32 v7, v7, 0xbdd2d3e7, v129
	v_mul_f32_e32 v7, v7, v6
	v_exp_f32_e32 v5, v5
	v_exp_f32_e32 v7, v7
	global_store_dwordx2 v[22:23], v[2:3], off offset:64
	v_add_f32_e32 v5, 1.0, v5
	v_rcp_f32_e32 v5, v5
	v_add_f32_e32 v2, 1.0, v7
	v_rcp_f32_e32 v2, v2
	s_lshr_b32 s0, s38, 2
	v_mul_f32_e32 v3, v5, v4
	v_add_f32_e32 v4, v10, v0
	v_mul_f32_e32 v3, v3, v4
	v_mul_f32_e32 v2, v2, v6
	v_add_f32_e32 v4, v11, v0
	v_mul_f32_e32 v2, v2, v4
	v_lshlrev_b32_e32 v4, 16, v19
	v_and_b32_e32 v6, 0xffff0000, v19
	v_mul_f32_e32 v5, v4, v4
	v_mul_f32_e32 v7, v6, v6
	v_fmamk_f32 v5, v5, 0xbdd2d3e7, v129
	v_fmamk_f32 v7, v7, 0xbdd2d3e7, v129
	v_mul_f32_e32 v5, v5, v4
	v_mul_f32_e32 v7, v7, v6
	v_exp_f32_e32 v5, v5
	v_exp_f32_e32 v7, v7
	v_cvt_pk_bf16_f32 v2, v3, v2
	s_and_b32 s4, s0, 64
	v_add_f32_e32 v5, 1.0, v5
	v_add_f32_e32 v3, 1.0, v7
	v_rcp_f32_e32 v5, v5
	v_rcp_f32_e32 v3, v3
	s_lshl_b32 s88, s4, 1
	s_mov_b64 s[0:1], 0x1b00
	v_mul_f32_e32 v4, v5, v4
	v_add_f32_e32 v5, v12, v0
	v_mul_f32_e32 v3, v3, v6
	v_add_f32_e32 v0, v13, v0
	v_mul_f32_e32 v4, v4, v5
	v_mul_f32_e32 v0, v3, v0
	v_cvt_pk_bf16_f32 v3, v4, v0
	v_mov_b32_e32 v0, v194
	global_store_dwordx2 v[22:23], v[2:3], off offset:96
	s_barrier
	s_nop 0
	v_bfe_u32 v12, v0, 2, 6
	v_lshlrev_b32_e32 v0, 4, v0
	v_and_b32_e32 v10, 48, v0
	v_or_b32_e32 v0, s2, v12
	v_mul_u32_u24_e32 v0, 0xf80, v0
	v_lshlrev_b32_e32 v0, 1, v0
	v_lshl_add_u64 v[2:3], s[46:47], 0, v[0:1]
	v_lshl_add_u64 v[2:3], v[2:3], 0, s[88:89]
	v_lshlrev_b32_e32 v0, 1, v10
	v_lshl_add_u64 v[6:7], v[2:3], 0, v[0:1]
	v_add_co_u32_e32 v2, vcc, s68, v6
	v_mul_u32_u24_e32 v10, 0x48, v10
	s_nop 0
	v_addc_co_u32_e32 v3, vcc, 0, v7, vcc
	global_load_dwordx4 v[2:5], v[2:3], off offset:2816
	v_lshl_add_u64 v[6:7], v[6:7], 0, s[0:1]
	global_load_dwordx4 v[6:9], v[6:7], off offset:16
	v_lshlrev_b32_e32 v10, 1, v10
	v_lshlrev_b32_e32 v11, 1, v12
	v_add3_u32 v13, s15, v10, v11
	v_add3_u32 v10, s15, v11, v10
	s_lshl_b32 s88, s2, 1
	s_waitcnt vmcnt(1)
	ds_write_b16 v13, v2
	ds_write_b16_d16_hi v10, v2 offset:144
	ds_write_b16 v13, v3 offset:288
	ds_write_b16_d16_hi v10, v3 offset:432
	ds_write_b16 v13, v4 offset:576
	ds_write_b16_d16_hi v10, v4 offset:720
	ds_write_b16 v13, v5 offset:864
	ds_write_b16_d16_hi v10, v5 offset:1008
	s_waitcnt vmcnt(0)
	ds_write_b16 v13, v6 offset:1152
	ds_write_b16_d16_hi v10, v6 offset:1296
	ds_write_b16 v13, v7 offset:1440
	ds_write_b16_d16_hi v10, v7 offset:1584
	ds_write_b16 v13, v8 offset:1728
	ds_write_b16_d16_hi v10, v8 offset:1872
	ds_write_b16 v13, v9 offset:2016
	ds_write_b16_d16_hi v10, v9 offset:2160
	v_or_b32_e32 v2, s4, v12
	v_lshlrev_b32_e32 v2, 15, v2
	v_mov_b32_e32 v3, v1
	v_lshl_add_u64 v[10:11], s[48:49], 0, v[2:3]
	v_mul_u32_u24_e32 v2, 0x90, v12
	v_add3_u32 v6, s15, v2, v0
	s_waitcnt lgkmcnt(0)
	s_barrier
	ds_read_b128 v[2:5], v6
	ds_read_b128 v[6:9], v6 offset:16
	v_lshl_add_u64 v[10:11], v[10:11], 0, s[88:89]
	v_lshl_add_u64 v[10:11], v[10:11], 0, v[0:1]
	s_mov_b64 s[4:5], -1
	s_waitcnt lgkmcnt(1)
	global_store_dwordx4 v[10:11], v[2:5], off
	s_waitcnt lgkmcnt(0)
	global_store_dwordx4 v[10:11], v[6:9], off offset:16
	s_barrier
